# MFMA order inside K-loop blocks: snake over the 2x4 operand grid (one source operand changes per step), bit-identical
# baseline (speedup 1.0000x reference)
; #define PG8_STAGE(bufoff, gbase, voff) do { _Pragma("unroll") for (int _i = 0; _i < 2; ++_i) \
;         __builtin_amdgcn_global_load_lds((const unsigned*)((const char*)(gbase) + (voff)[_i]), (PG8_LAS unsigned*)(lds + (bufoff) + ldsw + _i * 8192), 16, 0, AUX_A); } while (0)
; #define PG8_STAGEB(bufoff, gbase, voff) do { _Pragma("unroll") for (int _i = 0; _i < 2; ++_i) \
;         __builtin_amdgcn_global_load_lds((const unsigned*)((const char*)(gbase) + (voff)[_i]), (PG8_LAS unsigned*)(lds + (bufoff) + ldsw + _i * 8192), 16, 0, AUX_B); } while (0)
; #define PG8_LDA(dst, b, h) do { _Pragma("unroll") for (int m = 0; m < 4; ++m) _Pragma("unroll") for (int k = 0; k < 2; ++k) dst[m][k] = *(const PG8_LAS bf16x8*)(lds + PG8_SA(b, h) + aoff + m * 2048 + k * 1024); } while (0)
; #define PG8_LDB(dst, b, h) do { _Pragma("unroll") for (int n = 0; n < 2; ++n) _Pragma("unroll") for (int k = 0; k < 2; ++k) dst[n][k] = *(const PG8_LAS bf16x8*)(lds + PG8_SB(b, h) + boff + n * 2048 + k * 1024); } while (0)
; #define PG8_WAIT_V(n) asm volatile("s_waitcnt vmcnt(" #n ")" ::: "memory")
; #define PG8_WAIT_L(n) asm volatile("s_waitcnt lgkmcnt(" #n ")" ::: "memory")
; #define PG8_BAR __builtin_amdgcn_s_barrier()
; #define PG8_SCHED __builtin_amdgcn_sched_barrier(0)
; template <class Epi, class Sched, bool ALIGN_EPI = false, bool SP2 = false>
; __device__ __forceinline__ void gemm_phase(PG8_LAS unsigned char* lds, const Gemm g, const Sched& S, const Epi& E) {
;     ...
;         for (int t = 0; t < nt; t += 2) {
;             const bool last = (t == nt - 2);
;             const char* a1 = PG8_KP(cA, t + 1, rot, nt);
;             const char* a2 = last ? nAr : PG8_KP(cA, t + 2, rot, nt); const char* b2 = last ? nBr : PG8_KP(cB, t + 2, rot, nt);
;             const char* a3 = a2 + kstep; const char* b3 = b2 + kstep;
;             if (last && has_next) S.a_ready(nxt);
;             if constexpr (SP2) {
;             PG8_LDB(B0, 0, 0); PG8_LDB(B1, 0, 1); PG8_SCHED; PG8_LDA(At, 0, 0); PG8_STAGE(PG8_SA(1, 1), a1 + hstep, voffA);
;             PG8_WAIT_V(8); PG8_WAIT_L(0); PG8_BAR; PG8_MMA(0, 0, At, B0); PG8_MMA(0, 1, At, B1); PG8_BAR; PG8_SCHED;
;             PG8_LDA(At, 0, 1); PG8_STAGEB(PG8_SB(0, 0), b2, voffB); PG8_STAGEB(PG8_SB(0, 1), b2 + hstep, voffB); PG8_STAGE(PG8_SA(0, 0), a2, voffA);
.LBB0_270:
	s_add_i32 s81, s29, 2
	s_cmp_lt_u32 s29, 30
	s_cselect_b32 s0, 0, 0xffffffe0
	s_add_i32 s0, s81, s0
	s_ashr_i32 s1, s0, 31
	s_lshl_b64 s[0:1], s[0:1], 7
	s_add_u32 s42, s40, s0
	s_addc_u32 s43, s41, s1
	s_add_u32 s0, s38, s0
	s_addc_u32 s1, s39, s1
	s_cmp_eq_u32 s29, 30
	s_cselect_b32 s59, s49, s43
	s_cselect_b32 s58, s51, s42
	s_cselect_b32 s61, vcc_lo, s1
	s_cselect_b32 s60, vcc_hi, s0
	s_add_i32 s43, 0, 0x10000
	s_add_i32 s97, s43, s70
	s_add_i32 s46, 0, 0x14000
	s_add_i32 m0, s96, 0xc000
	s_add_i32 s69, s96, 0xe000
	s_add_i32 s84, s97, 0x2000
	s_add_u32 s62, s60, 0x80000
	s_addc_u32 s63, s61, 0
	s_add_i32 s4, s46, s70
	v_add_u32_e32 v148, s43, v221
	v_add_u32_e32 v164, s46, v221
	s_add_i32 s5, s4, 0x2000
	s_add_i32 s1, 0, 0x18000
	s_add_i32 s47, 0, 0x1c000
	ds_read_b128 v[136:139], v148
	ds_read_b128 v[140:143], v148 offset:1024
	ds_read_b128 v[144:147], v148 offset:2048
	ds_read_b128 v[148:151], v148 offset:3072
	ds_read_b128 v[152:155], v164
	ds_read_b128 v[156:159], v164 offset:1024
	ds_read_b128 v[160:163], v164 offset:2048
	ds_read_b128 v[164:167], v164 offset:3072
	s_add_u32 s56, s58, 0x80000
	s_addc_u32 s57, s59, 0
	s_add_i32 s0, s1, s70
	s_add_i32 s89, s0, 0x2000
	s_add_u32 s42, s60, 0x80080
	s_addc_u32 s43, s61, 0
	s_add_i32 s46, s47, s70
	s_add_i32 s92, s46, 0x2000
	s_cmp_gt_u32 s29, 29
	ds_read_b128 v[192:195], v222
	ds_read_b128 v[196:199], v222 offset:1024
	ds_read_b128 v[200:203], v222 offset:2048
	ds_read_b128 v[224:227], v222 offset:3072
	ds_read_b128 v[228:231], v222 offset:4096
	ds_read_b128 v[232:235], v222 offset:5120
	ds_read_b128 v[236:239], v222 offset:6144
	ds_read_b128 v[240:243], v222 offset:7168
	global_load_lds_dwordx4 v[134:135], off
	s_mov_b32 m0, s69
	s_nop 0
	global_load_lds_dwordx4 v[132:133], off
	s_waitcnt vmcnt(8)
	s_waitcnt lgkmcnt(0)
	s_barrier
	s_setprio 1
	s_waitcnt lgkmcnt(0)
	v_mfma_f32_16x16x32_bf16 v[128:131], v[136:139], v[192:195], v[128:131]
	v_mfma_f32_16x16x32_bf16 v[112:115], v[136:139], v[200:203], v[112:115]
	v_mfma_f32_16x16x32_bf16 v[94:97], v[136:139], v[228:231], v[94:97]
	v_mfma_f32_16x16x32_bf16 v[78:81], v[136:139], v[236:239], v[78:81]
	v_mfma_f32_16x16x32_bf16 v[74:77], v[144:147], v[236:239], v[74:77]
	v_mfma_f32_16x16x32_bf16 v[90:93], v[144:147], v[228:231], v[90:93]
	v_mfma_f32_16x16x32_bf16 v[108:111], v[144:147], v[200:203], v[108:111]
	v_mfma_f32_16x16x32_bf16 v[124:127], v[144:147], v[192:195], v[124:127]
	v_mfma_f32_16x16x32_bf16 v[128:131], v[140:143], v[196:199], v[128:131]
	v_mfma_f32_16x16x32_bf16 v[112:115], v[140:143], v[224:227], v[112:115]
	v_mfma_f32_16x16x32_bf16 v[94:97], v[140:143], v[232:235], v[94:97]
	v_mfma_f32_16x16x32_bf16 v[78:81], v[140:143], v[240:243], v[78:81]
	v_mfma_f32_16x16x32_bf16 v[74:77], v[148:151], v[240:243], v[74:77]
	v_mfma_f32_16x16x32_bf16 v[90:93], v[148:151], v[232:235], v[90:93]
	v_mfma_f32_16x16x32_bf16 v[108:111], v[148:151], v[224:227], v[108:111]
	v_mfma_f32_16x16x32_bf16 v[124:127], v[148:151], v[196:199], v[124:127]
	s_setprio 0
	s_setprio 1
	v_mfma_f32_16x16x32_bf16 v[120:123], v[152:155], v[192:195], v[120:123]
	v_mfma_f32_16x16x32_bf16 v[104:107], v[152:155], v[200:203], v[104:107]
	v_mfma_f32_16x16x32_bf16 v[86:89], v[152:155], v[228:231], v[86:89]
	v_mfma_f32_16x16x32_bf16 v[70:73], v[152:155], v[236:239], v[70:73]
	v_mfma_f32_16x16x32_bf16 v[66:69], v[160:163], v[236:239], v[66:69]
	v_mfma_f32_16x16x32_bf16 v[82:85], v[160:163], v[228:231], v[82:85]
	v_mfma_f32_16x16x32_bf16 v[100:103], v[160:163], v[200:203], v[100:103]
	v_mfma_f32_16x16x32_bf16 v[116:119], v[160:163], v[192:195], v[116:119]
	v_mfma_f32_16x16x32_bf16 v[120:123], v[156:159], v[196:199], v[120:123]
	v_mfma_f32_16x16x32_bf16 v[104:107], v[156:159], v[224:227], v[104:107]
	v_mfma_f32_16x16x32_bf16 v[86:89], v[156:159], v[232:235], v[86:89]
	v_mfma_f32_16x16x32_bf16 v[70:73], v[156:159], v[240:243], v[70:73]
	v_mfma_f32_16x16x32_bf16 v[66:69], v[164:167], v[240:243], v[66:69]
	v_mfma_f32_16x16x32_bf16 v[82:85], v[164:167], v[232:235], v[82:85]
	v_mfma_f32_16x16x32_bf16 v[100:103], v[164:167], v[224:227], v[100:103]
	v_mfma_f32_16x16x32_bf16 v[116:119], v[164:167], v[196:199], v[116:119]
	s_setprio 0
	s_barrier
	s_mov_b32 m0, s97
	v_lshl_add_u64 v[244:245], s[60:61], 0, v[184:185]
	ds_read_b128 v[192:195], v222 offset:16384
	ds_read_b128 v[196:199], v222 offset:17408
	ds_read_b128 v[200:203], v222 offset:18432
	ds_read_b128 v[224:227], v222 offset:19456
	ds_read_b128 v[228:231], v222 offset:20480
	ds_read_b128 v[232:235], v222 offset:21504
	ds_read_b128 v[236:239], v222 offset:22528
	ds_read_b128 v[240:243], v222 offset:23552
	global_load_lds_dwordx4 v[244:245], off
	v_lshl_add_u64 v[246:247], s[60:61], 0, v[180:181]
	s_mov_b32 m0, s84
	v_lshl_add_u64 v[212:213], s[62:63], 0, v[184:185]
	global_load_lds_dwordx4 v[246:247], off
	s_mov_b32 m0, s4
	v_lshl_add_u64 v[172:173], s[58:59], 0, v[182:183]
	global_load_lds_dwordx4 v[212:213], off
	v_lshl_add_u64 v[212:213], s[62:63], 0, v[180:181]
	s_mov_b32 m0, s5
	s_nop 0
	global_load_lds_dwordx4 v[212:213], off
	v_lshl_add_u64 v[212:213], s[58:59], 0, v[186:187]
	s_mov_b32 m0, s96
	s_nop 0
	global_load_lds_dwordx4 v[212:213], off
	s_mov_b32 m0, s71
	s_nop 0
	global_load_lds_dwordx4 v[172:173], off
	s_waitcnt vmcnt(8)
	s_waitcnt lgkmcnt(0)
	s_barrier
; #define PG8_STAGE(bufoff, gbase, voff) do { _Pragma("unroll") for (int _i = 0; _i < 2; ++_i) \
;         __builtin_amdgcn_global_load_lds((const unsigned*)((const char*)(gbase) + (voff)[_i]), (PG8_LAS unsigned*)(lds + (bufoff) + ldsw + _i * 8192), 16, 0, AUX_A); } while (0)
; #define PG8_LDA(dst, b, h) do { _Pragma("unroll") for (int m = 0; m < 4; ++m) _Pragma("unroll") for (int k = 0; k < 2; ++k) dst[m][k] = *(const PG8_LAS bf16x8*)(lds + PG8_SA(b, h) + aoff + m * 2048 + k * 1024); } while (0)
; #define PG8_LDB(dst, b, h) do { _Pragma("unroll") for (int n = 0; n < 2; ++n) _Pragma("unroll") for (int k = 0; k < 2; ++k) dst[n][k] = *(const PG8_LAS bf16x8*)(lds + PG8_SB(b, h) + boff + n * 2048 + k * 1024); } while (0)
; #define PG8_MMA(ai, bj, At, Bt) do { __builtin_amdgcn_s_setprio(1); _Pragma("unroll") for (int m = 0; m < 4; ++m) _Pragma("unroll") for (int n = 0; n < 2; ++n) _Pragma("unroll") for (int k = 0; k < 2; ++k) \
;         acc[ai][bj][m][n] = __builtin_amdgcn_mfma_f32_16x16x32_bf16(Bt[n][k], At[m][k], acc[ai][bj][m][n], 0, 0, 0); __builtin_amdgcn_s_setprio(0); } while (0)
; #define PG8_WAIT_V(n) asm volatile("s_waitcnt vmcnt(" #n ")" ::: "memory")
; #define PG8_WAIT_L(n) asm volatile("s_waitcnt lgkmcnt(" #n ")" ::: "memory")
; #define PG8_BAR __builtin_amdgcn_s_barrier()
; #define PG8_SCHED __builtin_amdgcn_sched_barrier(0)
; template <class Epi, class Sched, bool ALIGN_EPI = false, bool SP2 = false>
; __device__ __forceinline__ void gemm_phase(PG8_LAS unsigned char* lds, const Gemm g, const Sched& S, const Epi& E) {
;     ...
;             PG8_WAIT_V(8); PG8_WAIT_L(0); PG8_BAR; PG8_MMA(1, 0, At, B0); PG8_MMA(1, 1, At, B1); PG8_BAR; PG8_SCHED;
;             PG8_LDB(B0, 1, 0); PG8_LDB(B1, 1, 1); PG8_SCHED; PG8_LDA(At, 1, 0); PG8_STAGE(PG8_SA(0, 1), a2 + hstep, voffA);
;             PG8_WAIT_V(8); PG8_WAIT_L(0); PG8_BAR; PG8_MMA(0, 0, At, B0); PG8_MMA(0, 1, At, B1); PG8_BAR; PG8_SCHED;
	s_setprio 1
	s_waitcnt lgkmcnt(0)
	v_mfma_f32_16x16x32_bf16 v[62:65], v[136:139], v[192:195], v[62:65]
	v_mfma_f32_16x16x32_bf16 v[46:49], v[136:139], v[200:203], v[46:49]
	v_mfma_f32_16x16x32_bf16 v[30:33], v[136:139], v[228:231], v[30:33]
	v_mfma_f32_16x16x32_bf16 v[14:17], v[136:139], v[236:239], v[14:17]
	v_mfma_f32_16x16x32_bf16 v[10:13], v[144:147], v[236:239], v[10:13]
	v_mfma_f32_16x16x32_bf16 v[26:29], v[144:147], v[228:231], v[26:29]
	v_mfma_f32_16x16x32_bf16 v[42:45], v[144:147], v[200:203], v[42:45]
	v_mfma_f32_16x16x32_bf16 v[58:61], v[144:147], v[192:195], v[58:61]
	v_mfma_f32_16x16x32_bf16 v[62:65], v[140:143], v[196:199], v[62:65]
	v_mfma_f32_16x16x32_bf16 v[46:49], v[140:143], v[224:227], v[46:49]
	v_mfma_f32_16x16x32_bf16 v[30:33], v[140:143], v[232:235], v[30:33]
	v_mfma_f32_16x16x32_bf16 v[14:17], v[140:143], v[240:243], v[14:17]
	v_mfma_f32_16x16x32_bf16 v[10:13], v[148:151], v[240:243], v[10:13]
	v_mfma_f32_16x16x32_bf16 v[26:29], v[148:151], v[232:235], v[26:29]
	v_mfma_f32_16x16x32_bf16 v[42:45], v[148:151], v[224:227], v[42:45]
	v_mfma_f32_16x16x32_bf16 v[58:61], v[148:151], v[196:199], v[58:61]
	s_setprio 0
	s_setprio 1
	v_mfma_f32_16x16x32_bf16 v[54:57], v[152:155], v[192:195], v[54:57]
	v_mfma_f32_16x16x32_bf16 v[38:41], v[152:155], v[200:203], v[38:41]
	v_mfma_f32_16x16x32_bf16 v[22:25], v[152:155], v[228:231], v[22:25]
	v_mfma_f32_16x16x32_bf16 v[6:9], v[152:155], v[236:239], v[6:9]
	v_mfma_f32_16x16x32_bf16 v[2:5], v[160:163], v[236:239], v[2:5]
	v_mfma_f32_16x16x32_bf16 v[18:21], v[160:163], v[228:231], v[18:21]
	v_mfma_f32_16x16x32_bf16 v[34:37], v[160:163], v[200:203], v[34:37]
	v_mfma_f32_16x16x32_bf16 v[50:53], v[160:163], v[192:195], v[50:53]
	v_mfma_f32_16x16x32_bf16 v[54:57], v[156:159], v[196:199], v[54:57]
	v_mfma_f32_16x16x32_bf16 v[38:41], v[156:159], v[224:227], v[38:41]
	v_mfma_f32_16x16x32_bf16 v[22:25], v[156:159], v[232:235], v[22:25]
	v_mfma_f32_16x16x32_bf16 v[6:9], v[156:159], v[240:243], v[6:9]
	v_mfma_f32_16x16x32_bf16 v[2:5], v[164:167], v[240:243], v[2:5]
	v_mfma_f32_16x16x32_bf16 v[18:21], v[164:167], v[232:235], v[18:21]
	v_mfma_f32_16x16x32_bf16 v[34:37], v[164:167], v[224:227], v[34:37]
	v_mfma_f32_16x16x32_bf16 v[50:53], v[164:167], v[196:199], v[50:53]
	s_setprio 0
	s_barrier
	v_add_u32_e32 v148, s1, v221
	v_add_u32_e32 v164, s47, v221
	ds_read_b128 v[136:139], v148
	ds_read_b128 v[140:143], v148 offset:1024
	ds_read_b128 v[144:147], v148 offset:2048
	ds_read_b128 v[148:151], v148 offset:3072
	ds_read_b128 v[152:155], v164
	ds_read_b128 v[156:159], v164 offset:1024
	ds_read_b128 v[160:163], v164 offset:2048
	ds_read_b128 v[164:167], v164 offset:3072
	s_mov_b32 m0, s33
	v_lshl_add_u64 v[168:169], s[56:57], 0, v[186:187]
	ds_read_b128 v[192:195], v222 offset:32768
	ds_read_b128 v[196:199], v222 offset:33792
	ds_read_b128 v[200:203], v222 offset:34816
	ds_read_b128 v[224:227], v222 offset:35840
	ds_read_b128 v[228:231], v222 offset:36864
	ds_read_b128 v[232:235], v222 offset:37888
	ds_read_b128 v[236:239], v222 offset:38912
	ds_read_b128 v[240:243], v222 offset:39936
	global_load_lds_dwordx4 v[168:169], off
	v_lshl_add_u64 v[168:169], s[56:57], 0, v[182:183]
	s_mov_b32 m0, s30
	s_nop 0
	global_load_lds_dwordx4 v[168:169], off
	s_waitcnt vmcnt(8)
	s_waitcnt lgkmcnt(0)
	s_barrier
	s_setprio 1
	s_waitcnt lgkmcnt(0)
	v_mfma_f32_16x16x32_bf16 v[128:131], v[136:139], v[192:195], v[128:131]
	v_mfma_f32_16x16x32_bf16 v[112:115], v[136:139], v[200:203], v[112:115]
	v_mfma_f32_16x16x32_bf16 v[94:97], v[136:139], v[228:231], v[94:97]
	v_mfma_f32_16x16x32_bf16 v[78:81], v[136:139], v[236:239], v[78:81]
	v_mfma_f32_16x16x32_bf16 v[74:77], v[144:147], v[236:239], v[74:77]
	v_mfma_f32_16x16x32_bf16 v[90:93], v[144:147], v[228:231], v[90:93]
	v_mfma_f32_16x16x32_bf16 v[108:111], v[144:147], v[200:203], v[108:111]
	v_mfma_f32_16x16x32_bf16 v[124:127], v[144:147], v[192:195], v[124:127]
	v_mfma_f32_16x16x32_bf16 v[128:131], v[140:143], v[196:199], v[128:131]
	v_mfma_f32_16x16x32_bf16 v[112:115], v[140:143], v[224:227], v[112:115]
	v_mfma_f32_16x16x32_bf16 v[94:97], v[140:143], v[232:235], v[94:97]
	v_mfma_f32_16x16x32_bf16 v[78:81], v[140:143], v[240:243], v[78:81]
	v_mfma_f32_16x16x32_bf16 v[74:77], v[148:151], v[240:243], v[74:77]
	v_mfma_f32_16x16x32_bf16 v[90:93], v[148:151], v[232:235], v[90:93]
	v_mfma_f32_16x16x32_bf16 v[108:111], v[148:151], v[224:227], v[108:111]
	v_mfma_f32_16x16x32_bf16 v[124:127], v[148:151], v[196:199], v[124:127]
	s_setprio 0
	s_setprio 1
	v_mfma_f32_16x16x32_bf16 v[120:123], v[152:155], v[192:195], v[120:123]
	v_mfma_f32_16x16x32_bf16 v[104:107], v[152:155], v[200:203], v[104:107]
	v_mfma_f32_16x16x32_bf16 v[86:89], v[152:155], v[228:231], v[86:89]
	v_mfma_f32_16x16x32_bf16 v[70:73], v[152:155], v[236:239], v[70:73]
	v_mfma_f32_16x16x32_bf16 v[66:69], v[160:163], v[236:239], v[66:69]
	v_mfma_f32_16x16x32_bf16 v[82:85], v[160:163], v[228:231], v[82:85]
	v_mfma_f32_16x16x32_bf16 v[100:103], v[160:163], v[200:203], v[100:103]
	v_mfma_f32_16x16x32_bf16 v[116:119], v[160:163], v[192:195], v[116:119]
	v_mfma_f32_16x16x32_bf16 v[120:123], v[156:159], v[196:199], v[120:123]
	v_mfma_f32_16x16x32_bf16 v[104:107], v[156:159], v[224:227], v[104:107]
	v_mfma_f32_16x16x32_bf16 v[86:89], v[156:159], v[232:235], v[86:89]
	v_mfma_f32_16x16x32_bf16 v[70:73], v[156:159], v[240:243], v[70:73]
	v_mfma_f32_16x16x32_bf16 v[66:69], v[164:167], v[240:243], v[66:69]
	v_mfma_f32_16x16x32_bf16 v[82:85], v[164:167], v[232:235], v[82:85]
	v_mfma_f32_16x16x32_bf16 v[100:103], v[164:167], v[224:227], v[100:103]
	v_mfma_f32_16x16x32_bf16 v[116:119], v[164:167], v[196:199], v[116:119]
	s_setprio 0
	s_barrier
; #define PG8_STAGE(bufoff, gbase, voff) do { _Pragma("unroll") for (int _i = 0; _i < 2; ++_i) \
;         __builtin_amdgcn_global_load_lds((const unsigned*)((const char*)(gbase) + (voff)[_i]), (PG8_LAS unsigned*)(lds + (bufoff) + ldsw + _i * 8192), 16, 0, AUX_A); } while (0)
; #define PG8_STAGEB(bufoff, gbase, voff) do { _Pragma("unroll") for (int _i = 0; _i < 2; ++_i) \
;         __builtin_amdgcn_global_load_lds((const unsigned*)((const char*)(gbase) + (voff)[_i]), (PG8_LAS unsigned*)(lds + (bufoff) + ldsw + _i * 8192), 16, 0, AUX_B); } while (0)
; #define PG8_LDA(dst, b, h) do { _Pragma("unroll") for (int m = 0; m < 4; ++m) _Pragma("unroll") for (int k = 0; k < 2; ++k) dst[m][k] = *(const PG8_LAS bf16x8*)(lds + PG8_SA(b, h) + aoff + m * 2048 + k * 1024); } while (0)
; #define PG8_MMA(ai, bj, At, Bt) do { __builtin_amdgcn_s_setprio(1); _Pragma("unroll") for (int m = 0; m < 4; ++m) _Pragma("unroll") for (int n = 0; n < 2; ++n) _Pragma("unroll") for (int k = 0; k < 2; ++k) \
;         acc[ai][bj][m][n] = __builtin_amdgcn_mfma_f32_16x16x32_bf16(Bt[n][k], At[m][k], acc[ai][bj][m][n], 0, 0, 0); __builtin_amdgcn_s_setprio(0); } while (0)
; #define PG8_WAIT_V(n) asm volatile("s_waitcnt vmcnt(" #n ")" ::: "memory")
; #define PG8_WAIT_L(n) asm volatile("s_waitcnt lgkmcnt(" #n ")" ::: "memory")
; #define PG8_BAR __builtin_amdgcn_s_barrier()
; #define PG8_SCHED __builtin_amdgcn_sched_barrier(0)
; template <class Epi, class Sched, bool ALIGN_EPI = false, bool SP2 = false>
; __device__ __forceinline__ void gemm_phase(PG8_LAS unsigned char* lds, const Gemm g, const Sched& S, const Epi& E) {
;     ...
;             PG8_LDA(At, 1, 1); PG8_STAGEB(PG8_SB(1, 0), b3, voffB); PG8_STAGEB(PG8_SB(1, 1), b3 + hstep, voffB); PG8_STAGE(PG8_SA(1, 0), a3, voffA);
;             PG8_WAIT_V(8); PG8_WAIT_L(0); PG8_BAR; PG8_MMA(1, 0, At, B0); PG8_MMA(1, 1, At, B1); PG8_BAR; PG8_SCHED;
	s_mov_b32 m0, s0
	v_lshl_add_u64 v[168:169], v[244:245], 0, s[76:77]
	ds_read_b128 v[192:195], v222 offset:49152
	ds_read_b128 v[196:199], v222 offset:50176
	ds_read_b128 v[200:203], v222 offset:51200
	ds_read_b128 v[224:227], v222 offset:52224
	ds_read_b128 v[228:231], v222 offset:53248
	ds_read_b128 v[232:235], v222 offset:54272
	ds_read_b128 v[236:239], v222 offset:55296
	ds_read_b128 v[240:243], v222 offset:56320
	global_load_lds_dwordx4 v[168:169], off
	v_lshl_add_u64 v[168:169], v[246:247], 0, s[76:77]
	s_mov_b32 m0, s89
	s_nop 0
	global_load_lds_dwordx4 v[168:169], off
	v_lshl_add_u64 v[168:169], s[42:43], 0, v[184:185]
	s_mov_b32 m0, s46
	s_nop 0
	global_load_lds_dwordx4 v[168:169], off
	v_lshl_add_u64 v[168:169], s[42:43], 0, v[180:181]
	s_mov_b32 m0, s92
	s_nop 0
	global_load_lds_dwordx4 v[168:169], off
	v_lshl_add_u64 v[168:169], v[212:213], 0, s[76:77]
	s_mov_b32 m0, s90
	s_nop 0
	global_load_lds_dwordx4 v[168:169], off
	v_lshl_add_u64 v[168:169], v[172:173], 0, s[76:77]
	s_mov_b32 m0, s91
	s_nop 0
	global_load_lds_dwordx4 v[168:169], off
	s_waitcnt vmcnt(8)
	s_waitcnt lgkmcnt(0)
	s_barrier
	s_setprio 1
	s_waitcnt lgkmcnt(0)
	v_mfma_f32_16x16x32_bf16 v[62:65], v[136:139], v[192:195], v[62:65]
	v_mfma_f32_16x16x32_bf16 v[46:49], v[136:139], v[200:203], v[46:49]
	v_mfma_f32_16x16x32_bf16 v[30:33], v[136:139], v[228:231], v[30:33]
	v_mfma_f32_16x16x32_bf16 v[14:17], v[136:139], v[236:239], v[14:17]
	v_mfma_f32_16x16x32_bf16 v[10:13], v[144:147], v[236:239], v[10:13]
	v_mfma_f32_16x16x32_bf16 v[26:29], v[144:147], v[228:231], v[26:29]
	v_mfma_f32_16x16x32_bf16 v[42:45], v[144:147], v[200:203], v[42:45]
	v_mfma_f32_16x16x32_bf16 v[58:61], v[144:147], v[192:195], v[58:61]
	v_mfma_f32_16x16x32_bf16 v[62:65], v[140:143], v[196:199], v[62:65]
	v_mfma_f32_16x16x32_bf16 v[46:49], v[140:143], v[224:227], v[46:49]
	v_mfma_f32_16x16x32_bf16 v[30:33], v[140:143], v[232:235], v[30:33]
	v_mfma_f32_16x16x32_bf16 v[14:17], v[140:143], v[240:243], v[14:17]
	v_mfma_f32_16x16x32_bf16 v[10:13], v[148:151], v[240:243], v[10:13]
	v_mfma_f32_16x16x32_bf16 v[26:29], v[148:151], v[232:235], v[26:29]
	v_mfma_f32_16x16x32_bf16 v[42:45], v[148:151], v[224:227], v[42:45]
	v_mfma_f32_16x16x32_bf16 v[58:61], v[148:151], v[196:199], v[58:61]
	s_setprio 0
	s_setprio 1
	v_mfma_f32_16x16x32_bf16 v[54:57], v[152:155], v[192:195], v[54:57]
	v_mfma_f32_16x16x32_bf16 v[38:41], v[152:155], v[200:203], v[38:41]
	v_mfma_f32_16x16x32_bf16 v[22:25], v[152:155], v[228:231], v[22:25]
	v_mfma_f32_16x16x32_bf16 v[6:9], v[152:155], v[236:239], v[6:9]
	v_mfma_f32_16x16x32_bf16 v[2:5], v[160:163], v[236:239], v[2:5]
	v_mfma_f32_16x16x32_bf16 v[18:21], v[160:163], v[228:231], v[18:21]
	v_mfma_f32_16x16x32_bf16 v[34:37], v[160:163], v[200:203], v[34:37]
	v_mfma_f32_16x16x32_bf16 v[50:53], v[160:163], v[192:195], v[50:53]
	v_mfma_f32_16x16x32_bf16 v[54:57], v[156:159], v[196:199], v[54:57]
	v_mfma_f32_16x16x32_bf16 v[38:41], v[156:159], v[224:227], v[38:41]
	v_mfma_f32_16x16x32_bf16 v[22:25], v[156:159], v[232:235], v[22:25]
	v_mfma_f32_16x16x32_bf16 v[6:9], v[156:159], v[240:243], v[6:9]
	v_mfma_f32_16x16x32_bf16 v[2:5], v[164:167], v[240:243], v[2:5]
	v_mfma_f32_16x16x32_bf16 v[18:21], v[164:167], v[232:235], v[18:21]
	v_mfma_f32_16x16x32_bf16 v[34:37], v[164:167], v[224:227], v[34:37]
	v_mfma_f32_16x16x32_bf16 v[50:53], v[164:167], v[196:199], v[50:53]
	s_setprio 0
	s_barrier
	v_lshl_add_u64 v[132:133], v[132:133], 0, s[86:87]
	v_lshl_add_u64 v[134:135], v[134:135], 0, s[86:87]
	s_mov_b32 s29, s81
	s_cbranch_scc0 .LBB0_270
	s_and_b64 vcc, exec, s[10:11]
	s_cbranch_vccz .LBB0_273
	s_barrier

; #define PG8_STAGE(bufoff, gbase, voff) do { _Pragma("unroll") for (int _i = 0; _i < 2; ++_i) \
;         __builtin_amdgcn_global_load_lds((const unsigned*)((const char*)(gbase) + (voff)[_i]), (PG8_LAS unsigned*)(lds + (bufoff) + ldsw + _i * 8192), 16, 0, AUX_A); } while (0)
; #define PG8_STAGEB(bufoff, gbase, voff) do { _Pragma("unroll") for (int _i = 0; _i < 2; ++_i) \
;         __builtin_amdgcn_global_load_lds((const unsigned*)((const char*)(gbase) + (voff)[_i]), (PG8_LAS unsigned*)(lds + (bufoff) + ldsw + _i * 8192), 16, 0, AUX_B); } while (0)
; #define PG8_LDA(dst, b, h) do { _Pragma("unroll") for (int m = 0; m < 4; ++m) _Pragma("unroll") for (int k = 0; k < 2; ++k) dst[m][k] = *(const PG8_LAS bf16x8*)(lds + PG8_SA(b, h) + aoff + m * 2048 + k * 1024); } while (0)
; #define PG8_LDB(dst, b, h) do { _Pragma("unroll") for (int n = 0; n < 2; ++n) _Pragma("unroll") for (int k = 0; k < 2; ++k) dst[n][k] = *(const PG8_LAS bf16x8*)(lds + PG8_SB(b, h) + boff + n * 2048 + k * 1024); } while (0)
; #define PG8_WAIT_V(n) asm volatile("s_waitcnt vmcnt(" #n ")" ::: "memory")
; #define PG8_WAIT_L(n) asm volatile("s_waitcnt lgkmcnt(" #n ")" ::: "memory")
; #define PG8_BAR __builtin_amdgcn_s_barrier()
; #define PG8_SCHED __builtin_amdgcn_sched_barrier(0)
; template <class Epi, class Sched, bool ALIGN_EPI = false, bool SP2 = false>
; __device__ __forceinline__ void gemm_phase(PG8_LAS unsigned char* lds, const Gemm g, const Sched& S, const Epi& E) {
;     ...
;         for (int t = 0; t < nt; t += 2) {
;             const bool last = (t == nt - 2);
;             const char* a1 = PG8_KP(cA, t + 1, rot, nt);
;             const char* a2 = last ? nAr : PG8_KP(cA, t + 2, rot, nt); const char* b2 = last ? nBr : PG8_KP(cB, t + 2, rot, nt);
;             const char* a3 = a2 + kstep; const char* b3 = b2 + kstep;
;             if (last && has_next) S.a_ready(nxt);
;             if constexpr (SP2) {
;             PG8_LDB(B0, 0, 0); PG8_LDB(B1, 0, 1); PG8_SCHED; PG8_LDA(At, 0, 0); PG8_STAGE(PG8_SA(1, 1), a1 + hstep, voffA);
;             PG8_WAIT_V(8); PG8_WAIT_L(0); PG8_BAR; PG8_MMA(0, 0, At, B0); PG8_MMA(0, 1, At, B1); PG8_BAR; PG8_SCHED;
;             PG8_LDA(At, 0, 1); PG8_STAGEB(PG8_SB(0, 0), b2, voffB); PG8_STAGEB(PG8_SB(0, 1), b2 + hstep, voffB); PG8_STAGE(PG8_SA(0, 0), a2, voffA);
.LBB0_936:
	s_add_i32 s81, s29, 2
	s_cmp_lt_u32 s29, 14
	s_cselect_b32 s0, 0, -16
	s_add_i32 s0, s81, s0
	s_ashr_i32 s1, s0, 31
	s_lshl_b64 s[0:1], s[0:1], 7
	s_add_u32 s2, s64, s0
	s_addc_u32 s46, s65, s1
	s_add_u32 s0, s26, s0
	s_addc_u32 s1, s27, s1
	s_cmp_eq_u32 s29, 14
	s_cselect_b32 s57, s15, s46
	s_cselect_b32 s56, s17, s2
	s_cselect_b32 s59, s43, s1
	s_cselect_b32 s58, s78, s0
	s_add_i32 s2, 0, 0x10000
	s_add_i32 s83, s2, s33
	s_add_i32 s46, 0, 0x14000
	s_add_i32 m0, s25, 0xc000
	s_add_i32 s82, s25, 0xe000
	s_add_i32 s84, s83, 0x2000
	s_add_u32 s60, s58, 0x40000
	s_addc_u32 s61, s59, 0
	s_add_i32 s88, s46, s33
	v_add_u32_e32 v160, s2, v99
	v_add_u32_e32 v166, s46, v99
	s_add_i32 s89, s88, 0x2000
	s_add_i32 s90, 0, 0x18000
	s_add_i32 s91, 0, 0x1c000
	ds_read_b128 v[22:25], v160
	ds_read_b128 v[34:37], v160 offset:1024
	ds_read_b128 v[38:41], v160 offset:2048
	ds_read_b128 v[160:163], v160 offset:3072
	ds_read_b128 v[180:183], v166
	ds_read_b128 v[184:187], v166 offset:1024
	ds_read_b128 v[188:191], v166 offset:2048
	ds_read_b128 v[192:195], v166 offset:3072
	s_add_u32 s54, s56, 0x40000
	s_addc_u32 s55, s57, 0
	s_add_i32 s1, s90, s33
	s_add_i32 s0, s1, 0x2000
	s_add_u32 s52, s58, 0x40080
	s_addc_u32 s53, s59, 0
	s_add_i32 s47, s91, s33
	s_add_i32 s46, s47, 0x2000
	s_cmp_gt_u32 s29, 13
	ds_read_b128 v[196:199], v165
	ds_read_b128 v[200:203], v165 offset:1024
	ds_read_b128 v[222:225], v165 offset:2048
	ds_read_b128 v[226:229], v165 offset:3072
	ds_read_b128 v[230:233], v165 offset:4096
	ds_read_b128 v[234:237], v165 offset:5120
	ds_read_b128 v[238:241], v165 offset:6144
	ds_read_b128 v[242:245], v165 offset:7168
	global_load_lds_dwordx4 v[16:17], off
	s_mov_b32 m0, s82
	s_nop 0
	global_load_lds_dwordx4 v[14:15], off
	s_waitcnt vmcnt(8)
	s_waitcnt lgkmcnt(0)
	s_barrier
	s_setprio 1
	s_waitcnt lgkmcnt(0)
	v_mfma_f32_16x16x32_bf16 v[144:147], v[22:25], v[196:199], v[144:147]
	v_mfma_f32_16x16x32_bf16 v[128:131], v[22:25], v[222:225], v[128:131]
	v_mfma_f32_16x16x32_bf16 v[112:115], v[22:25], v[230:233], v[112:115]
	v_mfma_f32_16x16x32_bf16 v[94:97], v[22:25], v[238:241], v[94:97]
	v_mfma_f32_16x16x32_bf16 v[90:93], v[38:41], v[238:241], v[90:93]
	v_mfma_f32_16x16x32_bf16 v[108:111], v[38:41], v[230:233], v[108:111]
	v_mfma_f32_16x16x32_bf16 v[124:127], v[38:41], v[222:225], v[124:127]
	v_mfma_f32_16x16x32_bf16 v[140:143], v[38:41], v[196:199], v[140:143]
	v_mfma_f32_16x16x32_bf16 v[144:147], v[34:37], v[200:203], v[144:147]
	v_mfma_f32_16x16x32_bf16 v[128:131], v[34:37], v[226:229], v[128:131]
	v_mfma_f32_16x16x32_bf16 v[112:115], v[34:37], v[234:237], v[112:115]
	v_mfma_f32_16x16x32_bf16 v[94:97], v[34:37], v[242:245], v[94:97]
	v_mfma_f32_16x16x32_bf16 v[90:93], v[160:163], v[242:245], v[90:93]
	v_mfma_f32_16x16x32_bf16 v[108:111], v[160:163], v[234:237], v[108:111]
	v_mfma_f32_16x16x32_bf16 v[124:127], v[160:163], v[226:229], v[124:127]
	v_mfma_f32_16x16x32_bf16 v[140:143], v[160:163], v[200:203], v[140:143]
	s_setprio 0
	s_setprio 1
	v_mfma_f32_16x16x32_bf16 v[136:139], v[180:183], v[196:199], v[136:139]
	v_mfma_f32_16x16x32_bf16 v[120:123], v[180:183], v[222:225], v[120:123]
	v_mfma_f32_16x16x32_bf16 v[104:107], v[180:183], v[230:233], v[104:107]
	v_mfma_f32_16x16x32_bf16 v[86:89], v[180:183], v[238:241], v[86:89]
	v_mfma_f32_16x16x32_bf16 v[82:85], v[188:191], v[238:241], v[82:85]
	v_mfma_f32_16x16x32_bf16 v[100:103], v[188:191], v[230:233], v[100:103]
	v_mfma_f32_16x16x32_bf16 v[116:119], v[188:191], v[222:225], v[116:119]
	v_mfma_f32_16x16x32_bf16 v[132:135], v[188:191], v[196:199], v[132:135]
	v_mfma_f32_16x16x32_bf16 v[136:139], v[184:187], v[200:203], v[136:139]
	v_mfma_f32_16x16x32_bf16 v[120:123], v[184:187], v[226:229], v[120:123]
	v_mfma_f32_16x16x32_bf16 v[104:107], v[184:187], v[234:237], v[104:107]
	v_mfma_f32_16x16x32_bf16 v[86:89], v[184:187], v[242:245], v[86:89]
	v_mfma_f32_16x16x32_bf16 v[82:85], v[192:195], v[242:245], v[82:85]
	v_mfma_f32_16x16x32_bf16 v[100:103], v[192:195], v[234:237], v[100:103]
	v_mfma_f32_16x16x32_bf16 v[116:119], v[192:195], v[226:229], v[116:119]
	v_mfma_f32_16x16x32_bf16 v[132:135], v[192:195], v[200:203], v[132:135]
	s_setprio 0
	s_barrier
	s_mov_b32 m0, s83
	v_lshl_add_u64 v[166:167], s[58:59], 0, v[150:151]
	ds_read_b128 v[196:199], v165 offset:16384
	ds_read_b128 v[200:203], v165 offset:17408
	ds_read_b128 v[222:225], v165 offset:18432
	ds_read_b128 v[226:229], v165 offset:19456
	ds_read_b128 v[230:233], v165 offset:20480
	ds_read_b128 v[234:237], v165 offset:21504
	ds_read_b128 v[238:241], v165 offset:22528
	ds_read_b128 v[242:245], v165 offset:23552
	global_load_lds_dwordx4 v[166:167], off
	v_lshl_add_u64 v[168:169], s[58:59], 0, v[154:155]
	s_mov_b32 m0, s84
	v_lshl_add_u64 v[172:173], s[60:61], 0, v[150:151]
	global_load_lds_dwordx4 v[168:169], off
	s_mov_b32 m0, s88
	v_lshl_add_u64 v[212:213], s[56:57], 0, v[152:153]
	global_load_lds_dwordx4 v[172:173], off
	v_lshl_add_u64 v[172:173], s[60:61], 0, v[154:155]
	s_mov_b32 m0, s89
	s_nop 0
	global_load_lds_dwordx4 v[172:173], off
	v_lshl_add_u64 v[172:173], s[56:57], 0, v[148:149]
	s_mov_b32 m0, s25
	s_nop 0
	global_load_lds_dwordx4 v[172:173], off
	s_mov_b32 m0, s62
	s_nop 0
	global_load_lds_dwordx4 v[212:213], off
	s_waitcnt vmcnt(8)
	s_waitcnt lgkmcnt(0)
	s_barrier
; #define PG8_STAGE(bufoff, gbase, voff) do { _Pragma("unroll") for (int _i = 0; _i < 2; ++_i) \
;         __builtin_amdgcn_global_load_lds((const unsigned*)((const char*)(gbase) + (voff)[_i]), (PG8_LAS unsigned*)(lds + (bufoff) + ldsw + _i * 8192), 16, 0, AUX_A); } while (0)
; #define PG8_LDA(dst, b, h) do { _Pragma("unroll") for (int m = 0; m < 4; ++m) _Pragma("unroll") for (int k = 0; k < 2; ++k) dst[m][k] = *(const PG8_LAS bf16x8*)(lds + PG8_SA(b, h) + aoff + m * 2048 + k * 1024); } while (0)
; #define PG8_LDB(dst, b, h) do { _Pragma("unroll") for (int n = 0; n < 2; ++n) _Pragma("unroll") for (int k = 0; k < 2; ++k) dst[n][k] = *(const PG8_LAS bf16x8*)(lds + PG8_SB(b, h) + boff + n * 2048 + k * 1024); } while (0)
; #define PG8_MMA(ai, bj, At, Bt) do { __builtin_amdgcn_s_setprio(1); _Pragma("unroll") for (int m = 0; m < 4; ++m) _Pragma("unroll") for (int n = 0; n < 2; ++n) _Pragma("unroll") for (int k = 0; k < 2; ++k) \
;         acc[ai][bj][m][n] = __builtin_amdgcn_mfma_f32_16x16x32_bf16(Bt[n][k], At[m][k], acc[ai][bj][m][n], 0, 0, 0); __builtin_amdgcn_s_setprio(0); } while (0)
; #define PG8_WAIT_V(n) asm volatile("s_waitcnt vmcnt(" #n ")" ::: "memory")
; #define PG8_WAIT_L(n) asm volatile("s_waitcnt lgkmcnt(" #n ")" ::: "memory")
; #define PG8_BAR __builtin_amdgcn_s_barrier()
; #define PG8_SCHED __builtin_amdgcn_sched_barrier(0)
; template <class Epi, class Sched, bool ALIGN_EPI = false, bool SP2 = false>
; __device__ __forceinline__ void gemm_phase(PG8_LAS unsigned char* lds, const Gemm g, const Sched& S, const Epi& E) {
;     ...
;             PG8_WAIT_V(8); PG8_WAIT_L(0); PG8_BAR; PG8_MMA(1, 0, At, B0); PG8_MMA(1, 1, At, B1); PG8_BAR; PG8_SCHED;
;             PG8_LDB(B0, 1, 0); PG8_LDB(B1, 1, 1); PG8_SCHED; PG8_LDA(At, 1, 0); PG8_STAGE(PG8_SA(0, 1), a2 + hstep, voffA);
;             PG8_WAIT_V(8); PG8_WAIT_L(0); PG8_BAR; PG8_MMA(0, 0, At, B0); PG8_MMA(0, 1, At, B1); PG8_BAR; PG8_SCHED;
	s_setprio 1
	s_waitcnt lgkmcnt(0)
	v_mfma_f32_16x16x32_bf16 v[78:81], v[22:25], v[196:199], v[78:81]
	v_mfma_f32_16x16x32_bf16 v[62:65], v[22:25], v[222:225], v[62:65]
	v_mfma_f32_16x16x32_bf16 v[46:49], v[22:25], v[230:233], v[46:49]
	v_mfma_f32_16x16x32_bf16 v[18:21], v[22:25], v[238:241], v[18:21]
	v_mfma_f32_16x16x32_bf16 v[10:13], v[38:41], v[238:241], v[10:13]
	v_mfma_f32_16x16x32_bf16 v[42:45], v[38:41], v[230:233], v[42:45]
	v_mfma_f32_16x16x32_bf16 v[58:61], v[38:41], v[222:225], v[58:61]
	v_mfma_f32_16x16x32_bf16 v[74:77], v[38:41], v[196:199], v[74:77]
	v_mfma_f32_16x16x32_bf16 v[78:81], v[34:37], v[200:203], v[78:81]
	v_mfma_f32_16x16x32_bf16 v[62:65], v[34:37], v[226:229], v[62:65]
	v_mfma_f32_16x16x32_bf16 v[46:49], v[34:37], v[234:237], v[46:49]
	v_mfma_f32_16x16x32_bf16 v[18:21], v[34:37], v[242:245], v[18:21]
	v_mfma_f32_16x16x32_bf16 v[10:13], v[160:163], v[242:245], v[10:13]
	v_mfma_f32_16x16x32_bf16 v[42:45], v[160:163], v[234:237], v[42:45]
	v_mfma_f32_16x16x32_bf16 v[58:61], v[160:163], v[226:229], v[58:61]
	v_mfma_f32_16x16x32_bf16 v[74:77], v[160:163], v[200:203], v[74:77]
	s_setprio 0
	s_setprio 1
	v_mfma_f32_16x16x32_bf16 v[50:53], v[188:191], v[222:225], v[50:53]
	v_mfma_f32_16x16x32_bf16 v[26:29], v[188:191], v[230:233], v[26:29]
	v_mfma_f32_16x16x32_bf16 v[2:5], v[188:191], v[238:241], v[2:5]
	v_mfma_f32_16x16x32_bf16 v[34:37], v[188:191], v[196:199], v[66:69]
	v_mfma_f32_16x16x32_bf16 v[22:25], v[180:183], v[196:199], v[70:73]
	v_mfma_f32_16x16x32_bf16 v[6:9], v[180:183], v[238:241], v[6:9]
	v_mfma_f32_16x16x32_bf16 v[30:33], v[180:183], v[230:233], v[30:33]
	v_mfma_f32_16x16x32_bf16 v[38:41], v[180:183], v[222:225], v[54:57]
	v_mfma_f32_16x16x32_bf16 v[50:53], v[192:195], v[226:229], v[50:53]
	v_mfma_f32_16x16x32_bf16 v[26:29], v[192:195], v[234:237], v[26:29]
	v_mfma_f32_16x16x32_bf16 v[2:5], v[192:195], v[242:245], v[2:5]
	v_mfma_f32_16x16x32_bf16 v[34:37], v[192:195], v[200:203], v[34:37]
	v_mfma_f32_16x16x32_bf16 v[22:25], v[184:187], v[200:203], v[22:25]
	v_mfma_f32_16x16x32_bf16 v[6:9], v[184:187], v[242:245], v[6:9]
	v_mfma_f32_16x16x32_bf16 v[30:33], v[184:187], v[234:237], v[30:33]
	v_mfma_f32_16x16x32_bf16 v[38:41], v[184:187], v[226:229], v[38:41]
	s_setprio 0
	s_barrier
	v_add_u32_e32 v160, s90, v99
	v_add_u32_e32 v192, s91, v99
	ds_read_b128 v[54:57], v160
	ds_read_b128 v[66:69], v160 offset:1024
	ds_read_b128 v[70:73], v160 offset:2048
	ds_read_b128 v[160:163], v160 offset:3072
	ds_read_b128 v[180:183], v192
	ds_read_b128 v[184:187], v192 offset:1024
	ds_read_b128 v[188:191], v192 offset:2048
	ds_read_b128 v[192:195], v192 offset:3072
	s_mov_b32 m0, s63
	v_lshl_add_u64 v[246:247], s[54:55], 0, v[148:149]
	ds_read_b128 v[196:199], v165 offset:32768
	ds_read_b128 v[200:203], v165 offset:33792
	ds_read_b128 v[222:225], v165 offset:34816
	ds_read_b128 v[226:229], v165 offset:35840
	ds_read_b128 v[230:233], v165 offset:36864
	ds_read_b128 v[234:237], v165 offset:37888
	ds_read_b128 v[238:241], v165 offset:38912
	ds_read_b128 v[242:245], v165 offset:39936
	global_load_lds_dwordx4 v[246:247], off
	v_lshl_add_u64 v[246:247], s[54:55], 0, v[152:153]
	s_mov_b32 m0, s69
	s_nop 0
	global_load_lds_dwordx4 v[246:247], off
	s_waitcnt vmcnt(8)
	s_waitcnt lgkmcnt(0)
	s_barrier
	s_setprio 1
	s_waitcnt lgkmcnt(0)
	v_mfma_f32_16x16x32_bf16 v[144:147], v[54:57], v[196:199], v[144:147]
	v_mfma_f32_16x16x32_bf16 v[128:131], v[54:57], v[222:225], v[128:131]
	v_mfma_f32_16x16x32_bf16 v[112:115], v[54:57], v[230:233], v[112:115]
	v_mfma_f32_16x16x32_bf16 v[94:97], v[54:57], v[238:241], v[94:97]
	v_mfma_f32_16x16x32_bf16 v[90:93], v[70:73], v[238:241], v[90:93]
	v_mfma_f32_16x16x32_bf16 v[108:111], v[70:73], v[230:233], v[108:111]
	v_mfma_f32_16x16x32_bf16 v[124:127], v[70:73], v[222:225], v[124:127]
	v_mfma_f32_16x16x32_bf16 v[140:143], v[70:73], v[196:199], v[140:143]
	v_mfma_f32_16x16x32_bf16 v[144:147], v[66:69], v[200:203], v[144:147]
	v_mfma_f32_16x16x32_bf16 v[128:131], v[66:69], v[226:229], v[128:131]
	v_mfma_f32_16x16x32_bf16 v[112:115], v[66:69], v[234:237], v[112:115]
	v_mfma_f32_16x16x32_bf16 v[94:97], v[66:69], v[242:245], v[94:97]
	v_mfma_f32_16x16x32_bf16 v[90:93], v[160:163], v[242:245], v[90:93]
	v_mfma_f32_16x16x32_bf16 v[108:111], v[160:163], v[234:237], v[108:111]
	v_mfma_f32_16x16x32_bf16 v[124:127], v[160:163], v[226:229], v[124:127]
	v_mfma_f32_16x16x32_bf16 v[140:143], v[160:163], v[200:203], v[140:143]
	s_setprio 0
	s_setprio 1
	v_mfma_f32_16x16x32_bf16 v[136:139], v[180:183], v[196:199], v[136:139]
	v_mfma_f32_16x16x32_bf16 v[120:123], v[180:183], v[222:225], v[120:123]
	v_mfma_f32_16x16x32_bf16 v[104:107], v[180:183], v[230:233], v[104:107]
	v_mfma_f32_16x16x32_bf16 v[86:89], v[180:183], v[238:241], v[86:89]
	v_mfma_f32_16x16x32_bf16 v[82:85], v[188:191], v[238:241], v[82:85]
	v_mfma_f32_16x16x32_bf16 v[100:103], v[188:191], v[230:233], v[100:103]
	v_mfma_f32_16x16x32_bf16 v[116:119], v[188:191], v[222:225], v[116:119]
	v_mfma_f32_16x16x32_bf16 v[132:135], v[188:191], v[196:199], v[132:135]
	v_mfma_f32_16x16x32_bf16 v[136:139], v[184:187], v[200:203], v[136:139]
	v_mfma_f32_16x16x32_bf16 v[120:123], v[184:187], v[226:229], v[120:123]
	v_mfma_f32_16x16x32_bf16 v[104:107], v[184:187], v[234:237], v[104:107]
	v_mfma_f32_16x16x32_bf16 v[86:89], v[184:187], v[242:245], v[86:89]
	v_mfma_f32_16x16x32_bf16 v[82:85], v[192:195], v[242:245], v[82:85]
	v_mfma_f32_16x16x32_bf16 v[100:103], v[192:195], v[234:237], v[100:103]
	v_mfma_f32_16x16x32_bf16 v[116:119], v[192:195], v[226:229], v[116:119]
	v_mfma_f32_16x16x32_bf16 v[132:135], v[192:195], v[200:203], v[132:135]
	s_setprio 0
	s_barrier
; #define PG8_STAGE(bufoff, gbase, voff) do { _Pragma("unroll") for (int _i = 0; _i < 2; ++_i) \
;         __builtin_amdgcn_global_load_lds((const unsigned*)((const char*)(gbase) + (voff)[_i]), (PG8_LAS unsigned*)(lds + (bufoff) + ldsw + _i * 8192), 16, 0, AUX_A); } while (0)
; #define PG8_STAGEB(bufoff, gbase, voff) do { _Pragma("unroll") for (int _i = 0; _i < 2; ++_i) \
;         __builtin_amdgcn_global_load_lds((const unsigned*)((const char*)(gbase) + (voff)[_i]), (PG8_LAS unsigned*)(lds + (bufoff) + ldsw + _i * 8192), 16, 0, AUX_B); } while (0)
; #define PG8_LDA(dst, b, h) do { _Pragma("unroll") for (int m = 0; m < 4; ++m) _Pragma("unroll") for (int k = 0; k < 2; ++k) dst[m][k] = *(const PG8_LAS bf16x8*)(lds + PG8_SA(b, h) + aoff + m * 2048 + k * 1024); } while (0)
; #define PG8_MMA(ai, bj, At, Bt) do { __builtin_amdgcn_s_setprio(1); _Pragma("unroll") for (int m = 0; m < 4; ++m) _Pragma("unroll") for (int n = 0; n < 2; ++n) _Pragma("unroll") for (int k = 0; k < 2; ++k) \
;         acc[ai][bj][m][n] = __builtin_amdgcn_mfma_f32_16x16x32_bf16(Bt[n][k], At[m][k], acc[ai][bj][m][n], 0, 0, 0); __builtin_amdgcn_s_setprio(0); } while (0)
; #define PG8_WAIT_V(n) asm volatile("s_waitcnt vmcnt(" #n ")" ::: "memory")
; #define PG8_WAIT_L(n) asm volatile("s_waitcnt lgkmcnt(" #n ")" ::: "memory")
; #define PG8_BAR __builtin_amdgcn_s_barrier()
; #define PG8_SCHED __builtin_amdgcn_sched_barrier(0)
; template <class Epi, class Sched, bool ALIGN_EPI = false, bool SP2 = false>
; __device__ __forceinline__ void gemm_phase(PG8_LAS unsigned char* lds, const Gemm g, const Sched& S, const Epi& E) {
;     ...
;             PG8_LDA(At, 1, 1); PG8_STAGEB(PG8_SB(1, 0), b3, voffB); PG8_STAGEB(PG8_SB(1, 1), b3 + hstep, voffB); PG8_STAGE(PG8_SA(1, 0), a3, voffA);
;             PG8_WAIT_V(8); PG8_WAIT_L(0); PG8_BAR; PG8_MMA(1, 0, At, B0); PG8_MMA(1, 1, At, B1); PG8_BAR; PG8_SCHED;
	s_mov_b32 m0, s1
	v_lshl_add_u64 v[166:167], v[166:167], 0, s[76:77]
	ds_read_b128 v[196:199], v165 offset:49152
	ds_read_b128 v[200:203], v165 offset:50176
	ds_read_b128 v[222:225], v165 offset:51200
	ds_read_b128 v[226:229], v165 offset:52224
	ds_read_b128 v[230:233], v165 offset:53248
	ds_read_b128 v[234:237], v165 offset:54272
	ds_read_b128 v[238:241], v165 offset:55296
	ds_read_b128 v[242:245], v165 offset:56320
	global_load_lds_dwordx4 v[166:167], off
	v_lshl_add_u64 v[166:167], v[168:169], 0, s[76:77]
	s_mov_b32 m0, s0
	s_nop 0
	global_load_lds_dwordx4 v[166:167], off
	v_lshl_add_u64 v[166:167], s[52:53], 0, v[150:151]
	s_mov_b32 m0, s47
	s_nop 0
	global_load_lds_dwordx4 v[166:167], off
	v_lshl_add_u64 v[166:167], s[52:53], 0, v[154:155]
	s_mov_b32 m0, s46
	s_nop 0
	global_load_lds_dwordx4 v[166:167], off
	v_lshl_add_u64 v[166:167], v[172:173], 0, s[76:77]
	s_mov_b32 m0, s70
	s_nop 0
	global_load_lds_dwordx4 v[166:167], off
	v_lshl_add_u64 v[166:167], v[212:213], 0, s[76:77]
	s_mov_b32 m0, s71
	s_nop 0
	global_load_lds_dwordx4 v[166:167], off
	s_waitcnt vmcnt(8)
	s_waitcnt lgkmcnt(0)
	s_barrier
	s_setprio 1
	s_waitcnt lgkmcnt(0)
	v_mfma_f32_16x16x32_bf16 v[78:81], v[54:57], v[196:199], v[78:81]
	v_mfma_f32_16x16x32_bf16 v[62:65], v[54:57], v[222:225], v[62:65]
	v_mfma_f32_16x16x32_bf16 v[46:49], v[54:57], v[230:233], v[46:49]
	v_mfma_f32_16x16x32_bf16 v[18:21], v[54:57], v[238:241], v[18:21]
	v_mfma_f32_16x16x32_bf16 v[10:13], v[70:73], v[238:241], v[10:13]
	v_mfma_f32_16x16x32_bf16 v[42:45], v[70:73], v[230:233], v[42:45]
	v_mfma_f32_16x16x32_bf16 v[58:61], v[70:73], v[222:225], v[58:61]
	v_mfma_f32_16x16x32_bf16 v[74:77], v[70:73], v[196:199], v[74:77]
	v_mfma_f32_16x16x32_bf16 v[78:81], v[66:69], v[200:203], v[78:81]
	v_mfma_f32_16x16x32_bf16 v[62:65], v[66:69], v[226:229], v[62:65]
	v_mfma_f32_16x16x32_bf16 v[46:49], v[66:69], v[234:237], v[46:49]
	v_mfma_f32_16x16x32_bf16 v[18:21], v[66:69], v[242:245], v[18:21]
	v_mfma_f32_16x16x32_bf16 v[10:13], v[160:163], v[242:245], v[10:13]
	v_mfma_f32_16x16x32_bf16 v[42:45], v[160:163], v[234:237], v[42:45]
	v_mfma_f32_16x16x32_bf16 v[58:61], v[160:163], v[226:229], v[58:61]
	v_mfma_f32_16x16x32_bf16 v[74:77], v[160:163], v[200:203], v[74:77]
	s_setprio 0
	s_setprio 1
	v_mfma_f32_16x16x32_bf16 v[22:25], v[180:183], v[196:199], v[22:25]
	v_mfma_f32_16x16x32_bf16 v[70:73], v[184:187], v[200:203], v[22:25]
	v_mfma_f32_16x16x32_bf16 v[22:25], v[188:191], v[196:199], v[34:37]
	v_mfma_f32_16x16x32_bf16 v[66:69], v[192:195], v[200:203], v[22:25]
	v_mfma_f32_16x16x32_bf16 v[22:25], v[180:183], v[222:225], v[38:41]
	v_mfma_f32_16x16x32_bf16 v[54:57], v[184:187], v[226:229], v[22:25]
	v_mfma_f32_16x16x32_bf16 v[22:25], v[188:191], v[222:225], v[50:53]
	v_mfma_f32_16x16x32_bf16 v[50:53], v[192:195], v[226:229], v[22:25]
	v_mfma_f32_16x16x32_bf16 v[22:25], v[180:183], v[230:233], v[30:33]
	v_mfma_f32_16x16x32_bf16 v[30:33], v[184:187], v[234:237], v[22:25]
	v_mfma_f32_16x16x32_bf16 v[22:25], v[188:191], v[230:233], v[26:29]
	v_mfma_f32_16x16x32_bf16 v[6:9], v[180:183], v[238:241], v[6:9]
	v_mfma_f32_16x16x32_bf16 v[2:5], v[188:191], v[238:241], v[2:5]
	v_mfma_f32_16x16x32_bf16 v[26:29], v[192:195], v[234:237], v[22:25]
	v_mfma_f32_16x16x32_bf16 v[6:9], v[184:187], v[242:245], v[6:9]
	v_mfma_f32_16x16x32_bf16 v[2:5], v[192:195], v[242:245], v[2:5]
	s_setprio 0
	s_barrier
	v_lshl_add_u64 v[14:15], v[14:15], 0, s[86:87]
	v_lshl_add_u64 v[16:17], v[16:17], 0, s[86:87]
	s_mov_b32 s29, s81
	s_cbranch_scc0 .LBB0_936
	s_and_b64 vcc, exec, s[12:13]
	s_cbranch_vccz .LBB0_939
	s_barrier

; #define PG8_STAGE(bufoff, gbase, voff) do { _Pragma("unroll") for (int _i = 0; _i < 2; ++_i) \
;         __builtin_amdgcn_global_load_lds((const unsigned*)((const char*)(gbase) + (voff)[_i]), (PG8_LAS unsigned*)(lds + (bufoff) + ldsw + _i * 8192), 16, 0, AUX_A); } while (0)
; #define PG8_STAGEB(bufoff, gbase, voff) do { _Pragma("unroll") for (int _i = 0; _i < 2; ++_i) \
;         __builtin_amdgcn_global_load_lds((const unsigned*)((const char*)(gbase) + (voff)[_i]), (PG8_LAS unsigned*)(lds + (bufoff) + ldsw + _i * 8192), 16, 0, AUX_B); } while (0)
; #define PG8_LDA(dst, b, h) do { _Pragma("unroll") for (int m = 0; m < 4; ++m) _Pragma("unroll") for (int k = 0; k < 2; ++k) dst[m][k] = *(const PG8_LAS bf16x8*)(lds + PG8_SA(b, h) + aoff + m * 2048 + k * 1024); } while (0)
; #define PG8_LDB(dst, b, h) do { _Pragma("unroll") for (int n = 0; n < 2; ++n) _Pragma("unroll") for (int k = 0; k < 2; ++k) dst[n][k] = *(const PG8_LAS bf16x8*)(lds + PG8_SB(b, h) + boff + n * 2048 + k * 1024); } while (0)
; #define PG8_WAIT_V(n) asm volatile("s_waitcnt vmcnt(" #n ")" ::: "memory")
; #define PG8_WAIT_L(n) asm volatile("s_waitcnt lgkmcnt(" #n ")" ::: "memory")
; #define PG8_BAR __builtin_amdgcn_s_barrier()
; #define PG8_SCHED __builtin_amdgcn_sched_barrier(0)
; template <class Epi, class Sched, bool ALIGN_EPI = false, bool SP2 = false>
; __device__ __forceinline__ void gemm_phase(PG8_LAS unsigned char* lds, const Gemm g, const Sched& S, const Epi& E) {
;     ...
;         for (int t = 0; t < nt; t += 2) {
;             const bool last = (t == nt - 2);
;             const char* a1 = PG8_KP(cA, t + 1, rot, nt);
;             const char* a2 = last ? nAr : PG8_KP(cA, t + 2, rot, nt); const char* b2 = last ? nBr : PG8_KP(cB, t + 2, rot, nt);
;             const char* a3 = a2 + kstep; const char* b3 = b2 + kstep;
;             if (last && has_next) S.a_ready(nxt);
;             if constexpr (SP2) {
;             PG8_LDB(B0, 0, 0); PG8_LDB(B1, 0, 1); PG8_SCHED; PG8_LDA(At, 0, 0); PG8_STAGE(PG8_SA(1, 1), a1 + hstep, voffA);
;             PG8_WAIT_V(8); PG8_WAIT_L(0); PG8_BAR; PG8_MMA(0, 0, At, B0); PG8_MMA(0, 1, At, B1); PG8_BAR; PG8_SCHED;
;             PG8_LDA(At, 0, 1); PG8_STAGEB(PG8_SB(0, 0), b2, voffB); PG8_STAGEB(PG8_SB(0, 1), b2 + hstep, voffB); PG8_STAGE(PG8_SA(0, 0), a2, voffA);
.LBB0_1067:
	s_add_i32 s81, s29, 2
	s_cmp_lt_u32 s29, 14
	s_cselect_b32 s0, 0, -16
	s_add_i32 s0, s81, s0
	s_ashr_i32 s1, s0, 31
	s_lshl_b64 s[0:1], s[0:1], 7
	s_add_u32 s2, s52, s0
	s_addc_u32 s46, s53, s1
	s_add_u32 s0, s42, s0
	s_addc_u32 s1, s43, s1
	s_cmp_eq_u32 s29, 14
	s_cselect_b32 s59, s15, s46
	s_cselect_b32 s58, s17, s2
	s_cselect_b32 s61, s92, s1
	s_cselect_b32 s60, s93, s0
	s_add_i32 s2, 0, 0x10000
	s_add_i32 s94, s2, s70
	s_add_i32 s46, 0, 0x14000
	s_add_i32 m0, s71, 0xc000
	s_add_i32 s84, s71, 0xe000
	s_add_i32 s95, s94, 0x2000
	s_add_u32 s62, s60, 0x40000
	v_add_u32_e32 v148, s2, v99
	s_addc_u32 s63, s61, 0
	s_add_i32 s96, s46, s70
	ds_read_b128 v[152:155], v148
	ds_read_b128 v[156:159], v148 offset:1024
	ds_read_b128 v[160:163], v148 offset:2048
	ds_read_b128 v[164:167], v148 offset:3072
	v_add_u32_e32 v148, s46, v99
	s_add_i32 s97, s96, 0x2000
	s_add_i32 vcc_lo, 0, 0x18000
	s_add_i32 vcc_hi, 0, 0x1c000
	ds_read_b128 v[180:183], v148
	ds_read_b128 v[184:187], v148 offset:1024
	ds_read_b128 v[188:191], v148 offset:2048
	ds_read_b128 v[192:195], v148 offset:3072
	s_add_u32 s56, s58, 0x40000
	s_addc_u32 s57, s59, 0
	s_add_i32 s1, vcc_lo, s70
	s_add_i32 s0, s1, 0x2000
	s_add_u32 s54, s60, 0x40080
	s_addc_u32 s55, s61, 0
	s_add_i32 s47, vcc_hi, s70
	s_add_i32 s46, s47, 0x2000
	s_cmp_gt_u32 s29, 13
	ds_read_b128 v[196:199], v151
	ds_read_b128 v[200:203], v151 offset:1024
	ds_read_b128 v[222:225], v151 offset:2048
	ds_read_b128 v[226:229], v151 offset:3072
	ds_read_b128 v[230:233], v151 offset:4096
	ds_read_b128 v[234:237], v151 offset:5120
	ds_read_b128 v[238:241], v151 offset:6144
	ds_read_b128 v[242:245], v151 offset:7168
	global_load_lds_dwordx4 v[146:147], off
	s_mov_b32 m0, s84
	s_nop 0
	global_load_lds_dwordx4 v[144:145], off
	s_waitcnt vmcnt(8)
	s_waitcnt lgkmcnt(0)
	s_barrier
	s_setprio 1
	s_waitcnt lgkmcnt(0)
	v_mfma_f32_16x16x32_bf16 v[128:131], v[152:155], v[196:199], v[128:131]
	v_mfma_f32_16x16x32_bf16 v[112:115], v[152:155], v[222:225], v[112:115]
	v_mfma_f32_16x16x32_bf16 v[94:97], v[152:155], v[230:233], v[94:97]
	v_mfma_f32_16x16x32_bf16 v[78:81], v[152:155], v[238:241], v[78:81]
	v_mfma_f32_16x16x32_bf16 v[74:77], v[160:163], v[238:241], v[74:77]
	v_mfma_f32_16x16x32_bf16 v[90:93], v[160:163], v[230:233], v[90:93]
	v_mfma_f32_16x16x32_bf16 v[108:111], v[160:163], v[222:225], v[108:111]
	v_mfma_f32_16x16x32_bf16 v[124:127], v[160:163], v[196:199], v[124:127]
	v_mfma_f32_16x16x32_bf16 v[128:131], v[156:159], v[200:203], v[128:131]
	v_mfma_f32_16x16x32_bf16 v[112:115], v[156:159], v[226:229], v[112:115]
	v_mfma_f32_16x16x32_bf16 v[94:97], v[156:159], v[234:237], v[94:97]
	v_mfma_f32_16x16x32_bf16 v[78:81], v[156:159], v[242:245], v[78:81]
	v_mfma_f32_16x16x32_bf16 v[74:77], v[164:167], v[242:245], v[74:77]
	v_mfma_f32_16x16x32_bf16 v[90:93], v[164:167], v[234:237], v[90:93]
	v_mfma_f32_16x16x32_bf16 v[108:111], v[164:167], v[226:229], v[108:111]
	v_mfma_f32_16x16x32_bf16 v[124:127], v[164:167], v[200:203], v[124:127]
	s_setprio 0
	s_setprio 1
	v_mfma_f32_16x16x32_bf16 v[120:123], v[180:183], v[196:199], v[120:123]
	v_mfma_f32_16x16x32_bf16 v[104:107], v[180:183], v[222:225], v[104:107]
	v_mfma_f32_16x16x32_bf16 v[86:89], v[180:183], v[230:233], v[86:89]
	v_mfma_f32_16x16x32_bf16 v[70:73], v[180:183], v[238:241], v[70:73]
	v_mfma_f32_16x16x32_bf16 v[66:69], v[188:191], v[238:241], v[66:69]
	v_mfma_f32_16x16x32_bf16 v[82:85], v[188:191], v[230:233], v[82:85]
	v_mfma_f32_16x16x32_bf16 v[100:103], v[188:191], v[222:225], v[100:103]
	v_mfma_f32_16x16x32_bf16 v[116:119], v[188:191], v[196:199], v[116:119]
	v_mfma_f32_16x16x32_bf16 v[120:123], v[184:187], v[200:203], v[120:123]
	v_mfma_f32_16x16x32_bf16 v[104:107], v[184:187], v[226:229], v[104:107]
	v_mfma_f32_16x16x32_bf16 v[86:89], v[184:187], v[234:237], v[86:89]
	v_mfma_f32_16x16x32_bf16 v[70:73], v[184:187], v[242:245], v[70:73]
	v_mfma_f32_16x16x32_bf16 v[66:69], v[192:195], v[242:245], v[66:69]
	v_mfma_f32_16x16x32_bf16 v[82:85], v[192:195], v[234:237], v[82:85]
	v_mfma_f32_16x16x32_bf16 v[100:103], v[192:195], v[226:229], v[100:103]
	v_mfma_f32_16x16x32_bf16 v[116:119], v[192:195], v[200:203], v[116:119]
	s_setprio 0
	s_barrier
	s_mov_b32 m0, s94
	v_lshl_add_u64 v[148:149], s[60:61], 0, v[136:137]
	ds_read_b128 v[196:199], v151 offset:16384
	ds_read_b128 v[200:203], v151 offset:17408
	ds_read_b128 v[222:225], v151 offset:18432
	ds_read_b128 v[226:229], v151 offset:19456
	ds_read_b128 v[230:233], v151 offset:20480
	ds_read_b128 v[234:237], v151 offset:21504
	ds_read_b128 v[238:241], v151 offset:22528
	ds_read_b128 v[242:245], v151 offset:23552
	global_load_lds_dwordx4 v[148:149], off
	v_lshl_add_u64 v[168:169], s[60:61], 0, v[132:133]
	s_mov_b32 m0, s95
	v_lshl_add_u64 v[172:173], s[62:63], 0, v[136:137]
	global_load_lds_dwordx4 v[168:169], off
	s_mov_b32 m0, s96
	v_lshl_add_u64 v[212:213], s[58:59], 0, v[134:135]
	global_load_lds_dwordx4 v[172:173], off
	v_lshl_add_u64 v[172:173], s[62:63], 0, v[132:133]
	s_mov_b32 m0, s97
	s_nop 0
	global_load_lds_dwordx4 v[172:173], off
	v_lshl_add_u64 v[172:173], s[58:59], 0, v[138:139]
	s_mov_b32 m0, s71
	s_nop 0
	global_load_lds_dwordx4 v[172:173], off
	s_mov_b32 m0, s75
	s_nop 0
	global_load_lds_dwordx4 v[212:213], off
	s_waitcnt vmcnt(8)
	s_waitcnt lgkmcnt(0)
	s_barrier
; #define PG8_STAGE(bufoff, gbase, voff) do { _Pragma("unroll") for (int _i = 0; _i < 2; ++_i) \
;         __builtin_amdgcn_global_load_lds((const unsigned*)((const char*)(gbase) + (voff)[_i]), (PG8_LAS unsigned*)(lds + (bufoff) + ldsw + _i * 8192), 16, 0, AUX_A); } while (0)
; #define PG8_LDA(dst, b, h) do { _Pragma("unroll") for (int m = 0; m < 4; ++m) _Pragma("unroll") for (int k = 0; k < 2; ++k) dst[m][k] = *(const PG8_LAS bf16x8*)(lds + PG8_SA(b, h) + aoff + m * 2048 + k * 1024); } while (0)
; #define PG8_LDB(dst, b, h) do { _Pragma("unroll") for (int n = 0; n < 2; ++n) _Pragma("unroll") for (int k = 0; k < 2; ++k) dst[n][k] = *(const PG8_LAS bf16x8*)(lds + PG8_SB(b, h) + boff + n * 2048 + k * 1024); } while (0)
; #define PG8_MMA(ai, bj, At, Bt) do { __builtin_amdgcn_s_setprio(1); _Pragma("unroll") for (int m = 0; m < 4; ++m) _Pragma("unroll") for (int n = 0; n < 2; ++n) _Pragma("unroll") for (int k = 0; k < 2; ++k) \
;         acc[ai][bj][m][n] = __builtin_amdgcn_mfma_f32_16x16x32_bf16(Bt[n][k], At[m][k], acc[ai][bj][m][n], 0, 0, 0); __builtin_amdgcn_s_setprio(0); } while (0)
; #define PG8_WAIT_V(n) asm volatile("s_waitcnt vmcnt(" #n ")" ::: "memory")
; #define PG8_WAIT_L(n) asm volatile("s_waitcnt lgkmcnt(" #n ")" ::: "memory")
; #define PG8_BAR __builtin_amdgcn_s_barrier()
; #define PG8_SCHED __builtin_amdgcn_sched_barrier(0)
; template <class Epi, class Sched, bool ALIGN_EPI = false, bool SP2 = false>
; __device__ __forceinline__ void gemm_phase(PG8_LAS unsigned char* lds, const Gemm g, const Sched& S, const Epi& E) {
;     ...
;             PG8_WAIT_V(8); PG8_WAIT_L(0); PG8_BAR; PG8_MMA(1, 0, At, B0); PG8_MMA(1, 1, At, B1); PG8_BAR; PG8_SCHED;
;             PG8_LDB(B0, 1, 0); PG8_LDB(B1, 1, 1); PG8_SCHED; PG8_LDA(At, 1, 0); PG8_STAGE(PG8_SA(0, 1), a2 + hstep, voffA);
;             PG8_WAIT_V(8); PG8_WAIT_L(0); PG8_BAR; PG8_MMA(0, 0, At, B0); PG8_MMA(0, 1, At, B1); PG8_BAR; PG8_SCHED;
	s_setprio 1
	s_waitcnt lgkmcnt(0)
	v_mfma_f32_16x16x32_bf16 v[62:65], v[152:155], v[196:199], v[62:65]
	v_mfma_f32_16x16x32_bf16 v[46:49], v[152:155], v[222:225], v[46:49]
	v_mfma_f32_16x16x32_bf16 v[30:33], v[152:155], v[230:233], v[30:33]
	v_mfma_f32_16x16x32_bf16 v[14:17], v[152:155], v[238:241], v[14:17]
	v_mfma_f32_16x16x32_bf16 v[10:13], v[160:163], v[238:241], v[10:13]
	v_mfma_f32_16x16x32_bf16 v[26:29], v[160:163], v[230:233], v[26:29]
	v_mfma_f32_16x16x32_bf16 v[42:45], v[160:163], v[222:225], v[42:45]
	v_mfma_f32_16x16x32_bf16 v[58:61], v[160:163], v[196:199], v[58:61]
	v_mfma_f32_16x16x32_bf16 v[62:65], v[156:159], v[200:203], v[62:65]
	v_mfma_f32_16x16x32_bf16 v[46:49], v[156:159], v[226:229], v[46:49]
	v_mfma_f32_16x16x32_bf16 v[30:33], v[156:159], v[234:237], v[30:33]
	v_mfma_f32_16x16x32_bf16 v[14:17], v[156:159], v[242:245], v[14:17]
	v_mfma_f32_16x16x32_bf16 v[10:13], v[164:167], v[242:245], v[10:13]
	v_mfma_f32_16x16x32_bf16 v[26:29], v[164:167], v[234:237], v[26:29]
	v_mfma_f32_16x16x32_bf16 v[42:45], v[164:167], v[226:229], v[42:45]
	v_mfma_f32_16x16x32_bf16 v[58:61], v[164:167], v[200:203], v[58:61]
	s_setprio 0
	s_setprio 1
	v_mfma_f32_16x16x32_bf16 v[54:57], v[180:183], v[196:199], v[54:57]
	v_mfma_f32_16x16x32_bf16 v[38:41], v[180:183], v[222:225], v[38:41]
	v_mfma_f32_16x16x32_bf16 v[22:25], v[180:183], v[230:233], v[22:25]
	v_mfma_f32_16x16x32_bf16 v[6:9], v[180:183], v[238:241], v[6:9]
	v_mfma_f32_16x16x32_bf16 v[2:5], v[188:191], v[238:241], v[2:5]
	v_mfma_f32_16x16x32_bf16 v[18:21], v[188:191], v[230:233], v[18:21]
	v_mfma_f32_16x16x32_bf16 v[34:37], v[188:191], v[222:225], v[34:37]
	v_mfma_f32_16x16x32_bf16 v[50:53], v[188:191], v[196:199], v[50:53]
	v_mfma_f32_16x16x32_bf16 v[54:57], v[184:187], v[200:203], v[54:57]
	v_mfma_f32_16x16x32_bf16 v[38:41], v[184:187], v[226:229], v[38:41]
	v_mfma_f32_16x16x32_bf16 v[22:25], v[184:187], v[234:237], v[22:25]
	v_mfma_f32_16x16x32_bf16 v[6:9], v[184:187], v[242:245], v[6:9]
	v_mfma_f32_16x16x32_bf16 v[2:5], v[192:195], v[242:245], v[2:5]
	v_mfma_f32_16x16x32_bf16 v[18:21], v[192:195], v[234:237], v[18:21]
	v_mfma_f32_16x16x32_bf16 v[34:37], v[192:195], v[226:229], v[34:37]
	v_mfma_f32_16x16x32_bf16 v[50:53], v[192:195], v[200:203], v[50:53]
	s_setprio 0
	s_barrier
	v_add_u32_e32 v164, vcc_lo, v99
	v_add_u32_e32 v192, vcc_hi, v99
	ds_read_b128 v[152:155], v164
	ds_read_b128 v[156:159], v164 offset:1024
	ds_read_b128 v[160:163], v164 offset:2048
	ds_read_b128 v[164:167], v164 offset:3072
	ds_read_b128 v[180:183], v192
	ds_read_b128 v[184:187], v192 offset:1024
	ds_read_b128 v[188:191], v192 offset:2048
	ds_read_b128 v[192:195], v192 offset:3072
	s_mov_b32 m0, s78
	v_lshl_add_u64 v[246:247], s[56:57], 0, v[138:139]
	ds_read_b128 v[196:199], v151 offset:32768
	ds_read_b128 v[200:203], v151 offset:33792
	ds_read_b128 v[222:225], v151 offset:34816
	ds_read_b128 v[226:229], v151 offset:35840
	ds_read_b128 v[230:233], v151 offset:36864
	ds_read_b128 v[234:237], v151 offset:37888
	ds_read_b128 v[238:241], v151 offset:38912
	ds_read_b128 v[242:245], v151 offset:39936
	global_load_lds_dwordx4 v[246:247], off
	v_lshl_add_u64 v[246:247], s[56:57], 0, v[134:135]
	s_mov_b32 m0, s82
	s_nop 0
	global_load_lds_dwordx4 v[246:247], off
	s_waitcnt vmcnt(8)
	s_waitcnt lgkmcnt(0)
	s_barrier
	s_setprio 1
	s_waitcnt lgkmcnt(0)
	v_mfma_f32_16x16x32_bf16 v[128:131], v[152:155], v[196:199], v[128:131]
	v_mfma_f32_16x16x32_bf16 v[112:115], v[152:155], v[222:225], v[112:115]
	v_mfma_f32_16x16x32_bf16 v[94:97], v[152:155], v[230:233], v[94:97]
	v_mfma_f32_16x16x32_bf16 v[78:81], v[152:155], v[238:241], v[78:81]
	v_mfma_f32_16x16x32_bf16 v[74:77], v[160:163], v[238:241], v[74:77]
	v_mfma_f32_16x16x32_bf16 v[90:93], v[160:163], v[230:233], v[90:93]
	v_mfma_f32_16x16x32_bf16 v[108:111], v[160:163], v[222:225], v[108:111]
	v_mfma_f32_16x16x32_bf16 v[124:127], v[160:163], v[196:199], v[124:127]
	v_mfma_f32_16x16x32_bf16 v[128:131], v[156:159], v[200:203], v[128:131]
	v_mfma_f32_16x16x32_bf16 v[112:115], v[156:159], v[226:229], v[112:115]
	v_mfma_f32_16x16x32_bf16 v[94:97], v[156:159], v[234:237], v[94:97]
	v_mfma_f32_16x16x32_bf16 v[78:81], v[156:159], v[242:245], v[78:81]
	v_mfma_f32_16x16x32_bf16 v[74:77], v[164:167], v[242:245], v[74:77]
	v_mfma_f32_16x16x32_bf16 v[90:93], v[164:167], v[234:237], v[90:93]
	v_mfma_f32_16x16x32_bf16 v[108:111], v[164:167], v[226:229], v[108:111]
	v_mfma_f32_16x16x32_bf16 v[124:127], v[164:167], v[200:203], v[124:127]
	s_setprio 0
	s_setprio 1
	v_mfma_f32_16x16x32_bf16 v[120:123], v[180:183], v[196:199], v[120:123]
	v_mfma_f32_16x16x32_bf16 v[104:107], v[180:183], v[222:225], v[104:107]
	v_mfma_f32_16x16x32_bf16 v[86:89], v[180:183], v[230:233], v[86:89]
	v_mfma_f32_16x16x32_bf16 v[70:73], v[180:183], v[238:241], v[70:73]
	v_mfma_f32_16x16x32_bf16 v[66:69], v[188:191], v[238:241], v[66:69]
	v_mfma_f32_16x16x32_bf16 v[82:85], v[188:191], v[230:233], v[82:85]
	v_mfma_f32_16x16x32_bf16 v[100:103], v[188:191], v[222:225], v[100:103]
	v_mfma_f32_16x16x32_bf16 v[116:119], v[188:191], v[196:199], v[116:119]
	v_mfma_f32_16x16x32_bf16 v[120:123], v[184:187], v[200:203], v[120:123]
	v_mfma_f32_16x16x32_bf16 v[104:107], v[184:187], v[226:229], v[104:107]
	v_mfma_f32_16x16x32_bf16 v[86:89], v[184:187], v[234:237], v[86:89]
	v_mfma_f32_16x16x32_bf16 v[70:73], v[184:187], v[242:245], v[70:73]
	v_mfma_f32_16x16x32_bf16 v[66:69], v[192:195], v[242:245], v[66:69]
	v_mfma_f32_16x16x32_bf16 v[82:85], v[192:195], v[234:237], v[82:85]
	v_mfma_f32_16x16x32_bf16 v[100:103], v[192:195], v[226:229], v[100:103]
	v_mfma_f32_16x16x32_bf16 v[116:119], v[192:195], v[200:203], v[116:119]
	s_setprio 0
	s_barrier
; #define PG8_STAGE(bufoff, gbase, voff) do { _Pragma("unroll") for (int _i = 0; _i < 2; ++_i) \
;         __builtin_amdgcn_global_load_lds((const unsigned*)((const char*)(gbase) + (voff)[_i]), (PG8_LAS unsigned*)(lds + (bufoff) + ldsw + _i * 8192), 16, 0, AUX_A); } while (0)
; #define PG8_STAGEB(bufoff, gbase, voff) do { _Pragma("unroll") for (int _i = 0; _i < 2; ++_i) \
;         __builtin_amdgcn_global_load_lds((const unsigned*)((const char*)(gbase) + (voff)[_i]), (PG8_LAS unsigned*)(lds + (bufoff) + ldsw + _i * 8192), 16, 0, AUX_B); } while (0)
; #define PG8_LDA(dst, b, h) do { _Pragma("unroll") for (int m = 0; m < 4; ++m) _Pragma("unroll") for (int k = 0; k < 2; ++k) dst[m][k] = *(const PG8_LAS bf16x8*)(lds + PG8_SA(b, h) + aoff + m * 2048 + k * 1024); } while (0)
; #define PG8_MMA(ai, bj, At, Bt) do { __builtin_amdgcn_s_setprio(1); _Pragma("unroll") for (int m = 0; m < 4; ++m) _Pragma("unroll") for (int n = 0; n < 2; ++n) _Pragma("unroll") for (int k = 0; k < 2; ++k) \
;         acc[ai][bj][m][n] = __builtin_amdgcn_mfma_f32_16x16x32_bf16(Bt[n][k], At[m][k], acc[ai][bj][m][n], 0, 0, 0); __builtin_amdgcn_s_setprio(0); } while (0)
; #define PG8_WAIT_V(n) asm volatile("s_waitcnt vmcnt(" #n ")" ::: "memory")
; #define PG8_WAIT_L(n) asm volatile("s_waitcnt lgkmcnt(" #n ")" ::: "memory")
; #define PG8_BAR __builtin_amdgcn_s_barrier()
; #define PG8_SCHED __builtin_amdgcn_sched_barrier(0)
; template <class Epi, class Sched, bool ALIGN_EPI = false, bool SP2 = false>
; __device__ __forceinline__ void gemm_phase(PG8_LAS unsigned char* lds, const Gemm g, const Sched& S, const Epi& E) {
;     ...
;             PG8_LDA(At, 1, 1); PG8_STAGEB(PG8_SB(1, 0), b3, voffB); PG8_STAGEB(PG8_SB(1, 1), b3 + hstep, voffB); PG8_STAGE(PG8_SA(1, 0), a3, voffA);
;             PG8_WAIT_V(8); PG8_WAIT_L(0); PG8_BAR; PG8_MMA(1, 0, At, B0); PG8_MMA(1, 1, At, B1); PG8_BAR; PG8_SCHED;
	s_mov_b32 m0, s1
	v_lshl_add_u64 v[148:149], v[148:149], 0, s[76:77]
	ds_read_b128 v[196:199], v151 offset:49152
	ds_read_b128 v[200:203], v151 offset:50176
	ds_read_b128 v[222:225], v151 offset:51200
	ds_read_b128 v[226:229], v151 offset:52224
	ds_read_b128 v[230:233], v151 offset:53248
	ds_read_b128 v[234:237], v151 offset:54272
	ds_read_b128 v[238:241], v151 offset:55296
	ds_read_b128 v[242:245], v151 offset:56320
	global_load_lds_dwordx4 v[148:149], off
	v_lshl_add_u64 v[148:149], v[168:169], 0, s[76:77]
	s_mov_b32 m0, s0
	s_nop 0
	global_load_lds_dwordx4 v[148:149], off
	v_lshl_add_u64 v[148:149], s[54:55], 0, v[136:137]
	s_mov_b32 m0, s47
	s_nop 0
	global_load_lds_dwordx4 v[148:149], off
	v_lshl_add_u64 v[148:149], s[54:55], 0, v[132:133]
	s_mov_b32 m0, s46
	s_nop 0
	global_load_lds_dwordx4 v[148:149], off
	v_lshl_add_u64 v[148:149], v[172:173], 0, s[76:77]
	s_mov_b32 m0, s83
	s_nop 0
	global_load_lds_dwordx4 v[148:149], off
	v_lshl_add_u64 v[148:149], v[212:213], 0, s[76:77]
	s_mov_b32 m0, s88
	s_nop 0
	global_load_lds_dwordx4 v[148:149], off
	s_waitcnt vmcnt(8)
	s_waitcnt lgkmcnt(0)
	s_barrier
	s_setprio 1
	s_waitcnt lgkmcnt(0)
	v_mfma_f32_16x16x32_bf16 v[62:65], v[152:155], v[196:199], v[62:65]
	v_mfma_f32_16x16x32_bf16 v[46:49], v[152:155], v[222:225], v[46:49]
	v_mfma_f32_16x16x32_bf16 v[30:33], v[152:155], v[230:233], v[30:33]
	v_mfma_f32_16x16x32_bf16 v[14:17], v[152:155], v[238:241], v[14:17]
	v_mfma_f32_16x16x32_bf16 v[10:13], v[160:163], v[238:241], v[10:13]
	v_mfma_f32_16x16x32_bf16 v[26:29], v[160:163], v[230:233], v[26:29]
	v_mfma_f32_16x16x32_bf16 v[42:45], v[160:163], v[222:225], v[42:45]
	v_mfma_f32_16x16x32_bf16 v[58:61], v[160:163], v[196:199], v[58:61]
	v_mfma_f32_16x16x32_bf16 v[62:65], v[156:159], v[200:203], v[62:65]
	v_mfma_f32_16x16x32_bf16 v[46:49], v[156:159], v[226:229], v[46:49]
	v_mfma_f32_16x16x32_bf16 v[30:33], v[156:159], v[234:237], v[30:33]
	v_mfma_f32_16x16x32_bf16 v[14:17], v[156:159], v[242:245], v[14:17]
	v_mfma_f32_16x16x32_bf16 v[10:13], v[164:167], v[242:245], v[10:13]
	v_mfma_f32_16x16x32_bf16 v[26:29], v[164:167], v[234:237], v[26:29]
	v_mfma_f32_16x16x32_bf16 v[42:45], v[164:167], v[226:229], v[42:45]
	v_mfma_f32_16x16x32_bf16 v[58:61], v[164:167], v[200:203], v[58:61]
	s_setprio 0
	s_setprio 1
	v_mfma_f32_16x16x32_bf16 v[54:57], v[180:183], v[196:199], v[54:57]
	v_mfma_f32_16x16x32_bf16 v[38:41], v[180:183], v[222:225], v[38:41]
	v_mfma_f32_16x16x32_bf16 v[22:25], v[180:183], v[230:233], v[22:25]
	v_mfma_f32_16x16x32_bf16 v[6:9], v[180:183], v[238:241], v[6:9]
	v_mfma_f32_16x16x32_bf16 v[2:5], v[188:191], v[238:241], v[2:5]
	v_mfma_f32_16x16x32_bf16 v[18:21], v[188:191], v[230:233], v[18:21]
	v_mfma_f32_16x16x32_bf16 v[34:37], v[188:191], v[222:225], v[34:37]
	v_mfma_f32_16x16x32_bf16 v[50:53], v[188:191], v[196:199], v[50:53]
	v_mfma_f32_16x16x32_bf16 v[54:57], v[184:187], v[200:203], v[54:57]
	v_mfma_f32_16x16x32_bf16 v[38:41], v[184:187], v[226:229], v[38:41]
	v_mfma_f32_16x16x32_bf16 v[22:25], v[184:187], v[234:237], v[22:25]
	v_mfma_f32_16x16x32_bf16 v[6:9], v[184:187], v[242:245], v[6:9]
	v_mfma_f32_16x16x32_bf16 v[2:5], v[192:195], v[242:245], v[2:5]
	v_mfma_f32_16x16x32_bf16 v[18:21], v[192:195], v[234:237], v[18:21]
	v_mfma_f32_16x16x32_bf16 v[34:37], v[192:195], v[226:229], v[34:37]
	v_mfma_f32_16x16x32_bf16 v[50:53], v[192:195], v[200:203], v[50:53]
	s_setprio 0
	s_barrier
	v_lshl_add_u64 v[144:145], v[144:145], 0, s[86:87]
	v_lshl_add_u64 v[146:147], v[146:147], 0, s[86:87]
	s_mov_b32 s29, s81
	s_cbranch_scc0 .LBB0_1067
	s_and_b64 vcc, exec, s[12:13]
	s_cbranch_vccz .LBB0_1070
	s_barrier

; #define PG8_STAGE(bufoff, gbase, voff) do { _Pragma("unroll") for (int _i = 0; _i < 2; ++_i) \
;         __builtin_amdgcn_global_load_lds((const unsigned*)((const char*)(gbase) + (voff)[_i]), (PG8_LAS unsigned*)(lds + (bufoff) + ldsw + _i * 8192), 16, 0, AUX_A); } while (0)
; #define PG8_STAGEB(bufoff, gbase, voff) do { _Pragma("unroll") for (int _i = 0; _i < 2; ++_i) \
;         __builtin_amdgcn_global_load_lds((const unsigned*)((const char*)(gbase) + (voff)[_i]), (PG8_LAS unsigned*)(lds + (bufoff) + ldsw + _i * 8192), 16, 0, AUX_B); } while (0)
; #define PG8_LDA(dst, b, h) do { _Pragma("unroll") for (int m = 0; m < 4; ++m) _Pragma("unroll") for (int k = 0; k < 2; ++k) dst[m][k] = *(const PG8_LAS bf16x8*)(lds + PG8_SA(b, h) + aoff + m * 2048 + k * 1024); } while (0)
; #define PG8_LDB(dst, b, h) do { _Pragma("unroll") for (int n = 0; n < 2; ++n) _Pragma("unroll") for (int k = 0; k < 2; ++k) dst[n][k] = *(const PG8_LAS bf16x8*)(lds + PG8_SB(b, h) + boff + n * 2048 + k * 1024); } while (0)
; #define PG8_WAIT_V(n) asm volatile("s_waitcnt vmcnt(" #n ")" ::: "memory")
; #define PG8_WAIT_L(n) asm volatile("s_waitcnt lgkmcnt(" #n ")" ::: "memory")
; #define PG8_BAR __builtin_amdgcn_s_barrier()
; #define PG8_SCHED __builtin_amdgcn_sched_barrier(0)
; template <class Epi, class Sched, bool ALIGN_EPI = false, bool SP2 = false>
; __device__ __forceinline__ void gemm_phase(PG8_LAS unsigned char* lds, const Gemm g, const Sched& S, const Epi& E) {
;     ...
;         for (int t = 0; t < nt; t += 2) {
;             const bool last = (t == nt - 2);
;             const char* a1 = PG8_KP(cA, t + 1, rot, nt);
;             const char* a2 = last ? nAr : PG8_KP(cA, t + 2, rot, nt); const char* b2 = last ? nBr : PG8_KP(cB, t + 2, rot, nt);
;             const char* a3 = a2 + kstep; const char* b3 = b2 + kstep;
;             if (last && has_next) S.a_ready(nxt);
;             if constexpr (SP2) {
;             PG8_LDB(B0, 0, 0); PG8_LDB(B1, 0, 1); PG8_SCHED; PG8_LDA(At, 0, 0); PG8_STAGE(PG8_SA(1, 1), a1 + hstep, voffA);
;             PG8_WAIT_V(8); PG8_WAIT_L(0); PG8_BAR; PG8_MMA(0, 0, At, B0); PG8_MMA(0, 1, At, B1); PG8_BAR; PG8_SCHED;
;             PG8_LDA(At, 0, 1); PG8_STAGEB(PG8_SB(0, 0), b2, voffB); PG8_STAGEB(PG8_SB(0, 1), b2 + hstep, voffB); PG8_STAGE(PG8_SA(0, 0), a2, voffA);
.LBB0_1157:
	s_add_i32 s81, s29, 2
	s_cmp_lt_u32 s29, 14
	s_cselect_b32 s0, 0, -16
	s_add_i32 s0, s81, s0
	s_ashr_i32 s1, s0, 31
	s_lshl_b64 s[0:1], s[0:1], 7
	s_add_u32 s2, s52, s0
	s_addc_u32 s46, s53, s1
	s_add_u32 s0, s50, s0
	s_addc_u32 s1, s51, s1
	s_cmp_eq_u32 s29, 14
	s_cselect_b32 s59, s19, s46
	s_cselect_b32 s58, s39, s2
	s_cselect_b32 s61, s92, s1
	s_cselect_b32 s60, s93, s0
	s_add_i32 s2, 0, 0x10000
	s_add_i32 s94, s2, s70
	s_add_i32 s46, 0, 0x14000
	s_add_i32 m0, s71, 0xc000
	s_add_i32 s84, s71, 0xe000
	s_add_i32 s95, s94, 0x2000
	s_add_u32 s62, s60, 0x40000
	s_addc_u32 s63, s61, 0
	s_add_i32 s96, s46, s70
	v_add_u32_e32 v162, s2, v99
	v_add_u32_e32 v166, s46, v99
	s_add_i32 s97, s96, 0x2000
	s_add_i32 vcc_lo, 0, 0x18000
	s_add_i32 vcc_hi, 0, 0x1c000
	ds_read_b128 v[148:151], v162
	ds_read_b128 v[154:157], v162 offset:1024
	ds_read_b128 v[158:161], v162 offset:2048
	ds_read_b128 v[162:165], v162 offset:3072
	ds_read_b128 v[180:183], v166
	ds_read_b128 v[184:187], v166 offset:1024
	ds_read_b128 v[188:191], v166 offset:2048
	ds_read_b128 v[192:195], v166 offset:3072
	s_add_u32 s56, s58, 0x40000
	s_addc_u32 s57, s59, 0
	s_add_i32 s1, vcc_lo, s70
	s_add_i32 s0, s1, 0x2000
	s_add_u32 s54, s60, 0x40080
	s_addc_u32 s55, s61, 0
	s_add_i32 s47, vcc_hi, s70
	s_add_i32 s46, s47, 0x2000
	s_cmp_gt_u32 s29, 13
	ds_read_b128 v[196:199], v153
	ds_read_b128 v[200:203], v153 offset:1024
	ds_read_b128 v[222:225], v153 offset:2048
	ds_read_b128 v[226:229], v153 offset:3072
	ds_read_b128 v[230:233], v153 offset:4096
	ds_read_b128 v[234:237], v153 offset:5120
	ds_read_b128 v[238:241], v153 offset:6144
	ds_read_b128 v[242:245], v153 offset:7168
	global_load_lds_dwordx4 v[146:147], off
	s_mov_b32 m0, s84
	s_nop 0
	global_load_lds_dwordx4 v[144:145], off
	s_waitcnt vmcnt(8)
	s_waitcnt lgkmcnt(0)
	s_barrier
	s_setprio 1
	s_waitcnt lgkmcnt(0)
	v_mfma_f32_16x16x32_bf16 v[128:131], v[148:151], v[196:199], v[128:131]
	v_mfma_f32_16x16x32_bf16 v[112:115], v[148:151], v[222:225], v[112:115]
	v_mfma_f32_16x16x32_bf16 v[94:97], v[148:151], v[230:233], v[94:97]
	v_mfma_f32_16x16x32_bf16 v[78:81], v[148:151], v[238:241], v[78:81]
	v_mfma_f32_16x16x32_bf16 v[74:77], v[158:161], v[238:241], v[74:77]
	v_mfma_f32_16x16x32_bf16 v[90:93], v[158:161], v[230:233], v[90:93]
	v_mfma_f32_16x16x32_bf16 v[108:111], v[158:161], v[222:225], v[108:111]
	v_mfma_f32_16x16x32_bf16 v[124:127], v[158:161], v[196:199], v[124:127]
	v_mfma_f32_16x16x32_bf16 v[128:131], v[154:157], v[200:203], v[128:131]
	v_mfma_f32_16x16x32_bf16 v[112:115], v[154:157], v[226:229], v[112:115]
	v_mfma_f32_16x16x32_bf16 v[94:97], v[154:157], v[234:237], v[94:97]
	v_mfma_f32_16x16x32_bf16 v[78:81], v[154:157], v[242:245], v[78:81]
	v_mfma_f32_16x16x32_bf16 v[74:77], v[162:165], v[242:245], v[74:77]
	v_mfma_f32_16x16x32_bf16 v[90:93], v[162:165], v[234:237], v[90:93]
	v_mfma_f32_16x16x32_bf16 v[108:111], v[162:165], v[226:229], v[108:111]
	v_mfma_f32_16x16x32_bf16 v[124:127], v[162:165], v[200:203], v[124:127]
	s_setprio 0
	s_setprio 1
	v_mfma_f32_16x16x32_bf16 v[120:123], v[180:183], v[196:199], v[120:123]
	v_mfma_f32_16x16x32_bf16 v[104:107], v[180:183], v[222:225], v[104:107]
	v_mfma_f32_16x16x32_bf16 v[86:89], v[180:183], v[230:233], v[86:89]
	v_mfma_f32_16x16x32_bf16 v[70:73], v[180:183], v[238:241], v[70:73]
	v_mfma_f32_16x16x32_bf16 v[66:69], v[188:191], v[238:241], v[66:69]
	v_mfma_f32_16x16x32_bf16 v[82:85], v[188:191], v[230:233], v[82:85]
	v_mfma_f32_16x16x32_bf16 v[100:103], v[188:191], v[222:225], v[100:103]
	v_mfma_f32_16x16x32_bf16 v[116:119], v[188:191], v[196:199], v[116:119]
	v_mfma_f32_16x16x32_bf16 v[120:123], v[184:187], v[200:203], v[120:123]
	v_mfma_f32_16x16x32_bf16 v[104:107], v[184:187], v[226:229], v[104:107]
	v_mfma_f32_16x16x32_bf16 v[86:89], v[184:187], v[234:237], v[86:89]
	v_mfma_f32_16x16x32_bf16 v[70:73], v[184:187], v[242:245], v[70:73]
	v_mfma_f32_16x16x32_bf16 v[66:69], v[192:195], v[242:245], v[66:69]
	v_mfma_f32_16x16x32_bf16 v[82:85], v[192:195], v[234:237], v[82:85]
	v_mfma_f32_16x16x32_bf16 v[100:103], v[192:195], v[226:229], v[100:103]
	v_mfma_f32_16x16x32_bf16 v[116:119], v[192:195], v[200:203], v[116:119]
	s_setprio 0
	s_barrier
	s_mov_b32 m0, s94
	v_lshl_add_u64 v[166:167], s[60:61], 0, v[136:137]
	ds_read_b128 v[196:199], v153 offset:16384
	ds_read_b128 v[200:203], v153 offset:17408
	ds_read_b128 v[222:225], v153 offset:18432
	ds_read_b128 v[226:229], v153 offset:19456
	ds_read_b128 v[230:233], v153 offset:20480
	ds_read_b128 v[234:237], v153 offset:21504
	ds_read_b128 v[238:241], v153 offset:22528
	ds_read_b128 v[242:245], v153 offset:23552
	global_load_lds_dwordx4 v[166:167], off
	v_lshl_add_u64 v[168:169], s[60:61], 0, v[132:133]
	s_mov_b32 m0, s95
	v_lshl_add_u64 v[172:173], s[62:63], 0, v[136:137]
	global_load_lds_dwordx4 v[168:169], off
	s_mov_b32 m0, s96
	v_lshl_add_u64 v[212:213], s[58:59], 0, v[134:135]
	global_load_lds_dwordx4 v[172:173], off
	v_lshl_add_u64 v[172:173], s[62:63], 0, v[132:133]
	s_mov_b32 m0, s97
	s_nop 0
	global_load_lds_dwordx4 v[172:173], off
	v_lshl_add_u64 v[172:173], s[58:59], 0, v[138:139]
	s_mov_b32 m0, s71
	s_nop 0
	global_load_lds_dwordx4 v[172:173], off
	s_mov_b32 m0, s75
	s_nop 0
	global_load_lds_dwordx4 v[212:213], off
	s_waitcnt vmcnt(8)
	s_waitcnt lgkmcnt(0)
	s_barrier
; #define PG8_STAGE(bufoff, gbase, voff) do { _Pragma("unroll") for (int _i = 0; _i < 2; ++_i) \
;         __builtin_amdgcn_global_load_lds((const unsigned*)((const char*)(gbase) + (voff)[_i]), (PG8_LAS unsigned*)(lds + (bufoff) + ldsw + _i * 8192), 16, 0, AUX_A); } while (0)
; #define PG8_LDA(dst, b, h) do { _Pragma("unroll") for (int m = 0; m < 4; ++m) _Pragma("unroll") for (int k = 0; k < 2; ++k) dst[m][k] = *(const PG8_LAS bf16x8*)(lds + PG8_SA(b, h) + aoff + m * 2048 + k * 1024); } while (0)
; #define PG8_LDB(dst, b, h) do { _Pragma("unroll") for (int n = 0; n < 2; ++n) _Pragma("unroll") for (int k = 0; k < 2; ++k) dst[n][k] = *(const PG8_LAS bf16x8*)(lds + PG8_SB(b, h) + boff + n * 2048 + k * 1024); } while (0)
; #define PG8_MMA(ai, bj, At, Bt) do { __builtin_amdgcn_s_setprio(1); _Pragma("unroll") for (int m = 0; m < 4; ++m) _Pragma("unroll") for (int n = 0; n < 2; ++n) _Pragma("unroll") for (int k = 0; k < 2; ++k) \
;         acc[ai][bj][m][n] = __builtin_amdgcn_mfma_f32_16x16x32_bf16(Bt[n][k], At[m][k], acc[ai][bj][m][n], 0, 0, 0); __builtin_amdgcn_s_setprio(0); } while (0)
; #define PG8_WAIT_V(n) asm volatile("s_waitcnt vmcnt(" #n ")" ::: "memory")
; #define PG8_WAIT_L(n) asm volatile("s_waitcnt lgkmcnt(" #n ")" ::: "memory")
; #define PG8_BAR __builtin_amdgcn_s_barrier()
; #define PG8_SCHED __builtin_amdgcn_sched_barrier(0)
; template <class Epi, class Sched, bool ALIGN_EPI = false, bool SP2 = false>
; __device__ __forceinline__ void gemm_phase(PG8_LAS unsigned char* lds, const Gemm g, const Sched& S, const Epi& E) {
;     ...
;             PG8_WAIT_V(8); PG8_WAIT_L(0); PG8_BAR; PG8_MMA(1, 0, At, B0); PG8_MMA(1, 1, At, B1); PG8_BAR; PG8_SCHED;
;             PG8_LDB(B0, 1, 0); PG8_LDB(B1, 1, 1); PG8_SCHED; PG8_LDA(At, 1, 0); PG8_STAGE(PG8_SA(0, 1), a2 + hstep, voffA);
;             PG8_WAIT_V(8); PG8_WAIT_L(0); PG8_BAR; PG8_MMA(0, 0, At, B0); PG8_MMA(0, 1, At, B1); PG8_BAR; PG8_SCHED;
	s_setprio 1
	s_waitcnt lgkmcnt(0)
	v_mfma_f32_16x16x32_bf16 v[62:65], v[148:151], v[196:199], v[62:65]
	v_mfma_f32_16x16x32_bf16 v[46:49], v[148:151], v[222:225], v[46:49]
	v_mfma_f32_16x16x32_bf16 v[30:33], v[148:151], v[230:233], v[30:33]
	v_mfma_f32_16x16x32_bf16 v[14:17], v[148:151], v[238:241], v[14:17]
	v_mfma_f32_16x16x32_bf16 v[10:13], v[158:161], v[238:241], v[10:13]
	v_mfma_f32_16x16x32_bf16 v[26:29], v[158:161], v[230:233], v[26:29]
	v_mfma_f32_16x16x32_bf16 v[42:45], v[158:161], v[222:225], v[42:45]
	v_mfma_f32_16x16x32_bf16 v[58:61], v[158:161], v[196:199], v[58:61]
	v_mfma_f32_16x16x32_bf16 v[62:65], v[154:157], v[200:203], v[62:65]
	v_mfma_f32_16x16x32_bf16 v[46:49], v[154:157], v[226:229], v[46:49]
	v_mfma_f32_16x16x32_bf16 v[30:33], v[154:157], v[234:237], v[30:33]
	v_mfma_f32_16x16x32_bf16 v[14:17], v[154:157], v[242:245], v[14:17]
	v_mfma_f32_16x16x32_bf16 v[10:13], v[162:165], v[242:245], v[10:13]
	v_mfma_f32_16x16x32_bf16 v[26:29], v[162:165], v[234:237], v[26:29]
	v_mfma_f32_16x16x32_bf16 v[42:45], v[162:165], v[226:229], v[42:45]
	v_mfma_f32_16x16x32_bf16 v[58:61], v[162:165], v[200:203], v[58:61]
	s_setprio 0
	s_setprio 1
	v_mfma_f32_16x16x32_bf16 v[54:57], v[180:183], v[196:199], v[54:57]
	v_mfma_f32_16x16x32_bf16 v[38:41], v[180:183], v[222:225], v[38:41]
	v_mfma_f32_16x16x32_bf16 v[22:25], v[180:183], v[230:233], v[22:25]
	v_mfma_f32_16x16x32_bf16 v[6:9], v[180:183], v[238:241], v[6:9]
	v_mfma_f32_16x16x32_bf16 v[2:5], v[188:191], v[238:241], v[2:5]
	v_mfma_f32_16x16x32_bf16 v[18:21], v[188:191], v[230:233], v[18:21]
	v_mfma_f32_16x16x32_bf16 v[34:37], v[188:191], v[222:225], v[34:37]
	v_mfma_f32_16x16x32_bf16 v[50:53], v[188:191], v[196:199], v[50:53]
	v_mfma_f32_16x16x32_bf16 v[54:57], v[184:187], v[200:203], v[54:57]
	v_mfma_f32_16x16x32_bf16 v[38:41], v[184:187], v[226:229], v[38:41]
	v_mfma_f32_16x16x32_bf16 v[22:25], v[184:187], v[234:237], v[22:25]
	v_mfma_f32_16x16x32_bf16 v[6:9], v[184:187], v[242:245], v[6:9]
	v_mfma_f32_16x16x32_bf16 v[2:5], v[192:195], v[242:245], v[2:5]
	v_mfma_f32_16x16x32_bf16 v[18:21], v[192:195], v[234:237], v[18:21]
	v_mfma_f32_16x16x32_bf16 v[34:37], v[192:195], v[226:229], v[34:37]
	v_mfma_f32_16x16x32_bf16 v[50:53], v[192:195], v[200:203], v[50:53]
	s_setprio 0
	s_barrier
	v_add_u32_e32 v162, vcc_lo, v99
	v_add_u32_e32 v192, vcc_hi, v99
	ds_read_b128 v[148:151], v162
	ds_read_b128 v[154:157], v162 offset:1024
	ds_read_b128 v[158:161], v162 offset:2048
	ds_read_b128 v[162:165], v162 offset:3072
	ds_read_b128 v[180:183], v192
	ds_read_b128 v[184:187], v192 offset:1024
	ds_read_b128 v[188:191], v192 offset:2048
	ds_read_b128 v[192:195], v192 offset:3072
	s_mov_b32 m0, s78
	v_lshl_add_u64 v[246:247], s[56:57], 0, v[138:139]
	ds_read_b128 v[196:199], v153 offset:32768
	ds_read_b128 v[200:203], v153 offset:33792
	ds_read_b128 v[222:225], v153 offset:34816
	ds_read_b128 v[226:229], v153 offset:35840
	ds_read_b128 v[230:233], v153 offset:36864
	ds_read_b128 v[234:237], v153 offset:37888
	ds_read_b128 v[238:241], v153 offset:38912
	ds_read_b128 v[242:245], v153 offset:39936
	global_load_lds_dwordx4 v[246:247], off
	v_lshl_add_u64 v[246:247], s[56:57], 0, v[134:135]
	s_mov_b32 m0, s82
	s_nop 0
	global_load_lds_dwordx4 v[246:247], off
	s_waitcnt vmcnt(8)
	s_waitcnt lgkmcnt(0)
	s_barrier
	s_setprio 1
	s_waitcnt lgkmcnt(0)
	v_mfma_f32_16x16x32_bf16 v[128:131], v[148:151], v[196:199], v[128:131]
	v_mfma_f32_16x16x32_bf16 v[112:115], v[148:151], v[222:225], v[112:115]
	v_mfma_f32_16x16x32_bf16 v[94:97], v[148:151], v[230:233], v[94:97]
	v_mfma_f32_16x16x32_bf16 v[78:81], v[148:151], v[238:241], v[78:81]
	v_mfma_f32_16x16x32_bf16 v[74:77], v[158:161], v[238:241], v[74:77]
	v_mfma_f32_16x16x32_bf16 v[90:93], v[158:161], v[230:233], v[90:93]
	v_mfma_f32_16x16x32_bf16 v[108:111], v[158:161], v[222:225], v[108:111]
	v_mfma_f32_16x16x32_bf16 v[124:127], v[158:161], v[196:199], v[124:127]
	v_mfma_f32_16x16x32_bf16 v[128:131], v[154:157], v[200:203], v[128:131]
	v_mfma_f32_16x16x32_bf16 v[112:115], v[154:157], v[226:229], v[112:115]
	v_mfma_f32_16x16x32_bf16 v[94:97], v[154:157], v[234:237], v[94:97]
	v_mfma_f32_16x16x32_bf16 v[78:81], v[154:157], v[242:245], v[78:81]
	v_mfma_f32_16x16x32_bf16 v[74:77], v[162:165], v[242:245], v[74:77]
	v_mfma_f32_16x16x32_bf16 v[90:93], v[162:165], v[234:237], v[90:93]
	v_mfma_f32_16x16x32_bf16 v[108:111], v[162:165], v[226:229], v[108:111]
	v_mfma_f32_16x16x32_bf16 v[124:127], v[162:165], v[200:203], v[124:127]
	s_setprio 0
	s_setprio 1
	v_mfma_f32_16x16x32_bf16 v[120:123], v[180:183], v[196:199], v[120:123]
	v_mfma_f32_16x16x32_bf16 v[104:107], v[180:183], v[222:225], v[104:107]
	v_mfma_f32_16x16x32_bf16 v[86:89], v[180:183], v[230:233], v[86:89]
	v_mfma_f32_16x16x32_bf16 v[70:73], v[180:183], v[238:241], v[70:73]
	v_mfma_f32_16x16x32_bf16 v[66:69], v[188:191], v[238:241], v[66:69]
	v_mfma_f32_16x16x32_bf16 v[82:85], v[188:191], v[230:233], v[82:85]
	v_mfma_f32_16x16x32_bf16 v[100:103], v[188:191], v[222:225], v[100:103]
	v_mfma_f32_16x16x32_bf16 v[116:119], v[188:191], v[196:199], v[116:119]
	v_mfma_f32_16x16x32_bf16 v[120:123], v[184:187], v[200:203], v[120:123]
	v_mfma_f32_16x16x32_bf16 v[104:107], v[184:187], v[226:229], v[104:107]
	v_mfma_f32_16x16x32_bf16 v[86:89], v[184:187], v[234:237], v[86:89]
	v_mfma_f32_16x16x32_bf16 v[70:73], v[184:187], v[242:245], v[70:73]
	v_mfma_f32_16x16x32_bf16 v[66:69], v[192:195], v[242:245], v[66:69]
	v_mfma_f32_16x16x32_bf16 v[82:85], v[192:195], v[234:237], v[82:85]
	v_mfma_f32_16x16x32_bf16 v[100:103], v[192:195], v[226:229], v[100:103]
	v_mfma_f32_16x16x32_bf16 v[116:119], v[192:195], v[200:203], v[116:119]
	s_setprio 0
	s_barrier
; #define PG8_STAGE(bufoff, gbase, voff) do { _Pragma("unroll") for (int _i = 0; _i < 2; ++_i) \
;         __builtin_amdgcn_global_load_lds((const unsigned*)((const char*)(gbase) + (voff)[_i]), (PG8_LAS unsigned*)(lds + (bufoff) + ldsw + _i * 8192), 16, 0, AUX_A); } while (0)
; #define PG8_STAGEB(bufoff, gbase, voff) do { _Pragma("unroll") for (int _i = 0; _i < 2; ++_i) \
;         __builtin_amdgcn_global_load_lds((const unsigned*)((const char*)(gbase) + (voff)[_i]), (PG8_LAS unsigned*)(lds + (bufoff) + ldsw + _i * 8192), 16, 0, AUX_B); } while (0)
; #define PG8_LDA(dst, b, h) do { _Pragma("unroll") for (int m = 0; m < 4; ++m) _Pragma("unroll") for (int k = 0; k < 2; ++k) dst[m][k] = *(const PG8_LAS bf16x8*)(lds + PG8_SA(b, h) + aoff + m * 2048 + k * 1024); } while (0)
; #define PG8_MMA(ai, bj, At, Bt) do { __builtin_amdgcn_s_setprio(1); _Pragma("unroll") for (int m = 0; m < 4; ++m) _Pragma("unroll") for (int n = 0; n < 2; ++n) _Pragma("unroll") for (int k = 0; k < 2; ++k) \
;         acc[ai][bj][m][n] = __builtin_amdgcn_mfma_f32_16x16x32_bf16(Bt[n][k], At[m][k], acc[ai][bj][m][n], 0, 0, 0); __builtin_amdgcn_s_setprio(0); } while (0)
; #define PG8_WAIT_V(n) asm volatile("s_waitcnt vmcnt(" #n ")" ::: "memory")
; #define PG8_WAIT_L(n) asm volatile("s_waitcnt lgkmcnt(" #n ")" ::: "memory")
; #define PG8_BAR __builtin_amdgcn_s_barrier()
; #define PG8_SCHED __builtin_amdgcn_sched_barrier(0)
; template <class Epi, class Sched, bool ALIGN_EPI = false, bool SP2 = false>
; __device__ __forceinline__ void gemm_phase(PG8_LAS unsigned char* lds, const Gemm g, const Sched& S, const Epi& E) {
;     ...
;             PG8_LDA(At, 1, 1); PG8_STAGEB(PG8_SB(1, 0), b3, voffB); PG8_STAGEB(PG8_SB(1, 1), b3 + hstep, voffB); PG8_STAGE(PG8_SA(1, 0), a3, voffA);
;             PG8_WAIT_V(8); PG8_WAIT_L(0); PG8_BAR; PG8_MMA(1, 0, At, B0); PG8_MMA(1, 1, At, B1); PG8_BAR; PG8_SCHED;
	s_mov_b32 m0, s1
	v_lshl_add_u64 v[166:167], v[166:167], 0, s[76:77]
	ds_read_b128 v[196:199], v153 offset:49152
	ds_read_b128 v[200:203], v153 offset:50176
	ds_read_b128 v[222:225], v153 offset:51200
	ds_read_b128 v[226:229], v153 offset:52224
	ds_read_b128 v[230:233], v153 offset:53248
	ds_read_b128 v[234:237], v153 offset:54272
	ds_read_b128 v[238:241], v153 offset:55296
	ds_read_b128 v[242:245], v153 offset:56320
	global_load_lds_dwordx4 v[166:167], off
	v_lshl_add_u64 v[166:167], v[168:169], 0, s[76:77]
	s_mov_b32 m0, s0
	s_nop 0
	global_load_lds_dwordx4 v[166:167], off
	v_lshl_add_u64 v[166:167], s[54:55], 0, v[136:137]
	s_mov_b32 m0, s47
	s_nop 0
	global_load_lds_dwordx4 v[166:167], off
	v_lshl_add_u64 v[166:167], s[54:55], 0, v[132:133]
	s_mov_b32 m0, s46
	s_nop 0
	global_load_lds_dwordx4 v[166:167], off
	v_lshl_add_u64 v[166:167], v[172:173], 0, s[76:77]
	s_mov_b32 m0, s83
	s_nop 0
	global_load_lds_dwordx4 v[166:167], off
	v_lshl_add_u64 v[166:167], v[212:213], 0, s[76:77]
	s_mov_b32 m0, s88
	s_nop 0
	global_load_lds_dwordx4 v[166:167], off
	s_waitcnt vmcnt(8)
	s_waitcnt lgkmcnt(0)
	s_barrier
	s_setprio 1
	s_waitcnt lgkmcnt(0)
	v_mfma_f32_16x16x32_bf16 v[62:65], v[148:151], v[196:199], v[62:65]
	v_mfma_f32_16x16x32_bf16 v[46:49], v[148:151], v[222:225], v[46:49]
	v_mfma_f32_16x16x32_bf16 v[30:33], v[148:151], v[230:233], v[30:33]
	v_mfma_f32_16x16x32_bf16 v[14:17], v[148:151], v[238:241], v[14:17]
	v_mfma_f32_16x16x32_bf16 v[10:13], v[158:161], v[238:241], v[10:13]
	v_mfma_f32_16x16x32_bf16 v[26:29], v[158:161], v[230:233], v[26:29]
	v_mfma_f32_16x16x32_bf16 v[42:45], v[158:161], v[222:225], v[42:45]
	v_mfma_f32_16x16x32_bf16 v[58:61], v[158:161], v[196:199], v[58:61]
	v_mfma_f32_16x16x32_bf16 v[62:65], v[154:157], v[200:203], v[62:65]
	v_mfma_f32_16x16x32_bf16 v[46:49], v[154:157], v[226:229], v[46:49]
	v_mfma_f32_16x16x32_bf16 v[30:33], v[154:157], v[234:237], v[30:33]
	v_mfma_f32_16x16x32_bf16 v[14:17], v[154:157], v[242:245], v[14:17]
	v_mfma_f32_16x16x32_bf16 v[10:13], v[162:165], v[242:245], v[10:13]
	v_mfma_f32_16x16x32_bf16 v[26:29], v[162:165], v[234:237], v[26:29]
	v_mfma_f32_16x16x32_bf16 v[42:45], v[162:165], v[226:229], v[42:45]
	v_mfma_f32_16x16x32_bf16 v[58:61], v[162:165], v[200:203], v[58:61]
	s_setprio 0
	s_setprio 1
	v_mfma_f32_16x16x32_bf16 v[54:57], v[180:183], v[196:199], v[54:57]
	v_mfma_f32_16x16x32_bf16 v[38:41], v[180:183], v[222:225], v[38:41]
	v_mfma_f32_16x16x32_bf16 v[22:25], v[180:183], v[230:233], v[22:25]
	v_mfma_f32_16x16x32_bf16 v[6:9], v[180:183], v[238:241], v[6:9]
	v_mfma_f32_16x16x32_bf16 v[2:5], v[188:191], v[238:241], v[2:5]
	v_mfma_f32_16x16x32_bf16 v[18:21], v[188:191], v[230:233], v[18:21]
	v_mfma_f32_16x16x32_bf16 v[34:37], v[188:191], v[222:225], v[34:37]
	v_mfma_f32_16x16x32_bf16 v[50:53], v[188:191], v[196:199], v[50:53]
	v_mfma_f32_16x16x32_bf16 v[54:57], v[184:187], v[200:203], v[54:57]
	v_mfma_f32_16x16x32_bf16 v[38:41], v[184:187], v[226:229], v[38:41]
	v_mfma_f32_16x16x32_bf16 v[22:25], v[184:187], v[234:237], v[22:25]
	v_mfma_f32_16x16x32_bf16 v[6:9], v[184:187], v[242:245], v[6:9]
	v_mfma_f32_16x16x32_bf16 v[2:5], v[192:195], v[242:245], v[2:5]
	v_mfma_f32_16x16x32_bf16 v[18:21], v[192:195], v[234:237], v[18:21]
	v_mfma_f32_16x16x32_bf16 v[34:37], v[192:195], v[226:229], v[34:37]
	v_mfma_f32_16x16x32_bf16 v[50:53], v[192:195], v[200:203], v[50:53]
	s_setprio 0
	s_barrier
	v_lshl_add_u64 v[144:145], v[144:145], 0, s[86:87]
	v_lshl_add_u64 v[146:147], v[146:147], 0, s[86:87]
	s_mov_b32 s29, s81
	s_cbranch_scc0 .LBB0_1157
	s_and_b64 vcc, exec, s[16:17]
	s_cbranch_vccz .LBB0_1160
	s_barrier

; #define PG8_STAGE(bufoff, gbase, voff) do { _Pragma("unroll") for (int _i = 0; _i < 2; ++_i) \
;         __builtin_amdgcn_global_load_lds((const unsigned*)((const char*)(gbase) + (voff)[_i]), (PG8_LAS unsigned*)(lds + (bufoff) + ldsw + _i * 8192), 16, 0, AUX_A); } while (0)
; #define PG8_STAGEB(bufoff, gbase, voff) do { _Pragma("unroll") for (int _i = 0; _i < 2; ++_i) \
;         __builtin_amdgcn_global_load_lds((const unsigned*)((const char*)(gbase) + (voff)[_i]), (PG8_LAS unsigned*)(lds + (bufoff) + ldsw + _i * 8192), 16, 0, AUX_B); } while (0)
; #define PG8_LDA(dst, b, h) do { _Pragma("unroll") for (int m = 0; m < 4; ++m) _Pragma("unroll") for (int k = 0; k < 2; ++k) dst[m][k] = *(const PG8_LAS bf16x8*)(lds + PG8_SA(b, h) + aoff + m * 2048 + k * 1024); } while (0)
; #define PG8_LDB(dst, b, h) do { _Pragma("unroll") for (int n = 0; n < 2; ++n) _Pragma("unroll") for (int k = 0; k < 2; ++k) dst[n][k] = *(const PG8_LAS bf16x8*)(lds + PG8_SB(b, h) + boff + n * 2048 + k * 1024); } while (0)
; #define PG8_MMA(ai, bj, At, Bt) do { __builtin_amdgcn_s_setprio(1); _Pragma("unroll") for (int m = 0; m < 4; ++m) _Pragma("unroll") for (int n = 0; n < 2; ++n) _Pragma("unroll") for (int k = 0; k < 2; ++k) \
;         acc[ai][bj][m][n] = __builtin_amdgcn_mfma_f32_16x16x32_bf16(Bt[n][k], At[m][k], acc[ai][bj][m][n], 0, 0, 0); __builtin_amdgcn_s_setprio(0); } while (0)
; template <class Epi, class Sched, bool ALIGN_EPI = false, bool SP2 = false>
; __device__ __forceinline__ void gemm_phase(PG8_LAS unsigned char* lds, const Gemm g, const Sched& S, const Epi& E) {
;     ...
;             const bool last = (t == nt - 2);
;             const char* a1 = PG8_KP(cA, t + 1, rot, nt);
;             const char* a2 = last ? nAr : PG8_KP(cA, t + 2, rot, nt); const char* b2 = last ? nBr : PG8_KP(cB, t + 2, rot, nt);
;             const char* a3 = a2 + kstep; const char* b3 = b2 + kstep;
;             if (last && has_next) S.a_ready(nxt);
;             if constexpr (SP2) {
;             PG8_LDB(B0, 0, 0); PG8_LDB(B1, 0, 1); PG8_SCHED; PG8_LDA(At, 0, 0); PG8_STAGE(PG8_SA(1, 1), a1 + hstep, voffA);
;             PG8_WAIT_V(8); PG8_WAIT_L(0); PG8_BAR; PG8_MMA(0, 0, At, B0); PG8_MMA(0, 1, At, B1); PG8_BAR; PG8_SCHED;
;             PG8_LDA(At, 0, 1); PG8_STAGEB(PG8_SB(0, 0), b2, voffB); PG8_STAGEB(PG8_SB(0, 1), b2 + hstep, voffB); PG8_STAGE(PG8_SA(0, 0), a2, voffA);
.LBB0_1308:
	s_or_b32 s0, s11, 1
	s_cmp_ge_i32 s0, s71
	s_cselect_b32 s2, s71, 0
	s_add_i32 s11, s11, 2
	s_cmp_ge_i32 s11, s71
	s_cselect_b32 s0, s71, 0
	s_sub_i32 s0, s13, s0
	s_ashr_i32 s1, s0, 31
	s_lshl_b64 s[0:1], s[0:1], 7
	s_add_u32 s15, s40, s0
	s_addc_u32 s29, s41, s1
	s_add_u32 s0, s34, s0
	s_addc_u32 s1, s35, s1
	s_cmp_eq_u32 s71, s13
	s_cselect_b32 s45, s43, s29
	s_cselect_b32 s44, s42, s15
	s_cselect_b32 s37, s19, s1
	s_cselect_b32 s36, s18, s0
	s_add_i32 s15, 0, 0x10000
	s_add_i32 s29, 0, 0x14000
	v_add_u32_e32 v148, s15, v99
	v_add_u32_e32 v168, s29, v99
	ds_read_b128 v[136:139], v148
	ds_read_b128 v[140:143], v148 offset:1024
	ds_read_b128 v[144:147], v148 offset:2048
	ds_read_b128 v[148:151], v148 offset:3072
	ds_read_b128 v[164:167], v168
	ds_read_b128 v[182:185], v168 offset:1024
	ds_read_b128 v[186:189], v168 offset:2048
	ds_read_b128 v[190:193], v168 offset:3072
	v_mad_i64_i32 v[168:169], s[0:1], s2, v220, v[134:135]
	s_add_i32 m0, s50, 0xc000
	ds_read_b128 v[194:197], v181
	ds_read_b128 v[198:201], v181 offset:1024
	ds_read_b128 v[222:225], v181 offset:2048
	ds_read_b128 v[226:229], v181 offset:3072
	ds_read_b128 v[230:233], v181 offset:4096
	ds_read_b128 v[234:237], v181 offset:5120
	ds_read_b128 v[238:241], v181 offset:6144
	ds_read_b128 v[242:245], v181 offset:7168
	global_load_lds_dwordx4 v[168:169], off
	v_mad_i64_i32 v[168:169], s[0:1], s2, v220, v[132:133]
	s_add_i32 m0, s50, 0xe000
	s_nop 0
	global_load_lds_dwordx4 v[168:169], off
	s_waitcnt vmcnt(8)
	s_waitcnt lgkmcnt(0)
	s_barrier
	s_setprio 1
	s_waitcnt lgkmcnt(0)
	v_mfma_f32_16x16x32_bf16 v[128:131], v[136:139], v[194:197], v[128:131]
	v_mfma_f32_16x16x32_bf16 v[120:123], v[136:139], v[222:225], v[120:123]
	v_mfma_f32_16x16x32_bf16 v[104:107], v[136:139], v[230:233], v[104:107]
	v_mfma_f32_16x16x32_bf16 v[86:89], v[136:139], v[238:241], v[86:89]
	v_mfma_f32_16x16x32_bf16 v[78:81], v[144:147], v[238:241], v[78:81]
	v_mfma_f32_16x16x32_bf16 v[94:97], v[144:147], v[230:233], v[94:97]
	v_mfma_f32_16x16x32_bf16 v[112:115], v[144:147], v[222:225], v[112:115]
	v_mfma_f32_16x16x32_bf16 v[124:127], v[144:147], v[194:197], v[124:127]
	v_mfma_f32_16x16x32_bf16 v[128:131], v[140:143], v[198:201], v[128:131]
	v_mfma_f32_16x16x32_bf16 v[120:123], v[140:143], v[226:229], v[120:123]
	v_mfma_f32_16x16x32_bf16 v[104:107], v[140:143], v[234:237], v[104:107]
	v_mfma_f32_16x16x32_bf16 v[86:89], v[140:143], v[242:245], v[86:89]
	v_mfma_f32_16x16x32_bf16 v[78:81], v[148:151], v[242:245], v[78:81]
	v_mfma_f32_16x16x32_bf16 v[94:97], v[148:151], v[234:237], v[94:97]
	v_mfma_f32_16x16x32_bf16 v[112:115], v[148:151], v[226:229], v[112:115]
	v_mfma_f32_16x16x32_bf16 v[124:127], v[148:151], v[198:201], v[124:127]
	s_setprio 0
	s_setprio 1
	v_mfma_f32_16x16x32_bf16 v[116:119], v[164:167], v[194:197], v[116:119]
	v_mfma_f32_16x16x32_bf16 v[100:103], v[164:167], v[222:225], v[100:103]
	v_mfma_f32_16x16x32_bf16 v[82:85], v[164:167], v[230:233], v[82:85]
	v_mfma_f32_16x16x32_bf16 v[70:73], v[164:167], v[238:241], v[70:73]
	v_mfma_f32_16x16x32_bf16 v[66:69], v[186:189], v[238:241], v[66:69]
	v_mfma_f32_16x16x32_bf16 v[74:77], v[186:189], v[230:233], v[74:77]
	v_mfma_f32_16x16x32_bf16 v[90:93], v[186:189], v[222:225], v[90:93]
	v_mfma_f32_16x16x32_bf16 v[108:111], v[186:189], v[194:197], v[108:111]
	v_mfma_f32_16x16x32_bf16 v[116:119], v[182:185], v[198:201], v[116:119]
	v_mfma_f32_16x16x32_bf16 v[100:103], v[182:185], v[226:229], v[100:103]
	v_mfma_f32_16x16x32_bf16 v[82:85], v[182:185], v[234:237], v[82:85]
	v_mfma_f32_16x16x32_bf16 v[70:73], v[182:185], v[242:245], v[70:73]
	v_mfma_f32_16x16x32_bf16 v[66:69], v[190:193], v[242:245], v[66:69]
	v_mfma_f32_16x16x32_bf16 v[74:77], v[190:193], v[234:237], v[74:77]
	v_mfma_f32_16x16x32_bf16 v[90:93], v[190:193], v[226:229], v[90:93]
	v_mfma_f32_16x16x32_bf16 v[108:111], v[190:193], v[198:201], v[108:111]
	s_setprio 0
	s_barrier
	s_add_i32 s0, s15, s49
	v_lshl_add_u64 v[168:169], s[36:37], 0, v[156:157]
	s_mov_b32 m0, s0
	ds_read_b128 v[194:197], v181 offset:16384
	ds_read_b128 v[198:201], v181 offset:17408
	ds_read_b128 v[222:225], v181 offset:18432
	ds_read_b128 v[226:229], v181 offset:19456
	ds_read_b128 v[230:233], v181 offset:20480
	ds_read_b128 v[234:237], v181 offset:21504
	ds_read_b128 v[238:241], v181 offset:22528
	ds_read_b128 v[242:245], v181 offset:23552
	global_load_lds_dwordx4 v[168:169], off
	s_add_i32 m0, s0, 0x2000
	s_add_u32 s0, s36, 0x80000
	v_lshl_add_u64 v[172:173], s[36:37], 0, v[152:153]
	s_addc_u32 s1, s37, 0
	s_add_i32 s2, s29, s49
	global_load_lds_dwordx4 v[172:173], off
	v_lshl_add_u64 v[202:203], s[0:1], 0, v[156:157]
	s_mov_b32 m0, s2
	v_lshl_add_u64 v[212:213], s[44:45], 0, v[154:155]
	global_load_lds_dwordx4 v[202:203], off
	v_lshl_add_u64 v[202:203], s[0:1], 0, v[152:153]
	s_add_i32 m0, s2, 0x2000
	s_nop 0
	global_load_lds_dwordx4 v[202:203], off
	v_lshl_add_u64 v[202:203], s[44:45], 0, v[158:159]
	s_mov_b32 m0, s50
	s_nop 0
	global_load_lds_dwordx4 v[202:203], off
	s_mov_b32 m0, s51
	s_nop 0
	global_load_lds_dwordx4 v[212:213], off
	s_waitcnt vmcnt(8)
	s_waitcnt lgkmcnt(0)
	s_barrier
; #define PG8_STAGE(bufoff, gbase, voff) do { _Pragma("unroll") for (int _i = 0; _i < 2; ++_i) \
;         __builtin_amdgcn_global_load_lds((const unsigned*)((const char*)(gbase) + (voff)[_i]), (PG8_LAS unsigned*)(lds + (bufoff) + ldsw + _i * 8192), 16, 0, AUX_A); } while (0)
; #define PG8_LDA(dst, b, h) do { _Pragma("unroll") for (int m = 0; m < 4; ++m) _Pragma("unroll") for (int k = 0; k < 2; ++k) dst[m][k] = *(const PG8_LAS bf16x8*)(lds + PG8_SA(b, h) + aoff + m * 2048 + k * 1024); } while (0)
; #define PG8_LDB(dst, b, h) do { _Pragma("unroll") for (int n = 0; n < 2; ++n) _Pragma("unroll") for (int k = 0; k < 2; ++k) dst[n][k] = *(const PG8_LAS bf16x8*)(lds + PG8_SB(b, h) + boff + n * 2048 + k * 1024); } while (0)
; #define PG8_MMA(ai, bj, At, Bt) do { __builtin_amdgcn_s_setprio(1); _Pragma("unroll") for (int m = 0; m < 4; ++m) _Pragma("unroll") for (int n = 0; n < 2; ++n) _Pragma("unroll") for (int k = 0; k < 2; ++k) \
;         acc[ai][bj][m][n] = __builtin_amdgcn_mfma_f32_16x16x32_bf16(Bt[n][k], At[m][k], acc[ai][bj][m][n], 0, 0, 0); __builtin_amdgcn_s_setprio(0); } while (0)
; #define PG8_WAIT_V(n) asm volatile("s_waitcnt vmcnt(" #n ")" ::: "memory")
; #define PG8_WAIT_L(n) asm volatile("s_waitcnt lgkmcnt(" #n ")" ::: "memory")
; #define PG8_BAR __builtin_amdgcn_s_barrier()
; #define PG8_SCHED __builtin_amdgcn_sched_barrier(0)
; template <class Epi, class Sched, bool ALIGN_EPI = false, bool SP2 = false>
; __device__ __forceinline__ void gemm_phase(PG8_LAS unsigned char* lds, const Gemm g, const Sched& S, const Epi& E) {
;     ...
;             PG8_WAIT_V(8); PG8_WAIT_L(0); PG8_BAR; PG8_MMA(1, 0, At, B0); PG8_MMA(1, 1, At, B1); PG8_BAR; PG8_SCHED;
;             PG8_LDB(B0, 1, 0); PG8_LDB(B1, 1, 1); PG8_SCHED; PG8_LDA(At, 1, 0); PG8_STAGE(PG8_SA(0, 1), a2 + hstep, voffA);
;             PG8_WAIT_V(8); PG8_WAIT_L(0); PG8_BAR; PG8_MMA(0, 0, At, B0); PG8_MMA(0, 1, At, B1); PG8_BAR; PG8_SCHED;
	s_setprio 1
	s_waitcnt lgkmcnt(0)
	v_mfma_f32_16x16x32_bf16 v[62:65], v[136:139], v[194:197], v[62:65]
	v_mfma_f32_16x16x32_bf16 v[54:57], v[136:139], v[222:225], v[54:57]
	v_mfma_f32_16x16x32_bf16 v[38:41], v[136:139], v[230:233], v[38:41]
	v_mfma_f32_16x16x32_bf16 v[22:25], v[136:139], v[238:241], v[22:25]
	v_mfma_f32_16x16x32_bf16 v[14:17], v[144:147], v[238:241], v[14:17]
	v_mfma_f32_16x16x32_bf16 v[30:33], v[144:147], v[230:233], v[30:33]
	v_mfma_f32_16x16x32_bf16 v[46:49], v[144:147], v[222:225], v[46:49]
	v_mfma_f32_16x16x32_bf16 v[58:61], v[144:147], v[194:197], v[58:61]
	v_mfma_f32_16x16x32_bf16 v[62:65], v[140:143], v[198:201], v[62:65]
	v_mfma_f32_16x16x32_bf16 v[54:57], v[140:143], v[226:229], v[54:57]
	v_mfma_f32_16x16x32_bf16 v[38:41], v[140:143], v[234:237], v[38:41]
	v_mfma_f32_16x16x32_bf16 v[22:25], v[140:143], v[242:245], v[22:25]
	v_mfma_f32_16x16x32_bf16 v[14:17], v[148:151], v[242:245], v[14:17]
	v_mfma_f32_16x16x32_bf16 v[30:33], v[148:151], v[234:237], v[30:33]
	v_mfma_f32_16x16x32_bf16 v[46:49], v[148:151], v[226:229], v[46:49]
	v_mfma_f32_16x16x32_bf16 v[58:61], v[148:151], v[198:201], v[58:61]
	s_setprio 0
	s_setprio 1
	v_mfma_f32_16x16x32_bf16 v[50:53], v[164:167], v[194:197], v[50:53]
	v_mfma_f32_16x16x32_bf16 v[34:37], v[164:167], v[222:225], v[34:37]
	v_mfma_f32_16x16x32_bf16 v[18:21], v[164:167], v[230:233], v[18:21]
	v_mfma_f32_16x16x32_bf16 v[6:9], v[164:167], v[238:241], v[6:9]
	v_mfma_f32_16x16x32_bf16 v[2:5], v[186:189], v[238:241], v[2:5]
	v_mfma_f32_16x16x32_bf16 v[10:13], v[186:189], v[230:233], v[10:13]
	v_mfma_f32_16x16x32_bf16 v[26:29], v[186:189], v[222:225], v[26:29]
	v_mfma_f32_16x16x32_bf16 v[42:45], v[186:189], v[194:197], v[42:45]
	v_mfma_f32_16x16x32_bf16 v[50:53], v[182:185], v[198:201], v[50:53]
	v_mfma_f32_16x16x32_bf16 v[34:37], v[182:185], v[226:229], v[34:37]
	v_mfma_f32_16x16x32_bf16 v[18:21], v[182:185], v[234:237], v[18:21]
	v_mfma_f32_16x16x32_bf16 v[6:9], v[182:185], v[242:245], v[6:9]
	v_mfma_f32_16x16x32_bf16 v[2:5], v[190:193], v[242:245], v[2:5]
	v_mfma_f32_16x16x32_bf16 v[10:13], v[190:193], v[234:237], v[10:13]
	v_mfma_f32_16x16x32_bf16 v[26:29], v[190:193], v[226:229], v[26:29]
	v_mfma_f32_16x16x32_bf16 v[42:45], v[190:193], v[198:201], v[42:45]
	s_setprio 0
	s_barrier
	s_add_i32 s2, 0, 0x18000
	s_add_i32 s15, 0, 0x1c000
	v_add_u32_e32 v148, s2, v99
	v_add_u32_e32 v190, s15, v99
	ds_read_b128 v[136:139], v148
	ds_read_b128 v[140:143], v148 offset:1024
	ds_read_b128 v[144:147], v148 offset:2048
	ds_read_b128 v[148:151], v148 offset:3072
	ds_read_b128 v[164:167], v190
	ds_read_b128 v[182:185], v190 offset:1024
	ds_read_b128 v[186:189], v190 offset:2048
	ds_read_b128 v[190:193], v190 offset:3072
	s_add_u32 s0, s44, 0x80000
	s_addc_u32 s1, s45, 0
	s_mov_b32 m0, s52
	v_lshl_add_u64 v[246:247], s[0:1], 0, v[158:159]
	ds_read_b128 v[194:197], v181 offset:32768
	ds_read_b128 v[198:201], v181 offset:33792
	ds_read_b128 v[222:225], v181 offset:34816
	ds_read_b128 v[226:229], v181 offset:35840
	ds_read_b128 v[230:233], v181 offset:36864
	ds_read_b128 v[234:237], v181 offset:37888
	ds_read_b128 v[238:241], v181 offset:38912
	ds_read_b128 v[242:245], v181 offset:39936
	global_load_lds_dwordx4 v[246:247], off
	v_lshl_add_u64 v[246:247], s[0:1], 0, v[154:155]
	s_mov_b32 m0, s53
	s_nop 0
	global_load_lds_dwordx4 v[246:247], off
	s_waitcnt vmcnt(8)
	s_waitcnt lgkmcnt(0)
	s_barrier
	s_setprio 1
	s_waitcnt lgkmcnt(0)
	v_mfma_f32_16x16x32_bf16 v[128:131], v[136:139], v[194:197], v[128:131]
	v_mfma_f32_16x16x32_bf16 v[120:123], v[136:139], v[222:225], v[120:123]
	v_mfma_f32_16x16x32_bf16 v[104:107], v[136:139], v[230:233], v[104:107]
	v_mfma_f32_16x16x32_bf16 v[86:89], v[136:139], v[238:241], v[86:89]
	v_mfma_f32_16x16x32_bf16 v[78:81], v[144:147], v[238:241], v[78:81]
	v_mfma_f32_16x16x32_bf16 v[94:97], v[144:147], v[230:233], v[94:97]
	v_mfma_f32_16x16x32_bf16 v[112:115], v[144:147], v[222:225], v[112:115]
	v_mfma_f32_16x16x32_bf16 v[124:127], v[144:147], v[194:197], v[124:127]
	v_mfma_f32_16x16x32_bf16 v[128:131], v[140:143], v[198:201], v[128:131]
	v_mfma_f32_16x16x32_bf16 v[120:123], v[140:143], v[226:229], v[120:123]
	v_mfma_f32_16x16x32_bf16 v[104:107], v[140:143], v[234:237], v[104:107]
	v_mfma_f32_16x16x32_bf16 v[86:89], v[140:143], v[242:245], v[86:89]
	v_mfma_f32_16x16x32_bf16 v[78:81], v[148:151], v[242:245], v[78:81]
	v_mfma_f32_16x16x32_bf16 v[94:97], v[148:151], v[234:237], v[94:97]
	v_mfma_f32_16x16x32_bf16 v[112:115], v[148:151], v[226:229], v[112:115]
	v_mfma_f32_16x16x32_bf16 v[124:127], v[148:151], v[198:201], v[124:127]
	s_setprio 0
	s_setprio 1
	v_mfma_f32_16x16x32_bf16 v[116:119], v[164:167], v[194:197], v[116:119]
	v_mfma_f32_16x16x32_bf16 v[100:103], v[164:167], v[222:225], v[100:103]
	v_mfma_f32_16x16x32_bf16 v[82:85], v[164:167], v[230:233], v[82:85]
	v_mfma_f32_16x16x32_bf16 v[70:73], v[164:167], v[238:241], v[70:73]
	v_mfma_f32_16x16x32_bf16 v[66:69], v[186:189], v[238:241], v[66:69]
	v_mfma_f32_16x16x32_bf16 v[74:77], v[186:189], v[230:233], v[74:77]
	v_mfma_f32_16x16x32_bf16 v[90:93], v[186:189], v[222:225], v[90:93]
	v_mfma_f32_16x16x32_bf16 v[108:111], v[186:189], v[194:197], v[108:111]
	v_mfma_f32_16x16x32_bf16 v[116:119], v[182:185], v[198:201], v[116:119]
	v_mfma_f32_16x16x32_bf16 v[100:103], v[182:185], v[226:229], v[100:103]
	v_mfma_f32_16x16x32_bf16 v[82:85], v[182:185], v[234:237], v[82:85]
	v_mfma_f32_16x16x32_bf16 v[70:73], v[182:185], v[242:245], v[70:73]
	v_mfma_f32_16x16x32_bf16 v[66:69], v[190:193], v[242:245], v[66:69]
	v_mfma_f32_16x16x32_bf16 v[74:77], v[190:193], v[234:237], v[74:77]
	v_mfma_f32_16x16x32_bf16 v[90:93], v[190:193], v[226:229], v[90:93]
	v_mfma_f32_16x16x32_bf16 v[108:111], v[190:193], v[198:201], v[108:111]
	s_setprio 0
	s_barrier
; #define PG8_STAGE(bufoff, gbase, voff) do { _Pragma("unroll") for (int _i = 0; _i < 2; ++_i) \
;         __builtin_amdgcn_global_load_lds((const unsigned*)((const char*)(gbase) + (voff)[_i]), (PG8_LAS unsigned*)(lds + (bufoff) + ldsw + _i * 8192), 16, 0, AUX_A); } while (0)
; #define PG8_STAGEB(bufoff, gbase, voff) do { _Pragma("unroll") for (int _i = 0; _i < 2; ++_i) \
;         __builtin_amdgcn_global_load_lds((const unsigned*)((const char*)(gbase) + (voff)[_i]), (PG8_LAS unsigned*)(lds + (bufoff) + ldsw + _i * 8192), 16, 0, AUX_B); } while (0)
; #define PG8_LDA(dst, b, h) do { _Pragma("unroll") for (int m = 0; m < 4; ++m) _Pragma("unroll") for (int k = 0; k < 2; ++k) dst[m][k] = *(const PG8_LAS bf16x8*)(lds + PG8_SA(b, h) + aoff + m * 2048 + k * 1024); } while (0)
; #define PG8_MMA(ai, bj, At, Bt) do { __builtin_amdgcn_s_setprio(1); _Pragma("unroll") for (int m = 0; m < 4; ++m) _Pragma("unroll") for (int n = 0; n < 2; ++n) _Pragma("unroll") for (int k = 0; k < 2; ++k) \
;         acc[ai][bj][m][n] = __builtin_amdgcn_mfma_f32_16x16x32_bf16(Bt[n][k], At[m][k], acc[ai][bj][m][n], 0, 0, 0); __builtin_amdgcn_s_setprio(0); } while (0)
; #define PG8_WAIT_V(n) asm volatile("s_waitcnt vmcnt(" #n ")" ::: "memory")
; #define PG8_WAIT_L(n) asm volatile("s_waitcnt lgkmcnt(" #n ")" ::: "memory")
; #define PG8_BAR __builtin_amdgcn_s_barrier()
; #define PG8_SCHED __builtin_amdgcn_sched_barrier(0)
; template <class Epi, class Sched, bool ALIGN_EPI = false, bool SP2 = false>
; __device__ __forceinline__ void gemm_phase(PG8_LAS unsigned char* lds, const Gemm g, const Sched& S, const Epi& E) {
;     ...
;         for (int t = 0; t < nt; t += 2) {
;     ...
;             PG8_LDA(At, 1, 1); PG8_STAGEB(PG8_SB(1, 0), b3, voffB); PG8_STAGEB(PG8_SB(1, 1), b3 + hstep, voffB); PG8_STAGE(PG8_SA(1, 0), a3, voffA);
;             PG8_WAIT_V(8); PG8_WAIT_L(0); PG8_BAR; PG8_MMA(1, 0, At, B0); PG8_MMA(1, 1, At, B1); PG8_BAR; PG8_SCHED;
	s_add_i32 s0, s2, s49
	v_lshl_add_u64 v[168:169], v[168:169], 0, s[76:77]
	s_mov_b32 m0, s0
	ds_read_b128 v[194:197], v181 offset:49152
	ds_read_b128 v[198:201], v181 offset:50176
	ds_read_b128 v[222:225], v181 offset:51200
	ds_read_b128 v[226:229], v181 offset:52224
	ds_read_b128 v[230:233], v181 offset:53248
	ds_read_b128 v[234:237], v181 offset:54272
	ds_read_b128 v[238:241], v181 offset:55296
	ds_read_b128 v[242:245], v181 offset:56320
	global_load_lds_dwordx4 v[168:169], off
	s_add_i32 m0, s0, 0x2000
	s_add_u32 s0, s36, 0x80080
	v_lshl_add_u64 v[168:169], v[172:173], 0, s[76:77]
	s_addc_u32 s1, s37, 0
	s_add_i32 s2, s15, s49
	global_load_lds_dwordx4 v[168:169], off
	v_lshl_add_u64 v[168:169], s[0:1], 0, v[156:157]
	s_mov_b32 m0, s2
	s_nop 0
	global_load_lds_dwordx4 v[168:169], off
	v_lshl_add_u64 v[168:169], s[0:1], 0, v[152:153]
	s_add_i32 m0, s2, 0x2000
	s_nop 0
	global_load_lds_dwordx4 v[168:169], off
	v_lshl_add_u64 v[168:169], v[202:203], 0, s[76:77]
	s_mov_b32 m0, s59
	s_nop 0
	global_load_lds_dwordx4 v[168:169], off
	v_lshl_add_u64 v[168:169], v[212:213], 0, s[76:77]
	s_mov_b32 m0, s60
	s_nop 0
	global_load_lds_dwordx4 v[168:169], off
	s_waitcnt vmcnt(8)
	s_waitcnt lgkmcnt(0)
	s_barrier
	s_setprio 1
	s_waitcnt lgkmcnt(0)
	v_mfma_f32_16x16x32_bf16 v[62:65], v[136:139], v[194:197], v[62:65]
	v_mfma_f32_16x16x32_bf16 v[54:57], v[136:139], v[222:225], v[54:57]
	v_mfma_f32_16x16x32_bf16 v[38:41], v[136:139], v[230:233], v[38:41]
	v_mfma_f32_16x16x32_bf16 v[22:25], v[136:139], v[238:241], v[22:25]
	v_mfma_f32_16x16x32_bf16 v[14:17], v[144:147], v[238:241], v[14:17]
	v_mfma_f32_16x16x32_bf16 v[30:33], v[144:147], v[230:233], v[30:33]
	v_mfma_f32_16x16x32_bf16 v[46:49], v[144:147], v[222:225], v[46:49]
	v_mfma_f32_16x16x32_bf16 v[58:61], v[144:147], v[194:197], v[58:61]
	v_mfma_f32_16x16x32_bf16 v[62:65], v[140:143], v[198:201], v[62:65]
	v_mfma_f32_16x16x32_bf16 v[54:57], v[140:143], v[226:229], v[54:57]
	v_mfma_f32_16x16x32_bf16 v[38:41], v[140:143], v[234:237], v[38:41]
	v_mfma_f32_16x16x32_bf16 v[22:25], v[140:143], v[242:245], v[22:25]
	v_mfma_f32_16x16x32_bf16 v[14:17], v[148:151], v[242:245], v[14:17]
	v_mfma_f32_16x16x32_bf16 v[30:33], v[148:151], v[234:237], v[30:33]
	v_mfma_f32_16x16x32_bf16 v[46:49], v[148:151], v[226:229], v[46:49]
	v_mfma_f32_16x16x32_bf16 v[58:61], v[148:151], v[198:201], v[58:61]
	s_setprio 0
	s_setprio 1
	v_mfma_f32_16x16x32_bf16 v[50:53], v[164:167], v[194:197], v[50:53]
	v_mfma_f32_16x16x32_bf16 v[34:37], v[164:167], v[222:225], v[34:37]
	v_mfma_f32_16x16x32_bf16 v[18:21], v[164:167], v[230:233], v[18:21]
	v_mfma_f32_16x16x32_bf16 v[6:9], v[164:167], v[238:241], v[6:9]
	v_mfma_f32_16x16x32_bf16 v[2:5], v[186:189], v[238:241], v[2:5]
	v_mfma_f32_16x16x32_bf16 v[10:13], v[186:189], v[230:233], v[10:13]
	v_mfma_f32_16x16x32_bf16 v[26:29], v[186:189], v[222:225], v[26:29]
	v_mfma_f32_16x16x32_bf16 v[42:45], v[186:189], v[194:197], v[42:45]
	v_mfma_f32_16x16x32_bf16 v[50:53], v[182:185], v[198:201], v[50:53]
	v_mfma_f32_16x16x32_bf16 v[34:37], v[182:185], v[226:229], v[34:37]
	v_mfma_f32_16x16x32_bf16 v[18:21], v[182:185], v[234:237], v[18:21]
	v_mfma_f32_16x16x32_bf16 v[6:9], v[182:185], v[242:245], v[6:9]
	v_mfma_f32_16x16x32_bf16 v[2:5], v[190:193], v[242:245], v[2:5]
	v_mfma_f32_16x16x32_bf16 v[10:13], v[190:193], v[234:237], v[10:13]
	v_mfma_f32_16x16x32_bf16 v[26:29], v[190:193], v[226:229], v[26:29]
	v_mfma_f32_16x16x32_bf16 v[42:45], v[190:193], v[198:201], v[42:45]
	s_setprio 0
	s_barrier
	s_add_i32 s0, s13, 2
	v_lshl_add_u64 v[132:133], v[132:133], 0, s[86:87]
	v_lshl_add_u64 v[134:135], v[134:135], 0, s[86:87]
	s_cmp_ge_i32 s13, s71
	s_mov_b32 s13, s0
	s_cbranch_scc0 .LBB0_1308
	s_and_b64 vcc, exec, s[8:9]
	s_cbranch_vccz .LBB0_1311
	s_barrier

; #define PG8_STAGE(bufoff, gbase, voff) do { _Pragma("unroll") for (int _i = 0; _i < 2; ++_i) \
;         __builtin_amdgcn_global_load_lds((const unsigned*)((const char*)(gbase) + (voff)[_i]), (PG8_LAS unsigned*)(lds + (bufoff) + ldsw + _i * 8192), 16, 0, AUX_A); } while (0)
; #define PG8_STAGEB(bufoff, gbase, voff) do { _Pragma("unroll") for (int _i = 0; _i < 2; ++_i) \
;         __builtin_amdgcn_global_load_lds((const unsigned*)((const char*)(gbase) + (voff)[_i]), (PG8_LAS unsigned*)(lds + (bufoff) + ldsw + _i * 8192), 16, 0, AUX_B); } while (0)
; #define PG8_LDA(dst, b, h) do { _Pragma("unroll") for (int m = 0; m < 4; ++m) _Pragma("unroll") for (int k = 0; k < 2; ++k) dst[m][k] = *(const PG8_LAS bf16x8*)(lds + PG8_SA(b, h) + aoff + m * 2048 + k * 1024); } while (0)
; #define PG8_LDB(dst, b, h) do { _Pragma("unroll") for (int n = 0; n < 2; ++n) _Pragma("unroll") for (int k = 0; k < 2; ++k) dst[n][k] = *(const PG8_LAS bf16x8*)(lds + PG8_SB(b, h) + boff + n * 2048 + k * 1024); } while (0)
; #define PG8_WAIT_V(n) asm volatile("s_waitcnt vmcnt(" #n ")" ::: "memory")
; #define PG8_WAIT_L(n) asm volatile("s_waitcnt lgkmcnt(" #n ")" ::: "memory")
; #define PG8_BAR __builtin_amdgcn_s_barrier()
; #define PG8_SCHED __builtin_amdgcn_sched_barrier(0)
; template <class Epi, class Sched, bool ALIGN_EPI = false, bool SP2 = false>
; __device__ __forceinline__ void gemm_phase(PG8_LAS unsigned char* lds, const Gemm g, const Sched& S, const Epi& E) {
;     ...
;         for (int t = 0; t < nt; t += 2) {
;             const bool last = (t == nt - 2);
;             const char* a1 = PG8_KP(cA, t + 1, rot, nt);
;             const char* a2 = last ? nAr : PG8_KP(cA, t + 2, rot, nt); const char* b2 = last ? nBr : PG8_KP(cB, t + 2, rot, nt);
;             const char* a3 = a2 + kstep; const char* b3 = b2 + kstep;
;             if (last && has_next) S.a_ready(nxt);
;             if constexpr (SP2) {
;             PG8_LDB(B0, 0, 0); PG8_LDB(B1, 0, 1); PG8_SCHED; PG8_LDA(At, 0, 0); PG8_STAGE(PG8_SA(1, 1), a1 + hstep, voffA);
;             PG8_WAIT_V(8); PG8_WAIT_L(0); PG8_BAR; PG8_MMA(0, 0, At, B0); PG8_MMA(0, 1, At, B1); PG8_BAR; PG8_SCHED;
;             PG8_LDA(At, 0, 1); PG8_STAGEB(PG8_SB(0, 0), b2, voffB); PG8_STAGEB(PG8_SB(0, 1), b2 + hstep, voffB); PG8_STAGE(PG8_SA(0, 0), a2, voffA);
.LBB0_1458:
	s_add_i32 s30, s29, 2
	s_cmp_lt_u32 s29, 30
	s_cselect_b32 s0, 0, 0xffffffe0
	s_add_i32 s0, s30, s0
	s_ashr_i32 s1, s0, 31
	s_lshl_b64 s[0:1], s[0:1], 7
	s_add_u32 s2, s40, s0
	s_addc_u32 s31, s41, s1
	s_add_u32 s0, s34, s0
	s_addc_u32 s1, s35, s1
	s_cmp_eq_u32 s29, 30
	s_cselect_b32 s45, s13, s31
	s_cselect_b32 s44, s15, s2
	s_cselect_b32 s49, s71, s1
	s_cselect_b32 s48, s75, s0
	s_add_i32 s2, 0, 0x10000
	s_add_i32 s78, s2, s56
	s_add_i32 s31, 0, 0x14000
	s_add_i32 m0, s57, 0xc000
	s_add_i32 s47, s57, 0xe000
	s_add_i32 s81, s78, 0x2000
	s_add_u32 s50, s48, 0x80000
	s_addc_u32 s51, s49, 0
	s_add_i32 s82, s31, s56
	v_add_u32_e32 v162, s2, v99
	v_add_u32_e32 v166, s31, v99
	s_add_i32 s83, s82, 0x2000
	s_add_i32 s84, 0, 0x18000
	s_add_i32 s88, 0, 0x1c000
	ds_read_b128 v[150:153], v162
	ds_read_b128 v[154:157], v162 offset:1024
	ds_read_b128 v[158:161], v162 offset:2048
	ds_read_b128 v[162:165], v162 offset:3072
	ds_read_b128 v[180:183], v166
	ds_read_b128 v[184:187], v166 offset:1024
	ds_read_b128 v[188:191], v166 offset:2048
	ds_read_b128 v[192:195], v166 offset:3072
	s_add_u32 s42, s44, 0x80000
	s_addc_u32 s43, s45, 0
	s_add_i32 s1, s84, s56
	s_add_i32 s0, s1, 0x2000
	s_add_u32 s36, s48, 0x80080
	s_addc_u32 s37, s49, 0
	s_add_i32 s46, s88, s56
	s_add_i32 s31, s46, 0x2000
	s_cmp_gt_u32 s29, 29
	ds_read_b128 v[196:199], v149
	ds_read_b128 v[200:203], v149 offset:1024
	ds_read_b128 v[222:225], v149 offset:2048
	ds_read_b128 v[226:229], v149 offset:3072
	ds_read_b128 v[230:233], v149 offset:4096
	ds_read_b128 v[234:237], v149 offset:5120
	ds_read_b128 v[238:241], v149 offset:6144
	ds_read_b128 v[242:245], v149 offset:7168
	global_load_lds_dwordx4 v[146:147], off
	s_mov_b32 m0, s47
	s_nop 0
	global_load_lds_dwordx4 v[144:145], off
	s_waitcnt vmcnt(8)
	s_waitcnt lgkmcnt(0)
	s_barrier
	s_setprio 1
	s_waitcnt lgkmcnt(0)
	v_mfma_f32_16x16x32_bf16 v[128:131], v[150:153], v[196:199], v[128:131]
	v_mfma_f32_16x16x32_bf16 v[112:115], v[150:153], v[222:225], v[112:115]
	v_mfma_f32_16x16x32_bf16 v[94:97], v[150:153], v[230:233], v[94:97]
	v_mfma_f32_16x16x32_bf16 v[78:81], v[150:153], v[238:241], v[78:81]
	v_mfma_f32_16x16x32_bf16 v[70:73], v[158:161], v[238:241], v[70:73]
	v_mfma_f32_16x16x32_bf16 v[86:89], v[158:161], v[230:233], v[86:89]
	v_mfma_f32_16x16x32_bf16 v[104:107], v[158:161], v[222:225], v[104:107]
	v_mfma_f32_16x16x32_bf16 v[120:123], v[158:161], v[196:199], v[120:123]
	v_mfma_f32_16x16x32_bf16 v[128:131], v[154:157], v[200:203], v[128:131]
	v_mfma_f32_16x16x32_bf16 v[112:115], v[154:157], v[226:229], v[112:115]
	v_mfma_f32_16x16x32_bf16 v[94:97], v[154:157], v[234:237], v[94:97]
	v_mfma_f32_16x16x32_bf16 v[78:81], v[154:157], v[242:245], v[78:81]
	v_mfma_f32_16x16x32_bf16 v[70:73], v[162:165], v[242:245], v[70:73]
	v_mfma_f32_16x16x32_bf16 v[86:89], v[162:165], v[234:237], v[86:89]
	v_mfma_f32_16x16x32_bf16 v[104:107], v[162:165], v[226:229], v[104:107]
	v_mfma_f32_16x16x32_bf16 v[120:123], v[162:165], v[200:203], v[120:123]
	s_setprio 0
	s_setprio 1
	v_mfma_f32_16x16x32_bf16 v[124:127], v[180:183], v[196:199], v[124:127]
	v_mfma_f32_16x16x32_bf16 v[108:111], v[180:183], v[222:225], v[108:111]
	v_mfma_f32_16x16x32_bf16 v[90:93], v[180:183], v[230:233], v[90:93]
	v_mfma_f32_16x16x32_bf16 v[74:77], v[180:183], v[238:241], v[74:77]
	v_mfma_f32_16x16x32_bf16 v[66:69], v[188:191], v[238:241], v[66:69]
	v_mfma_f32_16x16x32_bf16 v[82:85], v[188:191], v[230:233], v[82:85]
	v_mfma_f32_16x16x32_bf16 v[100:103], v[188:191], v[222:225], v[100:103]
	v_mfma_f32_16x16x32_bf16 v[116:119], v[188:191], v[196:199], v[116:119]
	v_mfma_f32_16x16x32_bf16 v[124:127], v[184:187], v[200:203], v[124:127]
	v_mfma_f32_16x16x32_bf16 v[108:111], v[184:187], v[226:229], v[108:111]
	v_mfma_f32_16x16x32_bf16 v[90:93], v[184:187], v[234:237], v[90:93]
	v_mfma_f32_16x16x32_bf16 v[74:77], v[184:187], v[242:245], v[74:77]
	v_mfma_f32_16x16x32_bf16 v[66:69], v[192:195], v[242:245], v[66:69]
	v_mfma_f32_16x16x32_bf16 v[82:85], v[192:195], v[234:237], v[82:85]
	v_mfma_f32_16x16x32_bf16 v[100:103], v[192:195], v[226:229], v[100:103]
	v_mfma_f32_16x16x32_bf16 v[116:119], v[192:195], v[200:203], v[116:119]
	s_setprio 0
	s_barrier
	s_mov_b32 m0, s78
	v_lshl_add_u64 v[166:167], s[48:49], 0, v[136:137]
	ds_read_b128 v[196:199], v149 offset:16384
	ds_read_b128 v[200:203], v149 offset:17408
	ds_read_b128 v[222:225], v149 offset:18432
	ds_read_b128 v[226:229], v149 offset:19456
	ds_read_b128 v[230:233], v149 offset:20480
	ds_read_b128 v[234:237], v149 offset:21504
	ds_read_b128 v[238:241], v149 offset:22528
	ds_read_b128 v[242:245], v149 offset:23552
	global_load_lds_dwordx4 v[166:167], off
	v_lshl_add_u64 v[168:169], s[48:49], 0, v[132:133]
	s_mov_b32 m0, s81
	v_lshl_add_u64 v[172:173], s[50:51], 0, v[136:137]
	global_load_lds_dwordx4 v[168:169], off
	s_mov_b32 m0, s82
	v_lshl_add_u64 v[212:213], s[44:45], 0, v[134:135]
	global_load_lds_dwordx4 v[172:173], off
	v_lshl_add_u64 v[172:173], s[50:51], 0, v[132:133]
	s_mov_b32 m0, s83
	s_nop 0
	global_load_lds_dwordx4 v[172:173], off
	v_lshl_add_u64 v[172:173], s[44:45], 0, v[138:139]
	s_mov_b32 m0, s57
	s_nop 0
	global_load_lds_dwordx4 v[172:173], off
	s_mov_b32 m0, s58
	s_nop 0
	global_load_lds_dwordx4 v[212:213], off
	s_waitcnt vmcnt(8)
	s_waitcnt lgkmcnt(0)
	s_barrier
; #define PG8_STAGE(bufoff, gbase, voff) do { _Pragma("unroll") for (int _i = 0; _i < 2; ++_i) \
;         __builtin_amdgcn_global_load_lds((const unsigned*)((const char*)(gbase) + (voff)[_i]), (PG8_LAS unsigned*)(lds + (bufoff) + ldsw + _i * 8192), 16, 0, AUX_A); } while (0)
; #define PG8_LDA(dst, b, h) do { _Pragma("unroll") for (int m = 0; m < 4; ++m) _Pragma("unroll") for (int k = 0; k < 2; ++k) dst[m][k] = *(const PG8_LAS bf16x8*)(lds + PG8_SA(b, h) + aoff + m * 2048 + k * 1024); } while (0)
; #define PG8_LDB(dst, b, h) do { _Pragma("unroll") for (int n = 0; n < 2; ++n) _Pragma("unroll") for (int k = 0; k < 2; ++k) dst[n][k] = *(const PG8_LAS bf16x8*)(lds + PG8_SB(b, h) + boff + n * 2048 + k * 1024); } while (0)
; #define PG8_MMA(ai, bj, At, Bt) do { __builtin_amdgcn_s_setprio(1); _Pragma("unroll") for (int m = 0; m < 4; ++m) _Pragma("unroll") for (int n = 0; n < 2; ++n) _Pragma("unroll") for (int k = 0; k < 2; ++k) \
;         acc[ai][bj][m][n] = __builtin_amdgcn_mfma_f32_16x16x32_bf16(Bt[n][k], At[m][k], acc[ai][bj][m][n], 0, 0, 0); __builtin_amdgcn_s_setprio(0); } while (0)
; #define PG8_WAIT_V(n) asm volatile("s_waitcnt vmcnt(" #n ")" ::: "memory")
; #define PG8_WAIT_L(n) asm volatile("s_waitcnt lgkmcnt(" #n ")" ::: "memory")
; #define PG8_BAR __builtin_amdgcn_s_barrier()
; #define PG8_SCHED __builtin_amdgcn_sched_barrier(0)
; template <class Epi, class Sched, bool ALIGN_EPI = false, bool SP2 = false>
; __device__ __forceinline__ void gemm_phase(PG8_LAS unsigned char* lds, const Gemm g, const Sched& S, const Epi& E) {
;     ...
;             PG8_WAIT_V(8); PG8_WAIT_L(0); PG8_BAR; PG8_MMA(1, 0, At, B0); PG8_MMA(1, 1, At, B1); PG8_BAR; PG8_SCHED;
;             PG8_LDB(B0, 1, 0); PG8_LDB(B1, 1, 1); PG8_SCHED; PG8_LDA(At, 1, 0); PG8_STAGE(PG8_SA(0, 1), a2 + hstep, voffA);
;             PG8_WAIT_V(8); PG8_WAIT_L(0); PG8_BAR; PG8_MMA(0, 0, At, B0); PG8_MMA(0, 1, At, B1); PG8_BAR; PG8_SCHED;
	s_setprio 1
	s_waitcnt lgkmcnt(0)
	v_mfma_f32_16x16x32_bf16 v[62:65], v[150:153], v[196:199], v[62:65]
	v_mfma_f32_16x16x32_bf16 v[46:49], v[150:153], v[222:225], v[46:49]
	v_mfma_f32_16x16x32_bf16 v[30:33], v[150:153], v[230:233], v[30:33]
	v_mfma_f32_16x16x32_bf16 v[14:17], v[150:153], v[238:241], v[14:17]
	v_mfma_f32_16x16x32_bf16 v[6:9], v[158:161], v[238:241], v[6:9]
	v_mfma_f32_16x16x32_bf16 v[22:25], v[158:161], v[230:233], v[22:25]
	v_mfma_f32_16x16x32_bf16 v[38:41], v[158:161], v[222:225], v[38:41]
	v_mfma_f32_16x16x32_bf16 v[54:57], v[158:161], v[196:199], v[54:57]
	v_mfma_f32_16x16x32_bf16 v[62:65], v[154:157], v[200:203], v[62:65]
	v_mfma_f32_16x16x32_bf16 v[46:49], v[154:157], v[226:229], v[46:49]
	v_mfma_f32_16x16x32_bf16 v[30:33], v[154:157], v[234:237], v[30:33]
	v_mfma_f32_16x16x32_bf16 v[14:17], v[154:157], v[242:245], v[14:17]
	v_mfma_f32_16x16x32_bf16 v[6:9], v[162:165], v[242:245], v[6:9]
	v_mfma_f32_16x16x32_bf16 v[22:25], v[162:165], v[234:237], v[22:25]
	v_mfma_f32_16x16x32_bf16 v[38:41], v[162:165], v[226:229], v[38:41]
	v_mfma_f32_16x16x32_bf16 v[54:57], v[162:165], v[200:203], v[54:57]
	s_setprio 0
	s_setprio 1
	v_mfma_f32_16x16x32_bf16 v[58:61], v[180:183], v[196:199], v[58:61]
	v_mfma_f32_16x16x32_bf16 v[42:45], v[180:183], v[222:225], v[42:45]
	v_mfma_f32_16x16x32_bf16 v[26:29], v[180:183], v[230:233], v[26:29]
	v_mfma_f32_16x16x32_bf16 v[10:13], v[180:183], v[238:241], v[10:13]
	v_mfma_f32_16x16x32_bf16 v[2:5], v[188:191], v[238:241], v[2:5]
	v_mfma_f32_16x16x32_bf16 v[18:21], v[188:191], v[230:233], v[18:21]
	v_mfma_f32_16x16x32_bf16 v[34:37], v[188:191], v[222:225], v[34:37]
	v_mfma_f32_16x16x32_bf16 v[50:53], v[188:191], v[196:199], v[50:53]
	v_mfma_f32_16x16x32_bf16 v[58:61], v[184:187], v[200:203], v[58:61]
	v_mfma_f32_16x16x32_bf16 v[42:45], v[184:187], v[226:229], v[42:45]
	v_mfma_f32_16x16x32_bf16 v[26:29], v[184:187], v[234:237], v[26:29]
	v_mfma_f32_16x16x32_bf16 v[10:13], v[184:187], v[242:245], v[10:13]
	v_mfma_f32_16x16x32_bf16 v[2:5], v[192:195], v[242:245], v[2:5]
	v_mfma_f32_16x16x32_bf16 v[18:21], v[192:195], v[234:237], v[18:21]
	v_mfma_f32_16x16x32_bf16 v[34:37], v[192:195], v[226:229], v[34:37]
	v_mfma_f32_16x16x32_bf16 v[50:53], v[192:195], v[200:203], v[50:53]
	s_setprio 0
	s_barrier
	v_add_u32_e32 v162, s84, v99
	v_add_u32_e32 v192, s88, v99
	ds_read_b128 v[150:153], v162
	ds_read_b128 v[154:157], v162 offset:1024
	ds_read_b128 v[158:161], v162 offset:2048
	ds_read_b128 v[162:165], v162 offset:3072
	ds_read_b128 v[180:183], v192
	ds_read_b128 v[184:187], v192 offset:1024
	ds_read_b128 v[188:191], v192 offset:2048
	ds_read_b128 v[192:195], v192 offset:3072
	s_mov_b32 m0, s59
	v_lshl_add_u64 v[246:247], s[42:43], 0, v[138:139]
	ds_read_b128 v[196:199], v149 offset:32768
	ds_read_b128 v[200:203], v149 offset:33792
	ds_read_b128 v[222:225], v149 offset:34816
	ds_read_b128 v[226:229], v149 offset:35840
	ds_read_b128 v[230:233], v149 offset:36864
	ds_read_b128 v[234:237], v149 offset:37888
	ds_read_b128 v[238:241], v149 offset:38912
	ds_read_b128 v[242:245], v149 offset:39936
	global_load_lds_dwordx4 v[246:247], off
	v_lshl_add_u64 v[246:247], s[42:43], 0, v[134:135]
	s_mov_b32 m0, s60
	s_nop 0
	global_load_lds_dwordx4 v[246:247], off
	s_waitcnt vmcnt(8)
	s_waitcnt lgkmcnt(0)
	s_barrier
	s_setprio 1
	s_waitcnt lgkmcnt(0)
	v_mfma_f32_16x16x32_bf16 v[128:131], v[150:153], v[196:199], v[128:131]
	v_mfma_f32_16x16x32_bf16 v[112:115], v[150:153], v[222:225], v[112:115]
	v_mfma_f32_16x16x32_bf16 v[94:97], v[150:153], v[230:233], v[94:97]
	v_mfma_f32_16x16x32_bf16 v[78:81], v[150:153], v[238:241], v[78:81]
	v_mfma_f32_16x16x32_bf16 v[70:73], v[158:161], v[238:241], v[70:73]
	v_mfma_f32_16x16x32_bf16 v[86:89], v[158:161], v[230:233], v[86:89]
	v_mfma_f32_16x16x32_bf16 v[104:107], v[158:161], v[222:225], v[104:107]
	v_mfma_f32_16x16x32_bf16 v[120:123], v[158:161], v[196:199], v[120:123]
	v_mfma_f32_16x16x32_bf16 v[128:131], v[154:157], v[200:203], v[128:131]
	v_mfma_f32_16x16x32_bf16 v[112:115], v[154:157], v[226:229], v[112:115]
	v_mfma_f32_16x16x32_bf16 v[94:97], v[154:157], v[234:237], v[94:97]
	v_mfma_f32_16x16x32_bf16 v[78:81], v[154:157], v[242:245], v[78:81]
	v_mfma_f32_16x16x32_bf16 v[70:73], v[162:165], v[242:245], v[70:73]
	v_mfma_f32_16x16x32_bf16 v[86:89], v[162:165], v[234:237], v[86:89]
	v_mfma_f32_16x16x32_bf16 v[104:107], v[162:165], v[226:229], v[104:107]
	v_mfma_f32_16x16x32_bf16 v[120:123], v[162:165], v[200:203], v[120:123]
	s_setprio 0
	s_setprio 1
	v_mfma_f32_16x16x32_bf16 v[124:127], v[180:183], v[196:199], v[124:127]
	v_mfma_f32_16x16x32_bf16 v[108:111], v[180:183], v[222:225], v[108:111]
	v_mfma_f32_16x16x32_bf16 v[90:93], v[180:183], v[230:233], v[90:93]
	v_mfma_f32_16x16x32_bf16 v[74:77], v[180:183], v[238:241], v[74:77]
	v_mfma_f32_16x16x32_bf16 v[66:69], v[188:191], v[238:241], v[66:69]
	v_mfma_f32_16x16x32_bf16 v[82:85], v[188:191], v[230:233], v[82:85]
	v_mfma_f32_16x16x32_bf16 v[100:103], v[188:191], v[222:225], v[100:103]
	v_mfma_f32_16x16x32_bf16 v[116:119], v[188:191], v[196:199], v[116:119]
	v_mfma_f32_16x16x32_bf16 v[124:127], v[184:187], v[200:203], v[124:127]
	v_mfma_f32_16x16x32_bf16 v[108:111], v[184:187], v[226:229], v[108:111]
	v_mfma_f32_16x16x32_bf16 v[90:93], v[184:187], v[234:237], v[90:93]
	v_mfma_f32_16x16x32_bf16 v[74:77], v[184:187], v[242:245], v[74:77]
	v_mfma_f32_16x16x32_bf16 v[66:69], v[192:195], v[242:245], v[66:69]
	v_mfma_f32_16x16x32_bf16 v[82:85], v[192:195], v[234:237], v[82:85]
	v_mfma_f32_16x16x32_bf16 v[100:103], v[192:195], v[226:229], v[100:103]
	v_mfma_f32_16x16x32_bf16 v[116:119], v[192:195], v[200:203], v[116:119]
	s_setprio 0
	s_barrier
; #define PG8_STAGE(bufoff, gbase, voff) do { _Pragma("unroll") for (int _i = 0; _i < 2; ++_i) \
;         __builtin_amdgcn_global_load_lds((const unsigned*)((const char*)(gbase) + (voff)[_i]), (PG8_LAS unsigned*)(lds + (bufoff) + ldsw + _i * 8192), 16, 0, AUX_A); } while (0)
; #define PG8_STAGEB(bufoff, gbase, voff) do { _Pragma("unroll") for (int _i = 0; _i < 2; ++_i) \
;         __builtin_amdgcn_global_load_lds((const unsigned*)((const char*)(gbase) + (voff)[_i]), (PG8_LAS unsigned*)(lds + (bufoff) + ldsw + _i * 8192), 16, 0, AUX_B); } while (0)
; #define PG8_LDA(dst, b, h) do { _Pragma("unroll") for (int m = 0; m < 4; ++m) _Pragma("unroll") for (int k = 0; k < 2; ++k) dst[m][k] = *(const PG8_LAS bf16x8*)(lds + PG8_SA(b, h) + aoff + m * 2048 + k * 1024); } while (0)
; #define PG8_MMA(ai, bj, At, Bt) do { __builtin_amdgcn_s_setprio(1); _Pragma("unroll") for (int m = 0; m < 4; ++m) _Pragma("unroll") for (int n = 0; n < 2; ++n) _Pragma("unroll") for (int k = 0; k < 2; ++k) \
;         acc[ai][bj][m][n] = __builtin_amdgcn_mfma_f32_16x16x32_bf16(Bt[n][k], At[m][k], acc[ai][bj][m][n], 0, 0, 0); __builtin_amdgcn_s_setprio(0); } while (0)
; #define PG8_WAIT_V(n) asm volatile("s_waitcnt vmcnt(" #n ")" ::: "memory")
; #define PG8_WAIT_L(n) asm volatile("s_waitcnt lgkmcnt(" #n ")" ::: "memory")
; #define PG8_BAR __builtin_amdgcn_s_barrier()
; #define PG8_SCHED __builtin_amdgcn_sched_barrier(0)
; template <class Epi, class Sched, bool ALIGN_EPI = false, bool SP2 = false>
; __device__ __forceinline__ void gemm_phase(PG8_LAS unsigned char* lds, const Gemm g, const Sched& S, const Epi& E) {
;     ...
;             PG8_LDA(At, 1, 1); PG8_STAGEB(PG8_SB(1, 0), b3, voffB); PG8_STAGEB(PG8_SB(1, 1), b3 + hstep, voffB); PG8_STAGE(PG8_SA(1, 0), a3, voffA);
;             PG8_WAIT_V(8); PG8_WAIT_L(0); PG8_BAR; PG8_MMA(1, 0, At, B0); PG8_MMA(1, 1, At, B1); PG8_BAR; PG8_SCHED;
;     ...
;         }
;         if constexpr (ALIGN_EPI) { if (wr == 0) PG8_BAR; }
	s_mov_b32 m0, s1
	v_lshl_add_u64 v[166:167], v[166:167], 0, s[76:77]
	ds_read_b128 v[196:199], v149 offset:49152
	ds_read_b128 v[200:203], v149 offset:50176
	ds_read_b128 v[222:225], v149 offset:51200
	ds_read_b128 v[226:229], v149 offset:52224
	ds_read_b128 v[230:233], v149 offset:53248
	ds_read_b128 v[234:237], v149 offset:54272
	ds_read_b128 v[238:241], v149 offset:55296
	ds_read_b128 v[242:245], v149 offset:56320
	global_load_lds_dwordx4 v[166:167], off
	v_lshl_add_u64 v[166:167], v[168:169], 0, s[76:77]
	s_mov_b32 m0, s0
	s_nop 0
	global_load_lds_dwordx4 v[166:167], off
	v_lshl_add_u64 v[166:167], s[36:37], 0, v[136:137]
	s_mov_b32 m0, s46
	s_nop 0
	global_load_lds_dwordx4 v[166:167], off
	v_lshl_add_u64 v[166:167], s[36:37], 0, v[132:133]
	s_mov_b32 m0, s31
	s_nop 0
	global_load_lds_dwordx4 v[166:167], off
	v_lshl_add_u64 v[166:167], v[172:173], 0, s[76:77]
	s_mov_b32 m0, s61
	s_nop 0
	global_load_lds_dwordx4 v[166:167], off
	v_lshl_add_u64 v[166:167], v[212:213], 0, s[76:77]
	s_mov_b32 m0, s62
	s_nop 0
	global_load_lds_dwordx4 v[166:167], off
	s_waitcnt vmcnt(8)
	s_waitcnt lgkmcnt(0)
	s_barrier
	s_setprio 1
	s_waitcnt lgkmcnt(0)
	v_mfma_f32_16x16x32_bf16 v[62:65], v[150:153], v[196:199], v[62:65]
	v_mfma_f32_16x16x32_bf16 v[46:49], v[150:153], v[222:225], v[46:49]
	v_mfma_f32_16x16x32_bf16 v[30:33], v[150:153], v[230:233], v[30:33]
	v_mfma_f32_16x16x32_bf16 v[14:17], v[150:153], v[238:241], v[14:17]
	v_mfma_f32_16x16x32_bf16 v[6:9], v[158:161], v[238:241], v[6:9]
	v_mfma_f32_16x16x32_bf16 v[22:25], v[158:161], v[230:233], v[22:25]
	v_mfma_f32_16x16x32_bf16 v[38:41], v[158:161], v[222:225], v[38:41]
	v_mfma_f32_16x16x32_bf16 v[54:57], v[158:161], v[196:199], v[54:57]
	v_mfma_f32_16x16x32_bf16 v[62:65], v[154:157], v[200:203], v[62:65]
	v_mfma_f32_16x16x32_bf16 v[46:49], v[154:157], v[226:229], v[46:49]
	v_mfma_f32_16x16x32_bf16 v[30:33], v[154:157], v[234:237], v[30:33]
	v_mfma_f32_16x16x32_bf16 v[14:17], v[154:157], v[242:245], v[14:17]
	v_mfma_f32_16x16x32_bf16 v[6:9], v[162:165], v[242:245], v[6:9]
	v_mfma_f32_16x16x32_bf16 v[22:25], v[162:165], v[234:237], v[22:25]
	v_mfma_f32_16x16x32_bf16 v[38:41], v[162:165], v[226:229], v[38:41]
	v_mfma_f32_16x16x32_bf16 v[54:57], v[162:165], v[200:203], v[54:57]
	s_setprio 0
	s_setprio 1
	v_mfma_f32_16x16x32_bf16 v[58:61], v[180:183], v[196:199], v[58:61]
	v_mfma_f32_16x16x32_bf16 v[42:45], v[180:183], v[222:225], v[42:45]
	v_mfma_f32_16x16x32_bf16 v[26:29], v[180:183], v[230:233], v[26:29]
	v_mfma_f32_16x16x32_bf16 v[10:13], v[180:183], v[238:241], v[10:13]
	v_mfma_f32_16x16x32_bf16 v[2:5], v[188:191], v[238:241], v[2:5]
	v_mfma_f32_16x16x32_bf16 v[18:21], v[188:191], v[230:233], v[18:21]
	v_mfma_f32_16x16x32_bf16 v[34:37], v[188:191], v[222:225], v[34:37]
	v_mfma_f32_16x16x32_bf16 v[50:53], v[188:191], v[196:199], v[50:53]
	v_mfma_f32_16x16x32_bf16 v[58:61], v[184:187], v[200:203], v[58:61]
	v_mfma_f32_16x16x32_bf16 v[42:45], v[184:187], v[226:229], v[42:45]
	v_mfma_f32_16x16x32_bf16 v[26:29], v[184:187], v[234:237], v[26:29]
	v_mfma_f32_16x16x32_bf16 v[10:13], v[184:187], v[242:245], v[10:13]
	v_mfma_f32_16x16x32_bf16 v[2:5], v[192:195], v[242:245], v[2:5]
	v_mfma_f32_16x16x32_bf16 v[18:21], v[192:195], v[234:237], v[18:21]
	v_mfma_f32_16x16x32_bf16 v[34:37], v[192:195], v[226:229], v[34:37]
	v_mfma_f32_16x16x32_bf16 v[50:53], v[192:195], v[200:203], v[50:53]
	s_setprio 0
	s_barrier
	v_lshl_add_u64 v[144:145], v[144:145], 0, s[86:87]
	v_lshl_add_u64 v[146:147], v[146:147], 0, s[86:87]
	s_mov_b32 s29, s30
	s_cbranch_scc0 .LBB0_1458
	s_and_b64 vcc, exec, s[10:11]
	s_cbranch_vccz .LBB0_1461
	s_barrier

; #define PG8_STAGE(bufoff, gbase, voff) do { _Pragma("unroll") for (int _i = 0; _i < 2; ++_i) \
;         __builtin_amdgcn_global_load_lds((const unsigned*)((const char*)(gbase) + (voff)[_i]), (PG8_LAS unsigned*)(lds + (bufoff) + ldsw + _i * 8192), 16, 0, AUX_A); } while (0)
; #define PG8_STAGEB(bufoff, gbase, voff) do { _Pragma("unroll") for (int _i = 0; _i < 2; ++_i) \
;         __builtin_amdgcn_global_load_lds((const unsigned*)((const char*)(gbase) + (voff)[_i]), (PG8_LAS unsigned*)(lds + (bufoff) + ldsw + _i * 8192), 16, 0, AUX_B); } while (0)
; #define PG8_LDA(dst, b, h) do { _Pragma("unroll") for (int m = 0; m < 4; ++m) _Pragma("unroll") for (int k = 0; k < 2; ++k) dst[m][k] = *(const PG8_LAS bf16x8*)(lds + PG8_SA(b, h) + aoff + m * 2048 + k * 1024); } while (0)
; #define PG8_LDB(dst, b, h) do { _Pragma("unroll") for (int n = 0; n < 2; ++n) _Pragma("unroll") for (int k = 0; k < 2; ++k) dst[n][k] = *(const PG8_LAS bf16x8*)(lds + PG8_SB(b, h) + boff + n * 2048 + k * 1024); } while (0)
; #define PG8_WAIT_V(n) asm volatile("s_waitcnt vmcnt(" #n ")" ::: "memory")
; #define PG8_WAIT_L(n) asm volatile("s_waitcnt lgkmcnt(" #n ")" ::: "memory")
; #define PG8_BAR __builtin_amdgcn_s_barrier()
; #define PG8_SCHED __builtin_amdgcn_sched_barrier(0)
; template <class Epi, class Sched, bool ALIGN_EPI = false, bool SP2 = false>
; __device__ __forceinline__ void gemm_phase(PG8_LAS unsigned char* lds, const Gemm g, const Sched& S, const Epi& E) {
;     ...
;         for (int t = 0; t < nt; t += 2) {
;             const bool last = (t == nt - 2);
;             const char* a1 = PG8_KP(cA, t + 1, rot, nt);
;             const char* a2 = last ? nAr : PG8_KP(cA, t + 2, rot, nt); const char* b2 = last ? nBr : PG8_KP(cB, t + 2, rot, nt);
;             const char* a3 = a2 + kstep; const char* b3 = b2 + kstep;
;             if (last && has_next) S.a_ready(nxt);
;             if constexpr (SP2) {
;             PG8_LDB(B0, 0, 0); PG8_LDB(B1, 0, 1); PG8_SCHED; PG8_LDA(At, 0, 0); PG8_STAGE(PG8_SA(1, 1), a1 + hstep, voffA);
;             PG8_WAIT_V(8); PG8_WAIT_L(0); PG8_BAR; PG8_MMA(0, 0, At, B0); PG8_MMA(0, 1, At, B1); PG8_BAR; PG8_SCHED;
;             PG8_LDA(At, 0, 1); PG8_STAGEB(PG8_SB(0, 0), b2, voffB); PG8_STAGEB(PG8_SB(0, 1), b2 + hstep, voffB); PG8_STAGE(PG8_SA(0, 0), a2, voffA);
.LBB0_1654:
	s_or_b32 s0, s15, 1
	s_cmp_ge_i32 s0, s82
	s_cselect_b32 s2, s82, 0
	s_add_i32 s15, s15, 2
	s_cmp_ge_i32 s15, s82
	s_cselect_b32 s0, s82, 0
	s_sub_i32 s0, s83, s0
	s_ashr_i32 s1, s0, 31
	s_lshl_b64 s[0:1], s[0:1], 7
	s_add_u32 s29, s38, s0
	s_addc_u32 s42, s39, s1
	s_add_u32 s0, s34, s0
	s_addc_u32 s1, s35, s1
	s_cmp_eq_u32 s82, s83
	s_cselect_b32 s45, s41, s42
	s_cselect_b32 s44, s40, s29
	s_cselect_b32 s43, s19, s1
	s_cselect_b32 s42, s18, s0
	s_add_i32 s29, 0, 0x10000
	s_add_i32 s46, 0, 0x14000
	v_add_u32_e32 v148, s29, v99
	v_add_u32_e32 v168, s46, v99
	ds_read_b128 v[136:139], v148
	ds_read_b128 v[140:143], v148 offset:1024
	ds_read_b128 v[144:147], v148 offset:2048
	ds_read_b128 v[148:151], v148 offset:3072
	ds_read_b128 v[152:155], v168
	ds_read_b128 v[180:183], v168 offset:1024
	ds_read_b128 v[184:187], v168 offset:2048
	ds_read_b128 v[190:193], v168 offset:3072
	v_mad_i64_i32 v[168:169], s[0:1], s2, v220, v[134:135]
	s_add_i32 m0, s50, 0xc000
	ds_read_b128 v[194:197], v189
	ds_read_b128 v[198:201], v189 offset:1024
	ds_read_b128 v[222:225], v189 offset:2048
	ds_read_b128 v[226:229], v189 offset:3072
	ds_read_b128 v[230:233], v189 offset:4096
	ds_read_b128 v[234:237], v189 offset:5120
	ds_read_b128 v[238:241], v189 offset:6144
	ds_read_b128 v[242:245], v189 offset:7168
	global_load_lds_dwordx4 v[168:169], off
	v_mad_i64_i32 v[168:169], s[0:1], s2, v220, v[132:133]
	s_add_i32 m0, s50, 0xe000
	s_nop 0
	global_load_lds_dwordx4 v[168:169], off
	s_waitcnt vmcnt(8)
	s_waitcnt lgkmcnt(0)
	s_barrier
	s_setprio 1
	s_waitcnt lgkmcnt(0)
	v_mfma_f32_16x16x32_bf16 v[128:131], v[136:139], v[194:197], v[128:131]
	v_mfma_f32_16x16x32_bf16 v[120:123], v[136:139], v[222:225], v[120:123]
	v_mfma_f32_16x16x32_bf16 v[104:107], v[136:139], v[230:233], v[104:107]
	v_mfma_f32_16x16x32_bf16 v[86:89], v[136:139], v[238:241], v[86:89]
	v_mfma_f32_16x16x32_bf16 v[78:81], v[144:147], v[238:241], v[78:81]
	v_mfma_f32_16x16x32_bf16 v[94:97], v[144:147], v[230:233], v[94:97]
	v_mfma_f32_16x16x32_bf16 v[112:115], v[144:147], v[222:225], v[112:115]
	v_mfma_f32_16x16x32_bf16 v[124:127], v[144:147], v[194:197], v[124:127]
	v_mfma_f32_16x16x32_bf16 v[128:131], v[140:143], v[198:201], v[128:131]
	v_mfma_f32_16x16x32_bf16 v[120:123], v[140:143], v[226:229], v[120:123]
	v_mfma_f32_16x16x32_bf16 v[104:107], v[140:143], v[234:237], v[104:107]
	v_mfma_f32_16x16x32_bf16 v[86:89], v[140:143], v[242:245], v[86:89]
	v_mfma_f32_16x16x32_bf16 v[78:81], v[148:151], v[242:245], v[78:81]
	v_mfma_f32_16x16x32_bf16 v[94:97], v[148:151], v[234:237], v[94:97]
	v_mfma_f32_16x16x32_bf16 v[112:115], v[148:151], v[226:229], v[112:115]
	v_mfma_f32_16x16x32_bf16 v[124:127], v[148:151], v[198:201], v[124:127]
	s_setprio 0
	s_setprio 1
	v_mfma_f32_16x16x32_bf16 v[116:119], v[152:155], v[194:197], v[116:119]
	v_mfma_f32_16x16x32_bf16 v[100:103], v[152:155], v[222:225], v[100:103]
	v_mfma_f32_16x16x32_bf16 v[82:85], v[152:155], v[230:233], v[82:85]
	v_mfma_f32_16x16x32_bf16 v[70:73], v[152:155], v[238:241], v[70:73]
	v_mfma_f32_16x16x32_bf16 v[66:69], v[184:187], v[238:241], v[66:69]
	v_mfma_f32_16x16x32_bf16 v[74:77], v[184:187], v[230:233], v[74:77]
	v_mfma_f32_16x16x32_bf16 v[90:93], v[184:187], v[222:225], v[90:93]
	v_mfma_f32_16x16x32_bf16 v[108:111], v[184:187], v[194:197], v[108:111]
	v_mfma_f32_16x16x32_bf16 v[116:119], v[180:183], v[198:201], v[116:119]
	v_mfma_f32_16x16x32_bf16 v[100:103], v[180:183], v[226:229], v[100:103]
	v_mfma_f32_16x16x32_bf16 v[82:85], v[180:183], v[234:237], v[82:85]
	v_mfma_f32_16x16x32_bf16 v[70:73], v[180:183], v[242:245], v[70:73]
	v_mfma_f32_16x16x32_bf16 v[66:69], v[190:193], v[242:245], v[66:69]
	v_mfma_f32_16x16x32_bf16 v[74:77], v[190:193], v[234:237], v[74:77]
	v_mfma_f32_16x16x32_bf16 v[90:93], v[190:193], v[226:229], v[90:93]
	v_mfma_f32_16x16x32_bf16 v[108:111], v[190:193], v[198:201], v[108:111]
	s_setprio 0
	s_barrier
	s_add_i32 s0, s29, s49
	v_lshl_add_u64 v[168:169], s[42:43], 0, v[160:161]
	s_mov_b32 m0, s0
	ds_read_b128 v[194:197], v189 offset:16384
	ds_read_b128 v[198:201], v189 offset:17408
	ds_read_b128 v[222:225], v189 offset:18432
	ds_read_b128 v[226:229], v189 offset:19456
	ds_read_b128 v[230:233], v189 offset:20480
	ds_read_b128 v[234:237], v189 offset:21504
	ds_read_b128 v[238:241], v189 offset:22528
	ds_read_b128 v[242:245], v189 offset:23552
	global_load_lds_dwordx4 v[168:169], off
	s_add_i32 m0, s0, 0x2000
	s_add_u32 s0, s42, 0x160000
	v_lshl_add_u64 v[172:173], s[42:43], 0, v[156:157]
	s_addc_u32 s1, s43, 0
	s_add_i32 s2, s46, s49
	global_load_lds_dwordx4 v[172:173], off
	v_lshl_add_u64 v[202:203], s[0:1], 0, v[160:161]
	s_mov_b32 m0, s2
	v_lshl_add_u64 v[212:213], s[44:45], 0, v[158:159]
	global_load_lds_dwordx4 v[202:203], off
	v_lshl_add_u64 v[202:203], s[0:1], 0, v[156:157]
	s_add_i32 m0, s2, 0x2000
	s_nop 0
	global_load_lds_dwordx4 v[202:203], off
	v_lshl_add_u64 v[202:203], s[44:45], 0, v[162:163]
	s_mov_b32 m0, s50
	s_nop 0
	global_load_lds_dwordx4 v[202:203], off
	s_mov_b32 m0, s51
	s_nop 0
	global_load_lds_dwordx4 v[212:213], off
	s_waitcnt vmcnt(8)
	s_waitcnt lgkmcnt(0)
	s_barrier
; #define PG8_STAGE(bufoff, gbase, voff) do { _Pragma("unroll") for (int _i = 0; _i < 2; ++_i) \
;         __builtin_amdgcn_global_load_lds((const unsigned*)((const char*)(gbase) + (voff)[_i]), (PG8_LAS unsigned*)(lds + (bufoff) + ldsw + _i * 8192), 16, 0, AUX_A); } while (0)
; #define PG8_LDA(dst, b, h) do { _Pragma("unroll") for (int m = 0; m < 4; ++m) _Pragma("unroll") for (int k = 0; k < 2; ++k) dst[m][k] = *(const PG8_LAS bf16x8*)(lds + PG8_SA(b, h) + aoff + m * 2048 + k * 1024); } while (0)
; #define PG8_LDB(dst, b, h) do { _Pragma("unroll") for (int n = 0; n < 2; ++n) _Pragma("unroll") for (int k = 0; k < 2; ++k) dst[n][k] = *(const PG8_LAS bf16x8*)(lds + PG8_SB(b, h) + boff + n * 2048 + k * 1024); } while (0)
; #define PG8_MMA(ai, bj, At, Bt) do { __builtin_amdgcn_s_setprio(1); _Pragma("unroll") for (int m = 0; m < 4; ++m) _Pragma("unroll") for (int n = 0; n < 2; ++n) _Pragma("unroll") for (int k = 0; k < 2; ++k) \
;         acc[ai][bj][m][n] = __builtin_amdgcn_mfma_f32_16x16x32_bf16(Bt[n][k], At[m][k], acc[ai][bj][m][n], 0, 0, 0); __builtin_amdgcn_s_setprio(0); } while (0)
; #define PG8_WAIT_V(n) asm volatile("s_waitcnt vmcnt(" #n ")" ::: "memory")
; #define PG8_WAIT_L(n) asm volatile("s_waitcnt lgkmcnt(" #n ")" ::: "memory")
; #define PG8_BAR __builtin_amdgcn_s_barrier()
; #define PG8_SCHED __builtin_amdgcn_sched_barrier(0)
; template <class Epi, class Sched, bool ALIGN_EPI = false, bool SP2 = false>
; __device__ __forceinline__ void gemm_phase(PG8_LAS unsigned char* lds, const Gemm g, const Sched& S, const Epi& E) {
;     ...
;             PG8_WAIT_V(8); PG8_WAIT_L(0); PG8_BAR; PG8_MMA(1, 0, At, B0); PG8_MMA(1, 1, At, B1); PG8_BAR; PG8_SCHED;
;             PG8_LDB(B0, 1, 0); PG8_LDB(B1, 1, 1); PG8_SCHED; PG8_LDA(At, 1, 0); PG8_STAGE(PG8_SA(0, 1), a2 + hstep, voffA);
;             PG8_WAIT_V(8); PG8_WAIT_L(0); PG8_BAR; PG8_MMA(0, 0, At, B0); PG8_MMA(0, 1, At, B1); PG8_BAR; PG8_SCHED;
	s_setprio 1
	s_waitcnt lgkmcnt(0)
	v_mfma_f32_16x16x32_bf16 v[62:65], v[136:139], v[194:197], v[62:65]
	v_mfma_f32_16x16x32_bf16 v[54:57], v[136:139], v[222:225], v[54:57]
	v_mfma_f32_16x16x32_bf16 v[38:41], v[136:139], v[230:233], v[38:41]
	v_mfma_f32_16x16x32_bf16 v[22:25], v[136:139], v[238:241], v[22:25]
	v_mfma_f32_16x16x32_bf16 v[14:17], v[144:147], v[238:241], v[14:17]
	v_mfma_f32_16x16x32_bf16 v[30:33], v[144:147], v[230:233], v[30:33]
	v_mfma_f32_16x16x32_bf16 v[46:49], v[144:147], v[222:225], v[46:49]
	v_mfma_f32_16x16x32_bf16 v[58:61], v[144:147], v[194:197], v[58:61]
	v_mfma_f32_16x16x32_bf16 v[62:65], v[140:143], v[198:201], v[62:65]
	v_mfma_f32_16x16x32_bf16 v[54:57], v[140:143], v[226:229], v[54:57]
	v_mfma_f32_16x16x32_bf16 v[38:41], v[140:143], v[234:237], v[38:41]
	v_mfma_f32_16x16x32_bf16 v[22:25], v[140:143], v[242:245], v[22:25]
	v_mfma_f32_16x16x32_bf16 v[14:17], v[148:151], v[242:245], v[14:17]
	v_mfma_f32_16x16x32_bf16 v[30:33], v[148:151], v[234:237], v[30:33]
	v_mfma_f32_16x16x32_bf16 v[46:49], v[148:151], v[226:229], v[46:49]
	v_mfma_f32_16x16x32_bf16 v[58:61], v[148:151], v[198:201], v[58:61]
	s_setprio 0
	s_setprio 1
	v_mfma_f32_16x16x32_bf16 v[50:53], v[152:155], v[194:197], v[50:53]
	v_mfma_f32_16x16x32_bf16 v[34:37], v[152:155], v[222:225], v[34:37]
	v_mfma_f32_16x16x32_bf16 v[18:21], v[152:155], v[230:233], v[18:21]
	v_mfma_f32_16x16x32_bf16 v[6:9], v[152:155], v[238:241], v[6:9]
	v_mfma_f32_16x16x32_bf16 v[2:5], v[184:187], v[238:241], v[2:5]
	v_mfma_f32_16x16x32_bf16 v[10:13], v[184:187], v[230:233], v[10:13]
	v_mfma_f32_16x16x32_bf16 v[26:29], v[184:187], v[222:225], v[26:29]
	v_mfma_f32_16x16x32_bf16 v[42:45], v[184:187], v[194:197], v[42:45]
	v_mfma_f32_16x16x32_bf16 v[50:53], v[180:183], v[198:201], v[50:53]
	v_mfma_f32_16x16x32_bf16 v[34:37], v[180:183], v[226:229], v[34:37]
	v_mfma_f32_16x16x32_bf16 v[18:21], v[180:183], v[234:237], v[18:21]
	v_mfma_f32_16x16x32_bf16 v[6:9], v[180:183], v[242:245], v[6:9]
	v_mfma_f32_16x16x32_bf16 v[2:5], v[190:193], v[242:245], v[2:5]
	v_mfma_f32_16x16x32_bf16 v[10:13], v[190:193], v[234:237], v[10:13]
	v_mfma_f32_16x16x32_bf16 v[26:29], v[190:193], v[226:229], v[26:29]
	v_mfma_f32_16x16x32_bf16 v[42:45], v[190:193], v[198:201], v[42:45]
	s_setprio 0
	s_barrier
	s_add_i32 s2, 0, 0x18000
	s_add_i32 s29, 0, 0x1c000
	v_add_u32_e32 v148, s2, v99
	v_add_u32_e32 v190, s29, v99
	ds_read_b128 v[136:139], v148
	ds_read_b128 v[140:143], v148 offset:1024
	ds_read_b128 v[144:147], v148 offset:2048
	ds_read_b128 v[148:151], v148 offset:3072
	ds_read_b128 v[152:155], v190
	ds_read_b128 v[180:183], v190 offset:1024
	ds_read_b128 v[184:187], v190 offset:2048
	ds_read_b128 v[190:193], v190 offset:3072
	s_add_u32 s0, s44, 0x160000
	s_addc_u32 s1, s45, 0
	s_mov_b32 m0, s52
	v_lshl_add_u64 v[246:247], s[0:1], 0, v[162:163]
	ds_read_b128 v[194:197], v189 offset:32768
	ds_read_b128 v[198:201], v189 offset:33792
	ds_read_b128 v[222:225], v189 offset:34816
	ds_read_b128 v[226:229], v189 offset:35840
	ds_read_b128 v[230:233], v189 offset:36864
	ds_read_b128 v[234:237], v189 offset:37888
	ds_read_b128 v[238:241], v189 offset:38912
	ds_read_b128 v[242:245], v189 offset:39936
	global_load_lds_dwordx4 v[246:247], off
	v_lshl_add_u64 v[246:247], s[0:1], 0, v[158:159]
	s_mov_b32 m0, s53
	s_nop 0
	global_load_lds_dwordx4 v[246:247], off
	s_waitcnt vmcnt(8)
	s_waitcnt lgkmcnt(0)
	s_barrier
	s_setprio 1
	s_waitcnt lgkmcnt(0)
	v_mfma_f32_16x16x32_bf16 v[128:131], v[136:139], v[194:197], v[128:131]
	v_mfma_f32_16x16x32_bf16 v[120:123], v[136:139], v[222:225], v[120:123]
	v_mfma_f32_16x16x32_bf16 v[104:107], v[136:139], v[230:233], v[104:107]
	v_mfma_f32_16x16x32_bf16 v[86:89], v[136:139], v[238:241], v[86:89]
	v_mfma_f32_16x16x32_bf16 v[78:81], v[144:147], v[238:241], v[78:81]
	v_mfma_f32_16x16x32_bf16 v[94:97], v[144:147], v[230:233], v[94:97]
	v_mfma_f32_16x16x32_bf16 v[112:115], v[144:147], v[222:225], v[112:115]
	v_mfma_f32_16x16x32_bf16 v[124:127], v[144:147], v[194:197], v[124:127]
	v_mfma_f32_16x16x32_bf16 v[128:131], v[140:143], v[198:201], v[128:131]
	v_mfma_f32_16x16x32_bf16 v[120:123], v[140:143], v[226:229], v[120:123]
	v_mfma_f32_16x16x32_bf16 v[104:107], v[140:143], v[234:237], v[104:107]
	v_mfma_f32_16x16x32_bf16 v[86:89], v[140:143], v[242:245], v[86:89]
	v_mfma_f32_16x16x32_bf16 v[78:81], v[148:151], v[242:245], v[78:81]
	v_mfma_f32_16x16x32_bf16 v[94:97], v[148:151], v[234:237], v[94:97]
	v_mfma_f32_16x16x32_bf16 v[112:115], v[148:151], v[226:229], v[112:115]
	v_mfma_f32_16x16x32_bf16 v[124:127], v[148:151], v[198:201], v[124:127]
	s_setprio 0
	s_setprio 1
	v_mfma_f32_16x16x32_bf16 v[116:119], v[152:155], v[194:197], v[116:119]
	v_mfma_f32_16x16x32_bf16 v[100:103], v[152:155], v[222:225], v[100:103]
	v_mfma_f32_16x16x32_bf16 v[82:85], v[152:155], v[230:233], v[82:85]
	v_mfma_f32_16x16x32_bf16 v[70:73], v[152:155], v[238:241], v[70:73]
	v_mfma_f32_16x16x32_bf16 v[66:69], v[184:187], v[238:241], v[66:69]
	v_mfma_f32_16x16x32_bf16 v[74:77], v[184:187], v[230:233], v[74:77]
	v_mfma_f32_16x16x32_bf16 v[90:93], v[184:187], v[222:225], v[90:93]
	v_mfma_f32_16x16x32_bf16 v[108:111], v[184:187], v[194:197], v[108:111]
	v_mfma_f32_16x16x32_bf16 v[116:119], v[180:183], v[198:201], v[116:119]
	v_mfma_f32_16x16x32_bf16 v[100:103], v[180:183], v[226:229], v[100:103]
	v_mfma_f32_16x16x32_bf16 v[82:85], v[180:183], v[234:237], v[82:85]
	v_mfma_f32_16x16x32_bf16 v[70:73], v[180:183], v[242:245], v[70:73]
	v_mfma_f32_16x16x32_bf16 v[66:69], v[190:193], v[242:245], v[66:69]
	v_mfma_f32_16x16x32_bf16 v[74:77], v[190:193], v[234:237], v[74:77]
	v_mfma_f32_16x16x32_bf16 v[90:93], v[190:193], v[226:229], v[90:93]
	v_mfma_f32_16x16x32_bf16 v[108:111], v[190:193], v[198:201], v[108:111]
	s_setprio 0
	s_barrier
; #define PG8_STAGE(bufoff, gbase, voff) do { _Pragma("unroll") for (int _i = 0; _i < 2; ++_i) \
;         __builtin_amdgcn_global_load_lds((const unsigned*)((const char*)(gbase) + (voff)[_i]), (PG8_LAS unsigned*)(lds + (bufoff) + ldsw + _i * 8192), 16, 0, AUX_A); } while (0)
; #define PG8_STAGEB(bufoff, gbase, voff) do { _Pragma("unroll") for (int _i = 0; _i < 2; ++_i) \
;         __builtin_amdgcn_global_load_lds((const unsigned*)((const char*)(gbase) + (voff)[_i]), (PG8_LAS unsigned*)(lds + (bufoff) + ldsw + _i * 8192), 16, 0, AUX_B); } while (0)
; #define PG8_LDA(dst, b, h) do { _Pragma("unroll") for (int m = 0; m < 4; ++m) _Pragma("unroll") for (int k = 0; k < 2; ++k) dst[m][k] = *(const PG8_LAS bf16x8*)(lds + PG8_SA(b, h) + aoff + m * 2048 + k * 1024); } while (0)
; #define PG8_MMA(ai, bj, At, Bt) do { __builtin_amdgcn_s_setprio(1); _Pragma("unroll") for (int m = 0; m < 4; ++m) _Pragma("unroll") for (int n = 0; n < 2; ++n) _Pragma("unroll") for (int k = 0; k < 2; ++k) \
;         acc[ai][bj][m][n] = __builtin_amdgcn_mfma_f32_16x16x32_bf16(Bt[n][k], At[m][k], acc[ai][bj][m][n], 0, 0, 0); __builtin_amdgcn_s_setprio(0); } while (0)
; #define PG8_WAIT_V(n) asm volatile("s_waitcnt vmcnt(" #n ")" ::: "memory")
; #define PG8_WAIT_L(n) asm volatile("s_waitcnt lgkmcnt(" #n ")" ::: "memory")
; #define PG8_BAR __builtin_amdgcn_s_barrier()
; #define PG8_SCHED __builtin_amdgcn_sched_barrier(0)
; template <class Epi, class Sched, bool ALIGN_EPI = false, bool SP2 = false>
; __device__ __forceinline__ void gemm_phase(PG8_LAS unsigned char* lds, const Gemm g, const Sched& S, const Epi& E) {
;     ...
;             PG8_LDA(At, 1, 1); PG8_STAGEB(PG8_SB(1, 0), b3, voffB); PG8_STAGEB(PG8_SB(1, 1), b3 + hstep, voffB); PG8_STAGE(PG8_SA(1, 0), a3, voffA);
;             PG8_WAIT_V(8); PG8_WAIT_L(0); PG8_BAR; PG8_MMA(1, 0, At, B0); PG8_MMA(1, 1, At, B1); PG8_BAR; PG8_SCHED;
;     ...
;         if constexpr (ALIGN_EPI) { if (wr == 0) PG8_BAR; }
	s_add_i32 s0, s2, s49
	v_lshl_add_u64 v[168:169], v[168:169], 0, s[76:77]
	s_mov_b32 m0, s0
	ds_read_b128 v[194:197], v189 offset:49152
	ds_read_b128 v[198:201], v189 offset:50176
	ds_read_b128 v[222:225], v189 offset:51200
	ds_read_b128 v[226:229], v189 offset:52224
	ds_read_b128 v[230:233], v189 offset:53248
	ds_read_b128 v[234:237], v189 offset:54272
	ds_read_b128 v[238:241], v189 offset:55296
	ds_read_b128 v[242:245], v189 offset:56320
	global_load_lds_dwordx4 v[168:169], off
	s_add_i32 m0, s0, 0x2000
	s_add_u32 s0, s42, 0x160080
	v_lshl_add_u64 v[168:169], v[172:173], 0, s[76:77]
	s_addc_u32 s1, s43, 0
	s_add_i32 s2, s29, s49
	global_load_lds_dwordx4 v[168:169], off
	v_lshl_add_u64 v[168:169], s[0:1], 0, v[160:161]
	s_mov_b32 m0, s2
	s_nop 0
	global_load_lds_dwordx4 v[168:169], off
	v_lshl_add_u64 v[168:169], s[0:1], 0, v[156:157]
	s_add_i32 m0, s2, 0x2000
	s_nop 0
	global_load_lds_dwordx4 v[168:169], off
	v_lshl_add_u64 v[168:169], v[202:203], 0, s[76:77]
	s_mov_b32 m0, s60
	s_nop 0
	global_load_lds_dwordx4 v[168:169], off
	v_lshl_add_u64 v[168:169], v[212:213], 0, s[76:77]
	s_mov_b32 m0, s61
	s_nop 0
	global_load_lds_dwordx4 v[168:169], off
	s_waitcnt vmcnt(8)
	s_waitcnt lgkmcnt(0)
	s_barrier
	s_setprio 1
	s_waitcnt lgkmcnt(0)
	v_mfma_f32_16x16x32_bf16 v[62:65], v[136:139], v[194:197], v[62:65]
	v_mfma_f32_16x16x32_bf16 v[54:57], v[136:139], v[222:225], v[54:57]
	v_mfma_f32_16x16x32_bf16 v[38:41], v[136:139], v[230:233], v[38:41]
	v_mfma_f32_16x16x32_bf16 v[22:25], v[136:139], v[238:241], v[22:25]
	v_mfma_f32_16x16x32_bf16 v[14:17], v[144:147], v[238:241], v[14:17]
	v_mfma_f32_16x16x32_bf16 v[30:33], v[144:147], v[230:233], v[30:33]
	v_mfma_f32_16x16x32_bf16 v[46:49], v[144:147], v[222:225], v[46:49]
	v_mfma_f32_16x16x32_bf16 v[58:61], v[144:147], v[194:197], v[58:61]
	v_mfma_f32_16x16x32_bf16 v[62:65], v[140:143], v[198:201], v[62:65]
	v_mfma_f32_16x16x32_bf16 v[54:57], v[140:143], v[226:229], v[54:57]
	v_mfma_f32_16x16x32_bf16 v[38:41], v[140:143], v[234:237], v[38:41]
	v_mfma_f32_16x16x32_bf16 v[22:25], v[140:143], v[242:245], v[22:25]
	v_mfma_f32_16x16x32_bf16 v[14:17], v[148:151], v[242:245], v[14:17]
	v_mfma_f32_16x16x32_bf16 v[30:33], v[148:151], v[234:237], v[30:33]
	v_mfma_f32_16x16x32_bf16 v[46:49], v[148:151], v[226:229], v[46:49]
	v_mfma_f32_16x16x32_bf16 v[58:61], v[148:151], v[198:201], v[58:61]
	s_setprio 0
	s_setprio 1
	v_mfma_f32_16x16x32_bf16 v[50:53], v[152:155], v[194:197], v[50:53]
	v_mfma_f32_16x16x32_bf16 v[34:37], v[152:155], v[222:225], v[34:37]
	v_mfma_f32_16x16x32_bf16 v[18:21], v[152:155], v[230:233], v[18:21]
	v_mfma_f32_16x16x32_bf16 v[6:9], v[152:155], v[238:241], v[6:9]
	v_mfma_f32_16x16x32_bf16 v[2:5], v[184:187], v[238:241], v[2:5]
	v_mfma_f32_16x16x32_bf16 v[10:13], v[184:187], v[230:233], v[10:13]
	v_mfma_f32_16x16x32_bf16 v[26:29], v[184:187], v[222:225], v[26:29]
	v_mfma_f32_16x16x32_bf16 v[42:45], v[184:187], v[194:197], v[42:45]
	v_mfma_f32_16x16x32_bf16 v[50:53], v[180:183], v[198:201], v[50:53]
	v_mfma_f32_16x16x32_bf16 v[34:37], v[180:183], v[226:229], v[34:37]
	v_mfma_f32_16x16x32_bf16 v[18:21], v[180:183], v[234:237], v[18:21]
	v_mfma_f32_16x16x32_bf16 v[6:9], v[180:183], v[242:245], v[6:9]
	v_mfma_f32_16x16x32_bf16 v[2:5], v[190:193], v[242:245], v[2:5]
	v_mfma_f32_16x16x32_bf16 v[10:13], v[190:193], v[234:237], v[10:13]
	v_mfma_f32_16x16x32_bf16 v[26:29], v[190:193], v[226:229], v[26:29]
	v_mfma_f32_16x16x32_bf16 v[42:45], v[190:193], v[198:201], v[42:45]
	s_setprio 0
	s_barrier
	s_add_i32 s0, s83, 2
	v_lshl_add_u64 v[132:133], v[132:133], 0, s[86:87]
	v_lshl_add_u64 v[134:135], v[134:135], 0, s[86:87]
	s_cmp_ge_i32 s83, s82
	s_mov_b32 s83, s0
	s_cbranch_scc0 .LBB0_1654
	s_and_b64 vcc, exec, s[12:13]
	s_cbranch_vccz .LBB0_1657
	s_barrier
